# two instead of four pre-barrier MFMAs on the toggle-free peeled kernel
# speedup vs baseline: 1.0015x; 1.0015x over previous
; #define PG8_LAS __attribute__((address_space(3)))
; #define PG8_STAGE(bufoff, gbase, voff) do { _Pragma("unroll") for (int _i = 0; _i < 2; ++_i) \
;         __builtin_amdgcn_global_load_lds((const unsigned*)((const char*)(gbase) + (voff)[_i]), (PG8_LAS unsigned*)(lds + (bufoff) + ldsw + _i * 8192), 16, 0, 0); } while (0)
; #define PG8_WAIT_V(n) asm volatile("s_waitcnt vmcnt(" #n ")" ::: "memory")
; #define PG8_BAR __builtin_amdgcn_s_barrier()
;     __device__ __forceinline__ void stage(const Unit& u, PG8_LAS unsigned char* area, int wr, int lane) const {
;         const float* src = rs + u.pm * BM + wr * 64 + lane;
;         __builtin_amdgcn_global_load_lds((const unsigned*)src, (PG8_LAS unsigned*)area, 4, 0, 0);
;         __builtin_amdgcn_global_load_lds((const unsigned*)(src + HALF), (PG8_LAS unsigned*)(area + 256), 4, 0, 0);
; template <class Epi, class Sched, bool ALIGN_EPI = false, bool SP2 = false, bool ABLK = false, bool BBLK = false>
; __device__ __forceinline__ void gemm_phase(PG8_LAS unsigned char* lds, const Gemm g, const Sched& S, const Epi& E) {
;     ...
;         const bool has_next = S.next(ui + 1, nxt);
;         PG8_LAS unsigned char* const rs_area = lds + STAGE_BYTES + wid * 512;
;         E.stage(cur, rs_area, wr, lane);
;         const char* nA = has_next ? (const char*)g.A + (size_t)nxt.pm * tstep : cA; const char* nB = has_next ? (const char*)g.Bt + (size_t)nxt.pn * tstep : cB;
;         for (int t = 0; t < nt; t += 2) {
;             const bool last = (t == nt - 2);
;             const char* a1 = cA + (size_t)(t + 1) * kstepA;
;             const char* a2 = last ? nA : cA + (size_t)(t + 2) * kstepA; const char* b2 = last ? nB : cB + (size_t)(t + 2) * kstepB;
;             const char* a3 = a2 + kstepA; const char* b3 = b2 + kstepB;
;             if (last && has_next) S.a_ready(nxt);
;             if constexpr (SP2) {
;             PG8_LDB(B0, 0, 0); PG8_LDB(B1, 0, 1); PG8_SCHED; PG8_LDA(At, 0, 0); PG8_STAGE(PG8_SA(1, 1), a1 + hstepA, voffA);
;             PG8_WAIT_V(8); PG8_WAIT_L(0); PG8_BAR; PG8_MMA(0, 0, At, B0); PG8_MMA(0, 1, At, B1); PG8_BAR; PG8_SCHED;
;             PG8_LDA(At, 0, 1); PG8_STAGE(PG8_SB(0, 0), b2, voffB); PG8_STAGE(PG8_SB(0, 1), b2 + hstepB, voffB); PG8_STAGE(PG8_SA(0, 0), a2, voffA);
;             PG8_WAIT_V(8); PG8_WAIT_L(0); PG8_BAR; PG8_MMA(1, 0, At, B0); PG8_MMA(1, 1, At, B1); PG8_BAR; PG8_SCHED;
.LBB0_184:
	s_lshl_b32 s10, s18, 8
	s_ashr_i32 s11, s10, 31
	s_mov_b32 m0, s64
	v_lshl_add_u64 v[4:5], s[10:11], 2, v[144:145]
	global_load_lds_dword v[4:5], off
	v_lshl_add_u64 v[4:5], v[4:5], 0, s[90:91]
	s_add_i32 m0, s64, 0x100
	s_ashr_i32 s9, s8, 31
	global_load_lds_dword v[4:5], off
	s_lshl_b64 s[10:11], s[8:9], 20
	v_readlane_b32 s16, v252, 27
	v_readlane_b32 s17, v252, 28
	s_add_u32 s10, s16, s10
	s_addc_u32 s11, s17, s11
	s_and_b64 s[16:17], s[2:3], exec
	s_cselect_b32 s9, s11, s21
	s_cselect_b32 s70, s10, s20
	s_ashr_i32 s7, s6, 31
	s_lshl_b64 s[16:17], s[6:7], 20
	s_add_u32 s16, s29, s16
	s_addc_u32 s17, s30, s17
	s_and_b64 s[24:25], s[2:3], exec
	s_cselect_b32 s7, s17, s23
	s_cselect_b32 s71, s16, s22
	s_add_u32 s20, s20, 0xc000
	s_addc_u32 s21, s21, 0
	s_add_u32 s77, s22, 0x10000
	s_addc_u32 vcc_lo, s23, 0
	s_mov_b32 vcc_hi, -2
	s_add_u32 s13, s20, 0x4000
	s_addc_u32 s22, s21, 0
	s_cmp_eq_u32 vcc_hi, 28
	s_cselect_b32 s26, s70, s13
	s_cselect_b32 s27, s9, s22
	s_cselect_b32 s24, s71, s77
	s_cselect_b32 s25, s7, vcc_lo
	s_add_u32 s22, s26, 0x8000
	s_addc_u32 s23, s27, 0
	s_add_i32 s13, 0, 0x10000
	v_add_u32_e32 v36, s13, v160
	s_add_i32 s88, 0, 0x14000
	ds_read_b128 v[152:155], v36
	ds_read_b128 v[156:159], v36 offset:1024
	ds_read_b128 v[162:165], v36 offset:2048
	ds_read_b128 v[166:169], v36 offset:3072
	v_add_u32_e32 v36, s88, v160
	ds_read_b128 v[170:173], v36
	ds_read_b128 v[174:177], v36 offset:1024
	ds_read_b128 v[178:181], v36 offset:2048
	ds_read_b128 v[182:185], v36 offset:3072
	s_add_i32 m0, s19, 0xc000
	ds_read_b128 v[186:189], v161
	ds_read_b128 v[190:193], v161 offset:1024
	ds_read_b128 v[194:197], v161 offset:2048
	ds_read_b128 v[198:201], v161 offset:3072
	ds_read_b128 v[202:205], v161 offset:4096
	ds_read_b128 v[206:209], v161 offset:5120
	ds_read_b128 v[210:213], v161 offset:6144
	ds_read_b128 v[214:217], v161 offset:7168
	global_load_lds_dwordx4 v148, s[20:21]
	s_add_i32 m0, s19, 0xe000
	s_nop 0
	global_load_lds_dwordx4 v150, s[20:21]
	s_waitcnt vmcnt(8)
	s_waitcnt lgkmcnt(0)
	v_mfma_f32_16x16x32_bf16 v[132:135], v[152:155], v[186:189], 0
	v_mfma_f32_16x16x32_bf16 v[132:135], v[156:159], v[190:193], v[132:135]
	s_barrier
	s_setprio 1
	v_mfma_f32_16x16x32_bf16 v[128:131], v[166:169], v[190:193], 0
	v_mfma_f32_16x16x32_bf16 v[128:131], v[162:165], v[186:189], v[128:131]
	v_mfma_f32_16x16x32_bf16 v[112:115], v[162:165], v[194:197], 0
	v_mfma_f32_16x16x32_bf16 v[112:115], v[166:169], v[198:201], v[112:115]
	v_mfma_f32_16x16x32_bf16 v[116:119], v[156:159], v[198:201], 0
	v_mfma_f32_16x16x32_bf16 v[116:119], v[152:155], v[194:197], v[116:119]
	v_mfma_f32_16x16x32_bf16 v[100:103], v[152:155], v[202:205], 0
	v_mfma_f32_16x16x32_bf16 v[100:103], v[156:159], v[206:209], v[100:103]
	v_mfma_f32_16x16x32_bf16 v[96:99], v[166:169], v[206:209], 0
	v_mfma_f32_16x16x32_bf16 v[96:99], v[162:165], v[202:205], v[96:99]
	v_mfma_f32_16x16x32_bf16 v[80:83], v[162:165], v[210:213], 0
	v_mfma_f32_16x16x32_bf16 v[80:83], v[166:169], v[214:217], v[80:83]
	v_mfma_f32_16x16x32_bf16 v[84:87], v[156:159], v[214:217], 0
	v_mfma_f32_16x16x32_bf16 v[84:87], v[152:155], v[210:213], v[84:87]
	v_mfma_f32_16x16x32_bf16 v[76:79], v[170:173], v[210:213], 0
	v_mfma_f32_16x16x32_bf16 v[76:79], v[174:177], v[214:217], v[76:79]
	v_mfma_f32_16x16x32_bf16 v[124:127], v[174:177], v[190:193], 0
	v_mfma_f32_16x16x32_bf16 v[124:127], v[170:173], v[186:189], v[124:127]
	v_mfma_f32_16x16x32_bf16 v[120:123], v[178:181], v[186:189], 0
	v_mfma_f32_16x16x32_bf16 v[120:123], v[182:185], v[190:193], v[120:123]
	v_mfma_f32_16x16x32_bf16 v[104:107], v[182:185], v[198:201], 0
	v_mfma_f32_16x16x32_bf16 v[104:107], v[178:181], v[194:197], v[104:107]
	v_mfma_f32_16x16x32_bf16 v[108:111], v[170:173], v[194:197], 0
	v_mfma_f32_16x16x32_bf16 v[108:111], v[174:177], v[198:201], v[108:111]
	v_mfma_f32_16x16x32_bf16 v[92:95], v[174:177], v[206:209], 0
	v_mfma_f32_16x16x32_bf16 v[92:95], v[170:173], v[202:205], v[92:95]
	v_mfma_f32_16x16x32_bf16 v[88:91], v[178:181], v[202:205], 0
	v_mfma_f32_16x16x32_bf16 v[88:91], v[182:185], v[206:209], v[88:91]
	v_mfma_f32_16x16x32_bf16 v[72:75], v[182:185], v[214:217], 0
	v_mfma_f32_16x16x32_bf16 v[72:75], v[178:181], v[210:213], v[72:75]
	s_setprio 0
	s_barrier
	s_add_i32 s13, s13, s31
	s_mov_b32 m0, s13
	ds_read_b128 v[186:189], v161 offset:16384
	ds_read_b128 v[190:193], v161 offset:17408
	ds_read_b128 v[194:197], v161 offset:18432
	ds_read_b128 v[198:201], v161 offset:19456
	ds_read_b128 v[202:205], v161 offset:20480
	ds_read_b128 v[206:209], v161 offset:21504
	ds_read_b128 v[210:213], v161 offset:22528
	ds_read_b128 v[214:217], v161 offset:23552
	global_load_lds_dwordx4 v140, s[24:25]
	s_add_i32 m0, s13, 0x2000
	s_add_u32 s68, s24, 0x4000
	s_addc_u32 s69, s25, 0
	s_add_i32 s13, s88, s31
	global_load_lds_dwordx4 v136, s[24:25]
	s_mov_b32 m0, s13
	s_nop 0
	global_load_lds_dwordx4 v140, s[68:69]
	s_add_i32 m0, s13, 0x2000
	s_nop 0
	global_load_lds_dwordx4 v136, s[68:69]
	s_mov_b32 m0, s19
	s_nop 0
	global_load_lds_dwordx4 v142, s[26:27]
	s_mov_b32 m0, s35
	s_nop 0
	global_load_lds_dwordx4 v138, s[26:27]
	s_waitcnt vmcnt(8)
	s_waitcnt lgkmcnt(0)
	v_mfma_f32_16x16x32_bf16 v[68:71], v[152:155], v[186:189], 0
	v_mfma_f32_16x16x32_bf16 v[68:71], v[156:159], v[190:193], v[68:71]
	s_barrier
; #define PG8_STAGE(bufoff, gbase, voff) do { _Pragma("unroll") for (int _i = 0; _i < 2; ++_i) \
;         __builtin_amdgcn_global_load_lds((const unsigned*)((const char*)(gbase) + (voff)[_i]), (PG8_LAS unsigned*)(lds + (bufoff) + ldsw + _i * 8192), 16, 0, 0); } while (0)
; #define PG8_LDA(dst, b, h) do { _Pragma("unroll") for (int m = 0; m < 4; ++m) _Pragma("unroll") for (int k = 0; k < 2; ++k) dst[m][k] = *(const PG8_LAS bf16x8*)(lds + PG8_SA(b, h) + aoff + m * 2048 + k * 1024); } while (0)
; #define PG8_LDB(dst, b, h) do { _Pragma("unroll") for (int n = 0; n < 2; ++n) _Pragma("unroll") for (int k = 0; k < 2; ++k) dst[n][k] = *(const PG8_LAS bf16x8*)(lds + PG8_SB(b, h) + boff + n * 2048 + k * 1024); } while (0)
; #define PG8_MMA(ai, bj, At, Bt) do { __builtin_amdgcn_s_setprio(1); _Pragma("unroll") for (int m = 0; m < 4; ++m) _Pragma("unroll") for (int n = 0; n < 2; ++n) _Pragma("unroll") for (int k = 0; k < 2; ++k) \
;         acc[ai][bj][m][n] = __builtin_amdgcn_mfma_f32_16x16x32_bf16(Bt[n][k], At[m][k], acc[ai][bj][m][n], 0, 0, 0); __builtin_amdgcn_s_setprio(0); } while (0)
; #define PG8_WAIT_V(n) asm volatile("s_waitcnt vmcnt(" #n ")" ::: "memory")
; #define PG8_WAIT_L(n) asm volatile("s_waitcnt lgkmcnt(" #n ")" ::: "memory")
; #define PG8_BAR __builtin_amdgcn_s_barrier()
; #define PG8_SCHED __builtin_amdgcn_sched_barrier(0)
; template <class Epi, class Sched, bool ALIGN_EPI = false, bool SP2 = false, bool ABLK = false, bool BBLK = false>
; __device__ __forceinline__ void gemm_phase(PG8_LAS unsigned char* lds, const Gemm g, const Sched& S, const Epi& E) {
;     ...
;             PG8_WAIT_V(8); PG8_WAIT_L(0); PG8_BAR; PG8_MMA(1, 0, At, B0); PG8_MMA(1, 1, At, B1); PG8_BAR; PG8_SCHED;
;             PG8_LDB(B0, 1, 0); PG8_LDB(B1, 1, 1); PG8_SCHED; PG8_LDA(At, 1, 0); PG8_STAGE(PG8_SA(0, 1), a2 + hstepA, voffA);
;             PG8_WAIT_V(8); PG8_WAIT_L(0); PG8_BAR; PG8_MMA(0, 0, At, B0); PG8_MMA(0, 1, At, B1); PG8_BAR; PG8_SCHED;
	s_setprio 1
	v_mfma_f32_16x16x32_bf16 v[64:67], v[166:169], v[190:193], 0
	v_mfma_f32_16x16x32_bf16 v[64:67], v[162:165], v[186:189], v[64:67]
	v_mfma_f32_16x16x32_bf16 v[48:51], v[162:165], v[194:197], 0
	v_mfma_f32_16x16x32_bf16 v[48:51], v[166:169], v[198:201], v[48:51]
	v_mfma_f32_16x16x32_bf16 v[52:55], v[156:159], v[198:201], 0
	v_mfma_f32_16x16x32_bf16 v[52:55], v[152:155], v[194:197], v[52:55]
	v_mfma_f32_16x16x32_bf16 v[32:35], v[152:155], v[202:205], 0
	v_mfma_f32_16x16x32_bf16 v[32:35], v[156:159], v[206:209], v[32:35]
	v_mfma_f32_16x16x32_bf16 v[28:31], v[166:169], v[206:209], 0
	v_mfma_f32_16x16x32_bf16 v[28:31], v[162:165], v[202:205], v[28:31]
	v_mfma_f32_16x16x32_bf16 v[12:15], v[162:165], v[210:213], 0
	v_mfma_f32_16x16x32_bf16 v[12:15], v[166:169], v[214:217], v[12:15]
	v_mfma_f32_16x16x32_bf16 v[16:19], v[156:159], v[214:217], 0
	v_mfma_f32_16x16x32_bf16 v[16:19], v[152:155], v[210:213], v[16:19]
	v_mfma_f32_16x16x32_bf16 v[8:11], v[170:173], v[210:213], 0
	v_mfma_f32_16x16x32_bf16 v[8:11], v[174:177], v[214:217], v[8:11]
	v_mfma_f32_16x16x32_bf16 v[60:63], v[174:177], v[190:193], 0
	v_mfma_f32_16x16x32_bf16 v[60:63], v[170:173], v[186:189], v[60:63]
	v_mfma_f32_16x16x32_bf16 v[56:59], v[178:181], v[186:189], 0
	v_mfma_f32_16x16x32_bf16 v[56:59], v[182:185], v[190:193], v[56:59]
	v_mfma_f32_16x16x32_bf16 v[40:43], v[182:185], v[198:201], 0
	v_mfma_f32_16x16x32_bf16 v[40:43], v[178:181], v[194:197], v[40:43]
	v_mfma_f32_16x16x32_bf16 v[44:47], v[170:173], v[194:197], 0
	v_mfma_f32_16x16x32_bf16 v[44:47], v[174:177], v[198:201], v[44:47]
	v_mfma_f32_16x16x32_bf16 v[24:27], v[174:177], v[206:209], 0
	v_mfma_f32_16x16x32_bf16 v[24:27], v[170:173], v[202:205], v[24:27]
	v_mfma_f32_16x16x32_bf16 v[20:23], v[178:181], v[202:205], 0
	v_mfma_f32_16x16x32_bf16 v[20:23], v[182:185], v[206:209], v[20:23]
	v_mfma_f32_16x16x32_bf16 v[4:7], v[182:185], v[214:217], 0
	v_mfma_f32_16x16x32_bf16 v[4:7], v[178:181], v[210:213], v[4:7]
	s_setprio 0
	s_barrier
	s_add_i32 s13, 0, 0x18000
	v_add_u32_e32 v36, s13, v160
	s_add_i32 s68, 0, 0x1c000
	ds_read_b128 v[152:155], v36
	ds_read_b128 v[156:159], v36 offset:1024
	ds_read_b128 v[162:165], v36 offset:2048
	ds_read_b128 v[166:169], v36 offset:3072
	v_add_u32_e32 v36, s68, v160
	ds_read_b128 v[170:173], v36
	ds_read_b128 v[174:177], v36 offset:1024
	ds_read_b128 v[178:181], v36 offset:2048
	ds_read_b128 v[182:185], v36 offset:3072
	s_add_u32 s26, s26, 0x4000
	s_addc_u32 s27, s27, 0
	s_mov_b32 m0, s36
	ds_read_b128 v[186:189], v161 offset:32768
	ds_read_b128 v[190:193], v161 offset:33792
	ds_read_b128 v[194:197], v161 offset:34816
	ds_read_b128 v[198:201], v161 offset:35840
	ds_read_b128 v[202:205], v161 offset:36864
	ds_read_b128 v[206:209], v161 offset:37888
	ds_read_b128 v[210:213], v161 offset:38912
	ds_read_b128 v[214:217], v161 offset:39936
	global_load_lds_dwordx4 v142, s[26:27]
	s_mov_b32 m0, s37
	s_nop 0
	global_load_lds_dwordx4 v138, s[26:27]
	s_waitcnt vmcnt(8)
	s_waitcnt lgkmcnt(0)
	v_mfma_f32_16x16x32_bf16 v[132:135], v[152:155], v[186:189], v[132:135]
	v_mfma_f32_16x16x32_bf16 v[132:135], v[156:159], v[190:193], v[132:135]
	s_barrier
	s_setprio 1
	v_mfma_f32_16x16x32_bf16 v[128:131], v[166:169], v[190:193], v[128:131]
	v_mfma_f32_16x16x32_bf16 v[128:131], v[162:165], v[186:189], v[128:131]
	v_mfma_f32_16x16x32_bf16 v[112:115], v[162:165], v[194:197], v[112:115]
	v_mfma_f32_16x16x32_bf16 v[112:115], v[166:169], v[198:201], v[112:115]
	v_mfma_f32_16x16x32_bf16 v[116:119], v[156:159], v[198:201], v[116:119]
	v_mfma_f32_16x16x32_bf16 v[116:119], v[152:155], v[194:197], v[116:119]
	v_mfma_f32_16x16x32_bf16 v[100:103], v[152:155], v[202:205], v[100:103]
	v_mfma_f32_16x16x32_bf16 v[100:103], v[156:159], v[206:209], v[100:103]
	v_mfma_f32_16x16x32_bf16 v[96:99], v[166:169], v[206:209], v[96:99]
	v_mfma_f32_16x16x32_bf16 v[96:99], v[162:165], v[202:205], v[96:99]
	v_mfma_f32_16x16x32_bf16 v[80:83], v[162:165], v[210:213], v[80:83]
	v_mfma_f32_16x16x32_bf16 v[80:83], v[166:169], v[214:217], v[80:83]
	v_mfma_f32_16x16x32_bf16 v[84:87], v[156:159], v[214:217], v[84:87]
	v_mfma_f32_16x16x32_bf16 v[84:87], v[152:155], v[210:213], v[84:87]
	v_mfma_f32_16x16x32_bf16 v[76:79], v[170:173], v[210:213], v[76:79]
	v_mfma_f32_16x16x32_bf16 v[76:79], v[174:177], v[214:217], v[76:79]
	v_mfma_f32_16x16x32_bf16 v[124:127], v[174:177], v[190:193], v[124:127]
	v_mfma_f32_16x16x32_bf16 v[124:127], v[170:173], v[186:189], v[124:127]
	v_mfma_f32_16x16x32_bf16 v[120:123], v[178:181], v[186:189], v[120:123]
	v_mfma_f32_16x16x32_bf16 v[120:123], v[182:185], v[190:193], v[120:123]
	v_mfma_f32_16x16x32_bf16 v[104:107], v[182:185], v[198:201], v[104:107]
	v_mfma_f32_16x16x32_bf16 v[104:107], v[178:181], v[194:197], v[104:107]
	v_mfma_f32_16x16x32_bf16 v[108:111], v[170:173], v[194:197], v[108:111]
	v_mfma_f32_16x16x32_bf16 v[108:111], v[174:177], v[198:201], v[108:111]
	v_mfma_f32_16x16x32_bf16 v[92:95], v[174:177], v[206:209], v[92:95]
	v_mfma_f32_16x16x32_bf16 v[92:95], v[170:173], v[202:205], v[92:95]
	v_mfma_f32_16x16x32_bf16 v[88:91], v[178:181], v[202:205], v[88:91]
	v_mfma_f32_16x16x32_bf16 v[88:91], v[182:185], v[206:209], v[88:91]
	v_mfma_f32_16x16x32_bf16 v[72:75], v[182:185], v[214:217], v[72:75]
	v_mfma_f32_16x16x32_bf16 v[72:75], v[178:181], v[210:213], v[72:75]
	s_setprio 0
	s_barrier
; #define PG8_STAGE(bufoff, gbase, voff) do { _Pragma("unroll") for (int _i = 0; _i < 2; ++_i) \
;         __builtin_amdgcn_global_load_lds((const unsigned*)((const char*)(gbase) + (voff)[_i]), (PG8_LAS unsigned*)(lds + (bufoff) + ldsw + _i * 8192), 16, 0, 0); } while (0)
; #define PG8_LDA(dst, b, h) do { _Pragma("unroll") for (int m = 0; m < 4; ++m) _Pragma("unroll") for (int k = 0; k < 2; ++k) dst[m][k] = *(const PG8_LAS bf16x8*)(lds + PG8_SA(b, h) + aoff + m * 2048 + k * 1024); } while (0)
; #define PG8_LDB(dst, b, h) do { _Pragma("unroll") for (int n = 0; n < 2; ++n) _Pragma("unroll") for (int k = 0; k < 2; ++k) dst[n][k] = *(const PG8_LAS bf16x8*)(lds + PG8_SB(b, h) + boff + n * 2048 + k * 1024); } while (0)
; #define PG8_WAIT_V(n) asm volatile("s_waitcnt vmcnt(" #n ")" ::: "memory")
; #define PG8_WAIT_L(n) asm volatile("s_waitcnt lgkmcnt(" #n ")" ::: "memory")
; #define PG8_BAR __builtin_amdgcn_s_barrier()
; template <class Epi, class Sched, bool ALIGN_EPI = false, bool SP2 = false, bool ABLK = false, bool BBLK = false>
; __device__ __forceinline__ void gemm_phase(PG8_LAS unsigned char* lds, const Gemm g, const Sched& S, const Epi& E) {
;     ...
;         for (int t = 0; t < nt; t += 2) {
;             const bool last = (t == nt - 2);
;             const char* a1 = cA + (size_t)(t + 1) * kstepA;
;             const char* a2 = last ? nA : cA + (size_t)(t + 2) * kstepA; const char* b2 = last ? nB : cB + (size_t)(t + 2) * kstepB;
;             const char* a3 = a2 + kstepA; const char* b3 = b2 + kstepB;
;             if (last && has_next) S.a_ready(nxt);
;             if constexpr (SP2) {
;             PG8_LDB(B0, 0, 0); PG8_LDB(B1, 0, 1); PG8_SCHED; PG8_LDA(At, 0, 0); PG8_STAGE(PG8_SA(1, 1), a1 + hstepA, voffA);
;             PG8_WAIT_V(8); PG8_WAIT_L(0); PG8_BAR; PG8_MMA(0, 0, At, B0); PG8_MMA(0, 1, At, B1); PG8_BAR; PG8_SCHED;
;             PG8_LDA(At, 0, 1); PG8_STAGE(PG8_SB(0, 0), b2, voffB); PG8_STAGE(PG8_SB(0, 1), b2 + hstepB, voffB); PG8_STAGE(PG8_SA(0, 0), a2, voffA);
;             PG8_WAIT_V(8); PG8_WAIT_L(0); PG8_BAR; PG8_MMA(1, 0, At, B0); PG8_MMA(1, 1, At, B1); PG8_BAR; PG8_SCHED;
;     ...
;             PG8_LDA(At, 1, 1); PG8_STAGE(PG8_SB(1, 0), b3, voffB); PG8_STAGE(PG8_SB(1, 1), b3 + hstepB, voffB); PG8_STAGE(PG8_SA(1, 0), a3, voffA);
;             PG8_WAIT_V(8); PG8_WAIT_L(0); PG8_BAR; PG8_MMA(1, 0, At, B0); PG8_MMA(1, 1, At, B1); PG8_BAR; PG8_SCHED;
	s_add_u32 s26, s24, 0x8000
	s_addc_u32 s27, s25, 0
	s_add_i32 s13, s13, s31
	s_mov_b32 m0, s13
	ds_read_b128 v[186:189], v161 offset:49152
	ds_read_b128 v[190:193], v161 offset:50176
	ds_read_b128 v[194:197], v161 offset:51200
	ds_read_b128 v[198:201], v161 offset:52224
	ds_read_b128 v[202:205], v161 offset:53248
	ds_read_b128 v[206:209], v161 offset:54272
	ds_read_b128 v[210:213], v161 offset:55296
	ds_read_b128 v[214:217], v161 offset:56320
	global_load_lds_dwordx4 v140, s[26:27]
	s_add_i32 m0, s13, 0x2000
	s_add_u32 s24, s24, 0xc000
	s_addc_u32 s25, s25, 0
	s_add_i32 s13, s68, s31
	global_load_lds_dwordx4 v136, s[26:27]
	s_mov_b32 m0, s13
	s_nop 0
	global_load_lds_dwordx4 v140, s[24:25]
	s_add_i32 m0, s13, 0x2000
	s_nop 0
	global_load_lds_dwordx4 v136, s[24:25]
	s_mov_b32 m0, s62
	s_nop 0
	global_load_lds_dwordx4 v142, s[22:23]
	s_mov_b32 m0, s63
	s_nop 0
	global_load_lds_dwordx4 v138, s[22:23]
	s_waitcnt vmcnt(8)
	s_waitcnt lgkmcnt(0)
	v_mfma_f32_16x16x32_bf16 v[68:71], v[152:155], v[186:189], v[68:71]
	v_mfma_f32_16x16x32_bf16 v[68:71], v[156:159], v[190:193], v[68:71]
	s_barrier
	s_setprio 1
	v_mfma_f32_16x16x32_bf16 v[64:67], v[166:169], v[190:193], v[64:67]
	v_mfma_f32_16x16x32_bf16 v[64:67], v[162:165], v[186:189], v[64:67]
	v_mfma_f32_16x16x32_bf16 v[48:51], v[162:165], v[194:197], v[48:51]
	v_mfma_f32_16x16x32_bf16 v[48:51], v[166:169], v[198:201], v[48:51]
	v_mfma_f32_16x16x32_bf16 v[52:55], v[156:159], v[198:201], v[52:55]
	v_mfma_f32_16x16x32_bf16 v[52:55], v[152:155], v[194:197], v[52:55]
	v_mfma_f32_16x16x32_bf16 v[32:35], v[152:155], v[202:205], v[32:35]
	v_mfma_f32_16x16x32_bf16 v[32:35], v[156:159], v[206:209], v[32:35]
	v_mfma_f32_16x16x32_bf16 v[28:31], v[166:169], v[206:209], v[28:31]
	v_mfma_f32_16x16x32_bf16 v[28:31], v[162:165], v[202:205], v[28:31]
	v_mfma_f32_16x16x32_bf16 v[12:15], v[162:165], v[210:213], v[12:15]
	v_mfma_f32_16x16x32_bf16 v[12:15], v[166:169], v[214:217], v[12:15]
	v_mfma_f32_16x16x32_bf16 v[16:19], v[156:159], v[214:217], v[16:19]
	v_mfma_f32_16x16x32_bf16 v[16:19], v[152:155], v[210:213], v[16:19]
	v_mfma_f32_16x16x32_bf16 v[8:11], v[170:173], v[210:213], v[8:11]
	v_mfma_f32_16x16x32_bf16 v[8:11], v[174:177], v[214:217], v[8:11]
	v_mfma_f32_16x16x32_bf16 v[60:63], v[174:177], v[190:193], v[60:63]
	v_mfma_f32_16x16x32_bf16 v[60:63], v[170:173], v[186:189], v[60:63]
	v_mfma_f32_16x16x32_bf16 v[56:59], v[178:181], v[186:189], v[56:59]
	v_mfma_f32_16x16x32_bf16 v[56:59], v[182:185], v[190:193], v[56:59]
	v_mfma_f32_16x16x32_bf16 v[40:43], v[182:185], v[198:201], v[40:43]
	v_mfma_f32_16x16x32_bf16 v[40:43], v[178:181], v[194:197], v[40:43]
	v_mfma_f32_16x16x32_bf16 v[44:47], v[170:173], v[194:197], v[44:47]
	v_mfma_f32_16x16x32_bf16 v[44:47], v[174:177], v[198:201], v[44:47]
	v_mfma_f32_16x16x32_bf16 v[24:27], v[174:177], v[206:209], v[24:27]
	v_mfma_f32_16x16x32_bf16 v[24:27], v[170:173], v[202:205], v[24:27]
	v_mfma_f32_16x16x32_bf16 v[20:23], v[178:181], v[202:205], v[20:23]
	v_mfma_f32_16x16x32_bf16 v[20:23], v[182:185], v[206:209], v[20:23]
	v_mfma_f32_16x16x32_bf16 v[4:7], v[182:185], v[214:217], v[4:7]
	v_mfma_f32_16x16x32_bf16 v[4:7], v[178:181], v[210:213], v[4:7]
	s_setprio 0
	s_barrier
	s_add_i32 vcc_hi, vcc_hi, 2
	s_add_u32 s20, s20, 0x10000
	s_addc_u32 s21, s21, 0
	s_add_u32 s77, s77, 0x10000
	s_addc_u32 vcc_lo, vcc_lo, 0
	s_cmp_gt_u32 vcc_hi, 29
.LBB0_185:
	s_add_u32 s13, s20, 0x4000
	s_addc_u32 s22, s21, 0
	s_cmp_eq_u32 vcc_hi, 28
	s_cselect_b32 s26, s70, s13
	s_cselect_b32 s27, s9, s22
	s_cselect_b32 s24, s71, s77
	s_cselect_b32 s25, s7, vcc_lo
	s_add_u32 s22, s26, 0x8000
	s_addc_u32 s23, s27, 0
	s_add_i32 s13, 0, 0x10000
	v_add_u32_e32 v36, s13, v160
	s_add_i32 s88, 0, 0x14000
	ds_read_b128 v[152:155], v36
	ds_read_b128 v[156:159], v36 offset:1024
	ds_read_b128 v[162:165], v36 offset:2048
	ds_read_b128 v[166:169], v36 offset:3072
	v_add_u32_e32 v36, s88, v160
	ds_read_b128 v[170:173], v36
	ds_read_b128 v[174:177], v36 offset:1024
	ds_read_b128 v[178:181], v36 offset:2048
	ds_read_b128 v[182:185], v36 offset:3072
	s_add_i32 m0, s19, 0xc000
	ds_read_b128 v[186:189], v161
	ds_read_b128 v[190:193], v161 offset:1024
	ds_read_b128 v[194:197], v161 offset:2048
	ds_read_b128 v[198:201], v161 offset:3072
	ds_read_b128 v[202:205], v161 offset:4096
	ds_read_b128 v[206:209], v161 offset:5120
	ds_read_b128 v[210:213], v161 offset:6144
	ds_read_b128 v[214:217], v161 offset:7168
	global_load_lds_dwordx4 v148, s[20:21]
	s_add_i32 m0, s19, 0xe000
	s_nop 0
	global_load_lds_dwordx4 v150, s[20:21]
	s_waitcnt vmcnt(8)
	s_waitcnt lgkmcnt(0)
	v_mfma_f32_16x16x32_bf16 v[132:135], v[152:155], v[186:189], v[132:135]
	v_mfma_f32_16x16x32_bf16 v[132:135], v[156:159], v[190:193], v[132:135]
	s_barrier
; #define PG8_STAGE(bufoff, gbase, voff) do { _Pragma("unroll") for (int _i = 0; _i < 2; ++_i) \
;         __builtin_amdgcn_global_load_lds((const unsigned*)((const char*)(gbase) + (voff)[_i]), (PG8_LAS unsigned*)(lds + (bufoff) + ldsw + _i * 8192), 16, 0, 0); } while (0)
; #define PG8_LDA(dst, b, h) do { _Pragma("unroll") for (int m = 0; m < 4; ++m) _Pragma("unroll") for (int k = 0; k < 2; ++k) dst[m][k] = *(const PG8_LAS bf16x8*)(lds + PG8_SA(b, h) + aoff + m * 2048 + k * 1024); } while (0)
; #define PG8_MMA(ai, bj, At, Bt) do { __builtin_amdgcn_s_setprio(1); _Pragma("unroll") for (int m = 0; m < 4; ++m) _Pragma("unroll") for (int n = 0; n < 2; ++n) _Pragma("unroll") for (int k = 0; k < 2; ++k) \
;         acc[ai][bj][m][n] = __builtin_amdgcn_mfma_f32_16x16x32_bf16(Bt[n][k], At[m][k], acc[ai][bj][m][n], 0, 0, 0); __builtin_amdgcn_s_setprio(0); } while (0)
; #define PG8_WAIT_V(n) asm volatile("s_waitcnt vmcnt(" #n ")" ::: "memory")
; #define PG8_WAIT_L(n) asm volatile("s_waitcnt lgkmcnt(" #n ")" ::: "memory")
; #define PG8_BAR __builtin_amdgcn_s_barrier()
; #define PG8_SCHED __builtin_amdgcn_sched_barrier(0)
; template <class Epi, class Sched, bool ALIGN_EPI = false, bool SP2 = false, bool ABLK = false, bool BBLK = false>
; __device__ __forceinline__ void gemm_phase(PG8_LAS unsigned char* lds, const Gemm g, const Sched& S, const Epi& E) {
;     ...
;             PG8_WAIT_V(8); PG8_WAIT_L(0); PG8_BAR; PG8_MMA(0, 0, At, B0); PG8_MMA(0, 1, At, B1); PG8_BAR; PG8_SCHED;
;             PG8_LDA(At, 0, 1); PG8_STAGE(PG8_SB(0, 0), b2, voffB); PG8_STAGE(PG8_SB(0, 1), b2 + hstepB, voffB); PG8_STAGE(PG8_SA(0, 0), a2, voffA);
;             PG8_WAIT_V(8); PG8_WAIT_L(0); PG8_BAR; PG8_MMA(1, 0, At, B0); PG8_MMA(1, 1, At, B1); PG8_BAR; PG8_SCHED;
	s_setprio 1
	v_mfma_f32_16x16x32_bf16 v[128:131], v[166:169], v[190:193], v[128:131]
	v_mfma_f32_16x16x32_bf16 v[128:131], v[162:165], v[186:189], v[128:131]
	v_mfma_f32_16x16x32_bf16 v[112:115], v[162:165], v[194:197], v[112:115]
	v_mfma_f32_16x16x32_bf16 v[112:115], v[166:169], v[198:201], v[112:115]
	v_mfma_f32_16x16x32_bf16 v[116:119], v[156:159], v[198:201], v[116:119]
	v_mfma_f32_16x16x32_bf16 v[116:119], v[152:155], v[194:197], v[116:119]
	v_mfma_f32_16x16x32_bf16 v[100:103], v[152:155], v[202:205], v[100:103]
	v_mfma_f32_16x16x32_bf16 v[100:103], v[156:159], v[206:209], v[100:103]
	v_mfma_f32_16x16x32_bf16 v[96:99], v[166:169], v[206:209], v[96:99]
	v_mfma_f32_16x16x32_bf16 v[96:99], v[162:165], v[202:205], v[96:99]
	v_mfma_f32_16x16x32_bf16 v[80:83], v[162:165], v[210:213], v[80:83]
	v_mfma_f32_16x16x32_bf16 v[80:83], v[166:169], v[214:217], v[80:83]
	v_mfma_f32_16x16x32_bf16 v[84:87], v[156:159], v[214:217], v[84:87]
	v_mfma_f32_16x16x32_bf16 v[84:87], v[152:155], v[210:213], v[84:87]
	v_mfma_f32_16x16x32_bf16 v[76:79], v[170:173], v[210:213], v[76:79]
	v_mfma_f32_16x16x32_bf16 v[76:79], v[174:177], v[214:217], v[76:79]
	v_mfma_f32_16x16x32_bf16 v[124:127], v[174:177], v[190:193], v[124:127]
	v_mfma_f32_16x16x32_bf16 v[124:127], v[170:173], v[186:189], v[124:127]
	v_mfma_f32_16x16x32_bf16 v[120:123], v[178:181], v[186:189], v[120:123]
	v_mfma_f32_16x16x32_bf16 v[120:123], v[182:185], v[190:193], v[120:123]
	v_mfma_f32_16x16x32_bf16 v[104:107], v[182:185], v[198:201], v[104:107]
	v_mfma_f32_16x16x32_bf16 v[104:107], v[178:181], v[194:197], v[104:107]
	v_mfma_f32_16x16x32_bf16 v[108:111], v[170:173], v[194:197], v[108:111]
	v_mfma_f32_16x16x32_bf16 v[108:111], v[174:177], v[198:201], v[108:111]
	v_mfma_f32_16x16x32_bf16 v[92:95], v[174:177], v[206:209], v[92:95]
	v_mfma_f32_16x16x32_bf16 v[92:95], v[170:173], v[202:205], v[92:95]
	v_mfma_f32_16x16x32_bf16 v[88:91], v[178:181], v[202:205], v[88:91]
	v_mfma_f32_16x16x32_bf16 v[88:91], v[182:185], v[206:209], v[88:91]
	v_mfma_f32_16x16x32_bf16 v[72:75], v[182:185], v[214:217], v[72:75]
	v_mfma_f32_16x16x32_bf16 v[72:75], v[178:181], v[210:213], v[72:75]
	s_setprio 0
	s_barrier
	s_add_i32 s13, s13, s31
	s_mov_b32 m0, s13
	ds_read_b128 v[186:189], v161 offset:16384
	ds_read_b128 v[190:193], v161 offset:17408
	ds_read_b128 v[194:197], v161 offset:18432
	ds_read_b128 v[198:201], v161 offset:19456
	ds_read_b128 v[202:205], v161 offset:20480
	ds_read_b128 v[206:209], v161 offset:21504
	ds_read_b128 v[210:213], v161 offset:22528
	ds_read_b128 v[214:217], v161 offset:23552
	global_load_lds_dwordx4 v140, s[24:25]
	s_add_i32 m0, s13, 0x2000
	s_add_u32 s68, s24, 0x4000
	s_addc_u32 s69, s25, 0
	s_add_i32 s13, s88, s31
	global_load_lds_dwordx4 v136, s[24:25]
	s_mov_b32 m0, s13
	s_nop 0
	global_load_lds_dwordx4 v140, s[68:69]
	s_add_i32 m0, s13, 0x2000
	s_nop 0
	global_load_lds_dwordx4 v136, s[68:69]
	s_mov_b32 m0, s19
	s_nop 0
	global_load_lds_dwordx4 v142, s[26:27]
	s_mov_b32 m0, s35
	s_nop 0
	global_load_lds_dwordx4 v138, s[26:27]
	s_waitcnt vmcnt(8)
	s_waitcnt lgkmcnt(0)
	v_mfma_f32_16x16x32_bf16 v[68:71], v[152:155], v[186:189], v[68:71]
	v_mfma_f32_16x16x32_bf16 v[68:71], v[156:159], v[190:193], v[68:71]
	s_barrier
	s_setprio 1
	v_mfma_f32_16x16x32_bf16 v[64:67], v[166:169], v[190:193], v[64:67]
	v_mfma_f32_16x16x32_bf16 v[64:67], v[162:165], v[186:189], v[64:67]
	v_mfma_f32_16x16x32_bf16 v[48:51], v[162:165], v[194:197], v[48:51]
	v_mfma_f32_16x16x32_bf16 v[48:51], v[166:169], v[198:201], v[48:51]
	v_mfma_f32_16x16x32_bf16 v[52:55], v[156:159], v[198:201], v[52:55]
	v_mfma_f32_16x16x32_bf16 v[52:55], v[152:155], v[194:197], v[52:55]
	v_mfma_f32_16x16x32_bf16 v[32:35], v[152:155], v[202:205], v[32:35]
	v_mfma_f32_16x16x32_bf16 v[32:35], v[156:159], v[206:209], v[32:35]
	v_mfma_f32_16x16x32_bf16 v[28:31], v[166:169], v[206:209], v[28:31]
	v_mfma_f32_16x16x32_bf16 v[28:31], v[162:165], v[202:205], v[28:31]
	v_mfma_f32_16x16x32_bf16 v[12:15], v[162:165], v[210:213], v[12:15]
	v_mfma_f32_16x16x32_bf16 v[12:15], v[166:169], v[214:217], v[12:15]
	v_mfma_f32_16x16x32_bf16 v[16:19], v[156:159], v[214:217], v[16:19]
	v_mfma_f32_16x16x32_bf16 v[16:19], v[152:155], v[210:213], v[16:19]
	v_mfma_f32_16x16x32_bf16 v[8:11], v[170:173], v[210:213], v[8:11]
	v_mfma_f32_16x16x32_bf16 v[8:11], v[174:177], v[214:217], v[8:11]
	v_mfma_f32_16x16x32_bf16 v[60:63], v[174:177], v[190:193], v[60:63]
	v_mfma_f32_16x16x32_bf16 v[60:63], v[170:173], v[186:189], v[60:63]
	v_mfma_f32_16x16x32_bf16 v[56:59], v[178:181], v[186:189], v[56:59]
	v_mfma_f32_16x16x32_bf16 v[56:59], v[182:185], v[190:193], v[56:59]
	v_mfma_f32_16x16x32_bf16 v[40:43], v[182:185], v[198:201], v[40:43]
	v_mfma_f32_16x16x32_bf16 v[40:43], v[178:181], v[194:197], v[40:43]
	v_mfma_f32_16x16x32_bf16 v[44:47], v[170:173], v[194:197], v[44:47]
	v_mfma_f32_16x16x32_bf16 v[44:47], v[174:177], v[198:201], v[44:47]
	v_mfma_f32_16x16x32_bf16 v[24:27], v[174:177], v[206:209], v[24:27]
	v_mfma_f32_16x16x32_bf16 v[24:27], v[170:173], v[202:205], v[24:27]
	v_mfma_f32_16x16x32_bf16 v[20:23], v[178:181], v[202:205], v[20:23]
	v_mfma_f32_16x16x32_bf16 v[20:23], v[182:185], v[206:209], v[20:23]
	v_mfma_f32_16x16x32_bf16 v[4:7], v[182:185], v[214:217], v[4:7]
	v_mfma_f32_16x16x32_bf16 v[4:7], v[178:181], v[210:213], v[4:7]
	s_setprio 0
	s_barrier
; #define PG8_STAGE(bufoff, gbase, voff) do { _Pragma("unroll") for (int _i = 0; _i < 2; ++_i) \
;         __builtin_amdgcn_global_load_lds((const unsigned*)((const char*)(gbase) + (voff)[_i]), (PG8_LAS unsigned*)(lds + (bufoff) + ldsw + _i * 8192), 16, 0, 0); } while (0)
; #define PG8_LDA(dst, b, h) do { _Pragma("unroll") for (int m = 0; m < 4; ++m) _Pragma("unroll") for (int k = 0; k < 2; ++k) dst[m][k] = *(const PG8_LAS bf16x8*)(lds + PG8_SA(b, h) + aoff + m * 2048 + k * 1024); } while (0)
; #define PG8_LDB(dst, b, h) do { _Pragma("unroll") for (int n = 0; n < 2; ++n) _Pragma("unroll") for (int k = 0; k < 2; ++k) dst[n][k] = *(const PG8_LAS bf16x8*)(lds + PG8_SB(b, h) + boff + n * 2048 + k * 1024); } while (0)
; #define PG8_MMA(ai, bj, At, Bt) do { __builtin_amdgcn_s_setprio(1); _Pragma("unroll") for (int m = 0; m < 4; ++m) _Pragma("unroll") for (int n = 0; n < 2; ++n) _Pragma("unroll") for (int k = 0; k < 2; ++k) \
;         acc[ai][bj][m][n] = __builtin_amdgcn_mfma_f32_16x16x32_bf16(Bt[n][k], At[m][k], acc[ai][bj][m][n], 0, 0, 0); __builtin_amdgcn_s_setprio(0); } while (0)
; #define PG8_WAIT_V(n) asm volatile("s_waitcnt vmcnt(" #n ")" ::: "memory")
; #define PG8_BAR __builtin_amdgcn_s_barrier()
; template <class Epi, class Sched, bool ALIGN_EPI = false, bool SP2 = false, bool ABLK = false, bool BBLK = false>
; __device__ __forceinline__ void gemm_phase(PG8_LAS unsigned char* lds, const Gemm g, const Sched& S, const Epi& E) {
;     ...
;         for (int t = 0; t < nt; t += 2) {
;             const bool last = (t == nt - 2);
;             const char* a1 = cA + (size_t)(t + 1) * kstepA;
;             const char* a2 = last ? nA : cA + (size_t)(t + 2) * kstepA; const char* b2 = last ? nB : cB + (size_t)(t + 2) * kstepB;
;             const char* a3 = a2 + kstepA; const char* b3 = b2 + kstepB;
;     ...
;             PG8_LDB(B0, 1, 0); PG8_LDB(B1, 1, 1); PG8_SCHED; PG8_LDA(At, 1, 0); PG8_STAGE(PG8_SA(0, 1), a2 + hstepA, voffA);
;             PG8_WAIT_V(8); PG8_WAIT_L(0); PG8_BAR; PG8_MMA(0, 0, At, B0); PG8_MMA(0, 1, At, B1); PG8_BAR; PG8_SCHED;
;             PG8_LDA(At, 1, 1); PG8_STAGE(PG8_SB(1, 0), b3, voffB); PG8_STAGE(PG8_SB(1, 1), b3 + hstepB, voffB); PG8_STAGE(PG8_SA(1, 0), a3, voffA);
;             PG8_WAIT_V(8); PG8_WAIT_L(0); PG8_BAR; PG8_MMA(1, 0, At, B0); PG8_MMA(1, 1, At, B1); PG8_BAR; PG8_SCHED;
;     ...
;         if constexpr (ALIGN_EPI) { if (wr == 0) PG8_BAR; }
	s_add_i32 s13, 0, 0x18000
	v_add_u32_e32 v36, s13, v160
	s_add_i32 s68, 0, 0x1c000
	ds_read_b128 v[152:155], v36
	ds_read_b128 v[156:159], v36 offset:1024
	ds_read_b128 v[162:165], v36 offset:2048
	ds_read_b128 v[166:169], v36 offset:3072
	v_add_u32_e32 v36, s68, v160
	ds_read_b128 v[170:173], v36
	ds_read_b128 v[174:177], v36 offset:1024
	ds_read_b128 v[178:181], v36 offset:2048
	ds_read_b128 v[182:185], v36 offset:3072
	s_add_u32 s26, s26, 0x4000
	s_addc_u32 s27, s27, 0
	s_mov_b32 m0, s36
	ds_read_b128 v[186:189], v161 offset:32768
	ds_read_b128 v[190:193], v161 offset:33792
	ds_read_b128 v[194:197], v161 offset:34816
	ds_read_b128 v[198:201], v161 offset:35840
	ds_read_b128 v[202:205], v161 offset:36864
	ds_read_b128 v[206:209], v161 offset:37888
	ds_read_b128 v[210:213], v161 offset:38912
	ds_read_b128 v[214:217], v161 offset:39936
	global_load_lds_dwordx4 v142, s[26:27]
	s_mov_b32 m0, s37
	s_nop 0
	global_load_lds_dwordx4 v138, s[26:27]
	s_waitcnt vmcnt(8)
	s_waitcnt lgkmcnt(0)
	v_mfma_f32_16x16x32_bf16 v[132:135], v[152:155], v[186:189], v[132:135]
	v_mfma_f32_16x16x32_bf16 v[132:135], v[156:159], v[190:193], v[132:135]
	s_barrier
	s_setprio 1
	v_mfma_f32_16x16x32_bf16 v[128:131], v[166:169], v[190:193], v[128:131]
	v_mfma_f32_16x16x32_bf16 v[128:131], v[162:165], v[186:189], v[128:131]
	v_mfma_f32_16x16x32_bf16 v[112:115], v[162:165], v[194:197], v[112:115]
	v_mfma_f32_16x16x32_bf16 v[112:115], v[166:169], v[198:201], v[112:115]
	v_mfma_f32_16x16x32_bf16 v[116:119], v[156:159], v[198:201], v[116:119]
	v_mfma_f32_16x16x32_bf16 v[116:119], v[152:155], v[194:197], v[116:119]
	v_mfma_f32_16x16x32_bf16 v[100:103], v[152:155], v[202:205], v[100:103]
	v_mfma_f32_16x16x32_bf16 v[100:103], v[156:159], v[206:209], v[100:103]
	v_mfma_f32_16x16x32_bf16 v[96:99], v[166:169], v[206:209], v[96:99]
	v_mfma_f32_16x16x32_bf16 v[96:99], v[162:165], v[202:205], v[96:99]
	v_mfma_f32_16x16x32_bf16 v[80:83], v[162:165], v[210:213], v[80:83]
	v_mfma_f32_16x16x32_bf16 v[80:83], v[166:169], v[214:217], v[80:83]
	v_mfma_f32_16x16x32_bf16 v[84:87], v[156:159], v[214:217], v[84:87]
	v_mfma_f32_16x16x32_bf16 v[84:87], v[152:155], v[210:213], v[84:87]
	v_mfma_f32_16x16x32_bf16 v[76:79], v[170:173], v[210:213], v[76:79]
	v_mfma_f32_16x16x32_bf16 v[76:79], v[174:177], v[214:217], v[76:79]
	v_mfma_f32_16x16x32_bf16 v[124:127], v[174:177], v[190:193], v[124:127]
	v_mfma_f32_16x16x32_bf16 v[124:127], v[170:173], v[186:189], v[124:127]
	v_mfma_f32_16x16x32_bf16 v[120:123], v[178:181], v[186:189], v[120:123]
	v_mfma_f32_16x16x32_bf16 v[120:123], v[182:185], v[190:193], v[120:123]
	v_mfma_f32_16x16x32_bf16 v[104:107], v[182:185], v[198:201], v[104:107]
	v_mfma_f32_16x16x32_bf16 v[104:107], v[178:181], v[194:197], v[104:107]
	v_mfma_f32_16x16x32_bf16 v[108:111], v[170:173], v[194:197], v[108:111]
	v_mfma_f32_16x16x32_bf16 v[108:111], v[174:177], v[198:201], v[108:111]
	v_mfma_f32_16x16x32_bf16 v[92:95], v[174:177], v[206:209], v[92:95]
	v_mfma_f32_16x16x32_bf16 v[92:95], v[170:173], v[202:205], v[92:95]
	v_mfma_f32_16x16x32_bf16 v[88:91], v[178:181], v[202:205], v[88:91]
	v_mfma_f32_16x16x32_bf16 v[88:91], v[182:185], v[206:209], v[88:91]
	v_mfma_f32_16x16x32_bf16 v[72:75], v[182:185], v[214:217], v[72:75]
	v_mfma_f32_16x16x32_bf16 v[72:75], v[178:181], v[210:213], v[72:75]
	s_setprio 0
	s_barrier
	s_add_u32 s26, s24, 0x8000
	s_addc_u32 s27, s25, 0
	s_add_i32 s13, s13, s31
	s_mov_b32 m0, s13
	ds_read_b128 v[186:189], v161 offset:49152
	ds_read_b128 v[190:193], v161 offset:50176
	ds_read_b128 v[194:197], v161 offset:51200
	ds_read_b128 v[198:201], v161 offset:52224
	ds_read_b128 v[202:205], v161 offset:53248
	ds_read_b128 v[206:209], v161 offset:54272
	ds_read_b128 v[210:213], v161 offset:55296
	ds_read_b128 v[214:217], v161 offset:56320
	global_load_lds_dwordx4 v140, s[26:27]
	s_add_i32 m0, s13, 0x2000
	s_add_u32 s24, s24, 0xc000
	s_addc_u32 s25, s25, 0
	s_add_i32 s13, s68, s31
	global_load_lds_dwordx4 v136, s[26:27]
	s_mov_b32 m0, s13
	s_nop 0
	global_load_lds_dwordx4 v140, s[24:25]
	s_add_i32 m0, s13, 0x2000
	s_nop 0
	global_load_lds_dwordx4 v136, s[24:25]
	s_mov_b32 m0, s62
	s_nop 0
	global_load_lds_dwordx4 v142, s[22:23]
	s_mov_b32 m0, s63
	s_nop 0
	global_load_lds_dwordx4 v138, s[22:23]
	s_waitcnt vmcnt(8)
	s_waitcnt lgkmcnt(0)
	v_mfma_f32_16x16x32_bf16 v[68:71], v[152:155], v[186:189], v[68:71]
	v_mfma_f32_16x16x32_bf16 v[68:71], v[156:159], v[190:193], v[68:71]
	s_barrier
	s_setprio 1
	v_mfma_f32_16x16x32_bf16 v[64:67], v[166:169], v[190:193], v[64:67]
	v_mfma_f32_16x16x32_bf16 v[64:67], v[162:165], v[186:189], v[64:67]
	v_mfma_f32_16x16x32_bf16 v[48:51], v[162:165], v[194:197], v[48:51]
	v_mfma_f32_16x16x32_bf16 v[48:51], v[166:169], v[198:201], v[48:51]
	v_mfma_f32_16x16x32_bf16 v[52:55], v[156:159], v[198:201], v[52:55]
	v_mfma_f32_16x16x32_bf16 v[52:55], v[152:155], v[194:197], v[52:55]
	v_mfma_f32_16x16x32_bf16 v[32:35], v[152:155], v[202:205], v[32:35]
	v_mfma_f32_16x16x32_bf16 v[32:35], v[156:159], v[206:209], v[32:35]
	v_mfma_f32_16x16x32_bf16 v[28:31], v[166:169], v[206:209], v[28:31]
	v_mfma_f32_16x16x32_bf16 v[28:31], v[162:165], v[202:205], v[28:31]
	v_mfma_f32_16x16x32_bf16 v[12:15], v[162:165], v[210:213], v[12:15]
	v_mfma_f32_16x16x32_bf16 v[12:15], v[166:169], v[214:217], v[12:15]
	v_mfma_f32_16x16x32_bf16 v[16:19], v[156:159], v[214:217], v[16:19]
	v_mfma_f32_16x16x32_bf16 v[16:19], v[152:155], v[210:213], v[16:19]
	v_mfma_f32_16x16x32_bf16 v[8:11], v[170:173], v[210:213], v[8:11]
	v_mfma_f32_16x16x32_bf16 v[8:11], v[174:177], v[214:217], v[8:11]
	v_mfma_f32_16x16x32_bf16 v[60:63], v[174:177], v[190:193], v[60:63]
	v_mfma_f32_16x16x32_bf16 v[60:63], v[170:173], v[186:189], v[60:63]
	v_mfma_f32_16x16x32_bf16 v[56:59], v[178:181], v[186:189], v[56:59]
	v_mfma_f32_16x16x32_bf16 v[56:59], v[182:185], v[190:193], v[56:59]
	v_mfma_f32_16x16x32_bf16 v[40:43], v[182:185], v[198:201], v[40:43]
	v_mfma_f32_16x16x32_bf16 v[40:43], v[178:181], v[194:197], v[40:43]
	v_mfma_f32_16x16x32_bf16 v[44:47], v[170:173], v[194:197], v[44:47]
	v_mfma_f32_16x16x32_bf16 v[44:47], v[174:177], v[198:201], v[44:47]
	v_mfma_f32_16x16x32_bf16 v[24:27], v[174:177], v[206:209], v[24:27]
	v_mfma_f32_16x16x32_bf16 v[24:27], v[170:173], v[202:205], v[24:27]
	v_mfma_f32_16x16x32_bf16 v[20:23], v[178:181], v[202:205], v[20:23]
	v_mfma_f32_16x16x32_bf16 v[20:23], v[182:185], v[206:209], v[20:23]
	v_mfma_f32_16x16x32_bf16 v[4:7], v[182:185], v[214:217], v[4:7]
	v_mfma_f32_16x16x32_bf16 v[4:7], v[178:181], v[210:213], v[4:7]
	s_setprio 0
	s_barrier
	s_add_i32 vcc_hi, vcc_hi, 2
	s_add_u32 s20, s20, 0x10000
	s_addc_u32 s21, s21, 0
	s_add_u32 s77, s77, 0x10000
	s_addc_u32 vcc_lo, vcc_lo, 0
	s_cmp_gt_u32 vcc_hi, 29
	s_cbranch_scc0 .LBB0_185
	s_and_b64 vcc, exec, s[4:5]
	s_cbranch_vccz .LBB0_188
	s_barrier

; #define PG8_STAGE(bufoff, gbase, voff) do { _Pragma("unroll") for (int _i = 0; _i < 2; ++_i) \
;         __builtin_amdgcn_global_load_lds((const unsigned*)((const char*)(gbase) + (voff)[_i]), (PG8_LAS unsigned*)(lds + (bufoff) + ldsw + _i * 8192), 16, 0, 0); } while (0)
; #define PG8_LDA(dst, b, h) do { _Pragma("unroll") for (int m = 0; m < 4; ++m) _Pragma("unroll") for (int k = 0; k < 2; ++k) dst[m][k] = *(const PG8_LAS bf16x8*)(lds + PG8_SA(b, h) + aoff + m * 2048 + k * 1024); } while (0)
; #define PG8_LDB(dst, b, h) do { _Pragma("unroll") for (int n = 0; n < 2; ++n) _Pragma("unroll") for (int k = 0; k < 2; ++k) dst[n][k] = *(const PG8_LAS bf16x8*)(lds + PG8_SB(b, h) + boff + n * 2048 + k * 1024); } while (0)
; #define PG8_MMA(ai, bj, At, Bt) do { __builtin_amdgcn_s_setprio(1); _Pragma("unroll") for (int m = 0; m < 4; ++m) _Pragma("unroll") for (int n = 0; n < 2; ++n) _Pragma("unroll") for (int k = 0; k < 2; ++k) \
;         acc[ai][bj][m][n] = __builtin_amdgcn_mfma_f32_16x16x32_bf16(Bt[n][k], At[m][k], acc[ai][bj][m][n], 0, 0, 0); __builtin_amdgcn_s_setprio(0); } while (0)
; #define PG8_WAIT_V(n) asm volatile("s_waitcnt vmcnt(" #n ")" ::: "memory")
; #define PG8_BAR __builtin_amdgcn_s_barrier()
; template <class Epi, class Sched, bool ALIGN_EPI = false, bool SP2 = false, bool ABLK = false, bool BBLK = false>
; __device__ __forceinline__ void gemm_phase(PG8_LAS unsigned char* lds, const Gemm g, const Sched& S, const Epi& E) {
;     ...
;             const bool last = (t == nt - 2);
;             const char* a1 = cA + (size_t)(t + 1) * kstepA;
;             const char* a2 = last ? nA : cA + (size_t)(t + 2) * kstepA; const char* b2 = last ? nB : cB + (size_t)(t + 2) * kstepB;
;             const char* a3 = a2 + kstepA; const char* b3 = b2 + kstepB;
;             if (last && has_next) S.a_ready(nxt);
;             if constexpr (SP2) {
;             PG8_LDB(B0, 0, 0); PG8_LDB(B1, 0, 1); PG8_SCHED; PG8_LDA(At, 0, 0); PG8_STAGE(PG8_SA(1, 1), a1 + hstepA, voffA);
;             PG8_WAIT_V(8); PG8_WAIT_L(0); PG8_BAR; PG8_MMA(0, 0, At, B0); PG8_MMA(0, 1, At, B1); PG8_BAR; PG8_SCHED;
;             PG8_LDA(At, 0, 1); PG8_STAGE(PG8_SB(0, 0), b2, voffB); PG8_STAGE(PG8_SB(0, 1), b2 + hstepB, voffB); PG8_STAGE(PG8_SA(0, 0), a2, voffA);
;             PG8_WAIT_V(8); PG8_WAIT_L(0); PG8_BAR; PG8_MMA(1, 0, At, B0); PG8_MMA(1, 1, At, B1); PG8_BAR; PG8_SCHED;
.LBB0_438:
	s_add_u32 s10, s10, 0xc000
	s_addc_u32 s11, s11, 0
	s_add_u32 vcc_lo, s16, 0x10000
	s_addc_u32 vcc_hi, s17, 0
	s_mov_b32 s13, -2
	s_add_u32 s16, s10, 0x4000
	s_addc_u32 s17, s11, 0
	s_cmpk_eq_i32 s13, 0x54
	s_cselect_b32 s20, s0, s16
	s_cselect_b32 s21, s1, s17
	s_cselect_b32 s18, s8, vcc_lo
	s_cselect_b32 s19, s9, vcc_hi
	s_add_u32 s16, s20, 0x8000
	s_addc_u32 s17, s21, 0
	s_add_i32 s68, 0, 0x10000
	v_add_u32_e32 v36, s68, v148
	s_add_i32 s88, 0, 0x14000
	ds_read_b128 v[152:155], v36
	ds_read_b128 v[156:159], v36 offset:1024
	ds_read_b128 v[160:163], v36 offset:2048
	ds_read_b128 v[164:167], v36 offset:3072
	v_add_u32_e32 v36, s88, v148
	ds_read_b128 v[168:171], v36
	ds_read_b128 v[172:175], v36 offset:1024
	ds_read_b128 v[176:179], v36 offset:2048
	ds_read_b128 v[180:183], v36 offset:3072
	s_add_i32 m0, s27, 0xc000
	ds_read_b128 v[184:187], v150
	ds_read_b128 v[188:191], v150 offset:1024
	ds_read_b128 v[192:195], v150 offset:2048
	ds_read_b128 v[196:199], v150 offset:3072
	ds_read_b128 v[200:203], v150 offset:4096
	ds_read_b128 v[204:207], v150 offset:5120
	ds_read_b128 v[208:211], v150 offset:6144
	ds_read_b128 v[212:215], v150 offset:7168
	global_load_lds_dwordx4 v144, s[10:11]
	s_add_i32 m0, s27, 0xe000
	s_nop 0
	global_load_lds_dwordx4 v146, s[10:11]
	s_waitcnt vmcnt(8)
	s_waitcnt lgkmcnt(0)
	v_mfma_f32_16x16x32_bf16 v[132:135], v[152:155], v[184:187], 0
	v_mfma_f32_16x16x32_bf16 v[132:135], v[156:159], v[188:191], v[132:135]
	s_barrier
	s_setprio 1
	v_mfma_f32_16x16x32_bf16 v[128:131], v[164:167], v[188:191], 0
	v_mfma_f32_16x16x32_bf16 v[128:131], v[160:163], v[184:187], v[128:131]
	v_mfma_f32_16x16x32_bf16 v[120:123], v[160:163], v[192:195], 0
	v_mfma_f32_16x16x32_bf16 v[120:123], v[164:167], v[196:199], v[120:123]
	v_mfma_f32_16x16x32_bf16 v[124:127], v[156:159], v[196:199], 0
	v_mfma_f32_16x16x32_bf16 v[124:127], v[152:155], v[192:195], v[124:127]
	v_mfma_f32_16x16x32_bf16 v[108:111], v[152:155], v[200:203], 0
	v_mfma_f32_16x16x32_bf16 v[108:111], v[156:159], v[204:207], v[108:111]
	v_mfma_f32_16x16x32_bf16 v[104:107], v[164:167], v[204:207], 0
	v_mfma_f32_16x16x32_bf16 v[104:107], v[160:163], v[200:203], v[104:107]
	v_mfma_f32_16x16x32_bf16 v[88:91], v[160:163], v[208:211], 0
	v_mfma_f32_16x16x32_bf16 v[88:91], v[164:167], v[212:215], v[88:91]
	v_mfma_f32_16x16x32_bf16 v[92:95], v[156:159], v[212:215], 0
	v_mfma_f32_16x16x32_bf16 v[92:95], v[152:155], v[208:211], v[92:95]
	v_mfma_f32_16x16x32_bf16 v[76:79], v[168:171], v[208:211], 0
	v_mfma_f32_16x16x32_bf16 v[76:79], v[172:175], v[212:215], v[76:79]
	v_mfma_f32_16x16x32_bf16 v[116:119], v[172:175], v[188:191], 0
	v_mfma_f32_16x16x32_bf16 v[116:119], v[168:171], v[184:187], v[116:119]
	v_mfma_f32_16x16x32_bf16 v[112:115], v[176:179], v[184:187], 0
	v_mfma_f32_16x16x32_bf16 v[112:115], v[180:183], v[188:191], v[112:115]
	v_mfma_f32_16x16x32_bf16 v[96:99], v[180:183], v[196:199], 0
	v_mfma_f32_16x16x32_bf16 v[96:99], v[176:179], v[192:195], v[96:99]
	v_mfma_f32_16x16x32_bf16 v[100:103], v[168:171], v[192:195], 0
	v_mfma_f32_16x16x32_bf16 v[100:103], v[172:175], v[196:199], v[100:103]
	v_mfma_f32_16x16x32_bf16 v[84:87], v[172:175], v[204:207], 0
	v_mfma_f32_16x16x32_bf16 v[84:87], v[168:171], v[200:203], v[84:87]
	v_mfma_f32_16x16x32_bf16 v[80:83], v[176:179], v[200:203], 0
	v_mfma_f32_16x16x32_bf16 v[80:83], v[180:183], v[204:207], v[80:83]
	v_mfma_f32_16x16x32_bf16 v[72:75], v[180:183], v[212:215], 0
	v_mfma_f32_16x16x32_bf16 v[72:75], v[176:179], v[208:211], v[72:75]
	s_setprio 0
	s_barrier
	s_add_i32 s68, s68, s24
	s_mov_b32 m0, s68
	ds_read_b128 v[184:187], v150 offset:16384
	ds_read_b128 v[188:191], v150 offset:17408
	ds_read_b128 v[192:195], v150 offset:18432
	ds_read_b128 v[196:199], v150 offset:19456
	ds_read_b128 v[200:203], v150 offset:20480
	ds_read_b128 v[204:207], v150 offset:21504
	ds_read_b128 v[208:211], v150 offset:22528
	ds_read_b128 v[212:215], v150 offset:23552
	global_load_lds_dwordx4 v138, s[18:19]
	s_add_i32 m0, s68, 0x2000
	s_add_u32 s68, s18, 0x4000
	s_addc_u32 s69, s19, 0
	s_add_i32 s88, s88, s24
	global_load_lds_dwordx4 v142, s[18:19]
	s_mov_b32 m0, s88
	s_nop 0
	global_load_lds_dwordx4 v138, s[68:69]
	s_add_i32 m0, s88, 0x2000
	s_nop 0
	global_load_lds_dwordx4 v142, s[68:69]
	s_mov_b32 m0, s27
	s_nop 0
	global_load_lds_dwordx4 v136, s[20:21]
	s_mov_b32 m0, s28
	s_nop 0
	global_load_lds_dwordx4 v140, s[20:21]
	s_waitcnt vmcnt(8)
	s_waitcnt lgkmcnt(0)
	v_mfma_f32_16x16x32_bf16 v[68:71], v[152:155], v[184:187], 0
	v_mfma_f32_16x16x32_bf16 v[68:71], v[156:159], v[188:191], v[68:71]
	s_barrier
	s_setprio 1
	v_mfma_f32_16x16x32_bf16 v[64:67], v[164:167], v[188:191], 0
	v_mfma_f32_16x16x32_bf16 v[64:67], v[160:163], v[184:187], v[64:67]
	v_mfma_f32_16x16x32_bf16 v[56:59], v[160:163], v[192:195], 0
	v_mfma_f32_16x16x32_bf16 v[56:59], v[164:167], v[196:199], v[56:59]
	v_mfma_f32_16x16x32_bf16 v[60:63], v[156:159], v[196:199], 0
	v_mfma_f32_16x16x32_bf16 v[60:63], v[152:155], v[192:195], v[60:63]
	v_mfma_f32_16x16x32_bf16 v[44:47], v[152:155], v[200:203], 0
	v_mfma_f32_16x16x32_bf16 v[44:47], v[156:159], v[204:207], v[44:47]
	v_mfma_f32_16x16x32_bf16 v[40:43], v[164:167], v[204:207], 0
	v_mfma_f32_16x16x32_bf16 v[40:43], v[160:163], v[200:203], v[40:43]
	v_mfma_f32_16x16x32_bf16 v[20:23], v[160:163], v[208:211], 0
	v_mfma_f32_16x16x32_bf16 v[20:23], v[164:167], v[212:215], v[20:23]
	v_mfma_f32_16x16x32_bf16 v[24:27], v[156:159], v[212:215], 0
	v_mfma_f32_16x16x32_bf16 v[24:27], v[152:155], v[208:211], v[24:27]
	v_mfma_f32_16x16x32_bf16 v[8:11], v[168:171], v[208:211], 0
	v_mfma_f32_16x16x32_bf16 v[8:11], v[172:175], v[212:215], v[8:11]
	v_mfma_f32_16x16x32_bf16 v[52:55], v[172:175], v[188:191], 0
	v_mfma_f32_16x16x32_bf16 v[52:55], v[168:171], v[184:187], v[52:55]
	v_mfma_f32_16x16x32_bf16 v[48:51], v[176:179], v[184:187], 0
	v_mfma_f32_16x16x32_bf16 v[48:51], v[180:183], v[188:191], v[48:51]
	v_mfma_f32_16x16x32_bf16 v[28:31], v[180:183], v[196:199], 0
	v_mfma_f32_16x16x32_bf16 v[28:31], v[176:179], v[192:195], v[28:31]
	v_mfma_f32_16x16x32_bf16 v[32:35], v[168:171], v[192:195], 0
	v_mfma_f32_16x16x32_bf16 v[32:35], v[172:175], v[196:199], v[32:35]
	v_mfma_f32_16x16x32_bf16 v[16:19], v[172:175], v[204:207], 0
	v_mfma_f32_16x16x32_bf16 v[16:19], v[168:171], v[200:203], v[16:19]
	v_mfma_f32_16x16x32_bf16 v[12:15], v[176:179], v[200:203], 0
	v_mfma_f32_16x16x32_bf16 v[12:15], v[180:183], v[204:207], v[12:15]
	v_mfma_f32_16x16x32_bf16 v[4:7], v[180:183], v[212:215], 0
	v_mfma_f32_16x16x32_bf16 v[4:7], v[176:179], v[208:211], v[4:7]
	s_setprio 0
	s_barrier
; #define PG8_STAGE(bufoff, gbase, voff) do { _Pragma("unroll") for (int _i = 0; _i < 2; ++_i) \
;         __builtin_amdgcn_global_load_lds((const unsigned*)((const char*)(gbase) + (voff)[_i]), (PG8_LAS unsigned*)(lds + (bufoff) + ldsw + _i * 8192), 16, 0, 0); } while (0)
; #define PG8_LDA(dst, b, h) do { _Pragma("unroll") for (int m = 0; m < 4; ++m) _Pragma("unroll") for (int k = 0; k < 2; ++k) dst[m][k] = *(const PG8_LAS bf16x8*)(lds + PG8_SA(b, h) + aoff + m * 2048 + k * 1024); } while (0)
; #define PG8_LDB(dst, b, h) do { _Pragma("unroll") for (int n = 0; n < 2; ++n) _Pragma("unroll") for (int k = 0; k < 2; ++k) dst[n][k] = *(const PG8_LAS bf16x8*)(lds + PG8_SB(b, h) + boff + n * 2048 + k * 1024); } while (0)
; #define PG8_MMA(ai, bj, At, Bt) do { __builtin_amdgcn_s_setprio(1); _Pragma("unroll") for (int m = 0; m < 4; ++m) _Pragma("unroll") for (int n = 0; n < 2; ++n) _Pragma("unroll") for (int k = 0; k < 2; ++k) \
;         acc[ai][bj][m][n] = __builtin_amdgcn_mfma_f32_16x16x32_bf16(Bt[n][k], At[m][k], acc[ai][bj][m][n], 0, 0, 0); __builtin_amdgcn_s_setprio(0); } while (0)
; #define PG8_WAIT_V(n) asm volatile("s_waitcnt vmcnt(" #n ")" ::: "memory")
; #define PG8_WAIT_L(n) asm volatile("s_waitcnt lgkmcnt(" #n ")" ::: "memory")
; #define PG8_BAR __builtin_amdgcn_s_barrier()
; #define PG8_SCHED __builtin_amdgcn_sched_barrier(0)
; template <class Epi, class Sched, bool ALIGN_EPI = false, bool SP2 = false, bool ABLK = false, bool BBLK = false>
; __device__ __forceinline__ void gemm_phase(PG8_LAS unsigned char* lds, const Gemm g, const Sched& S, const Epi& E) {
;     ...
;             PG8_LDB(B0, 1, 0); PG8_LDB(B1, 1, 1); PG8_SCHED; PG8_LDA(At, 1, 0); PG8_STAGE(PG8_SA(0, 1), a2 + hstepA, voffA);
;             PG8_WAIT_V(8); PG8_WAIT_L(0); PG8_BAR; PG8_MMA(0, 0, At, B0); PG8_MMA(0, 1, At, B1); PG8_BAR; PG8_SCHED;
;             PG8_LDA(At, 1, 1); PG8_STAGE(PG8_SB(1, 0), b3, voffB); PG8_STAGE(PG8_SB(1, 1), b3 + hstepB, voffB); PG8_STAGE(PG8_SA(1, 0), a3, voffA);
;             PG8_WAIT_V(8); PG8_WAIT_L(0); PG8_BAR; PG8_MMA(1, 0, At, B0); PG8_MMA(1, 1, At, B1); PG8_BAR; PG8_SCHED;
	s_add_i32 s68, 0, 0x18000
	v_add_u32_e32 v36, s68, v148
	s_add_i32 s69, 0, 0x1c000
	ds_read_b128 v[152:155], v36
	ds_read_b128 v[156:159], v36 offset:1024
	ds_read_b128 v[160:163], v36 offset:2048
	ds_read_b128 v[164:167], v36 offset:3072
	v_add_u32_e32 v36, s69, v148
	ds_read_b128 v[168:171], v36
	ds_read_b128 v[172:175], v36 offset:1024
	ds_read_b128 v[176:179], v36 offset:2048
	ds_read_b128 v[180:183], v36 offset:3072
	s_add_u32 s20, s20, 0x4000
	s_addc_u32 s21, s21, 0
	s_mov_b32 m0, s29
	ds_read_b128 v[184:187], v150 offset:32768
	ds_read_b128 v[188:191], v150 offset:33792
	ds_read_b128 v[192:195], v150 offset:34816
	ds_read_b128 v[196:199], v150 offset:35840
	ds_read_b128 v[200:203], v150 offset:36864
	ds_read_b128 v[204:207], v150 offset:37888
	ds_read_b128 v[208:211], v150 offset:38912
	ds_read_b128 v[212:215], v150 offset:39936
	global_load_lds_dwordx4 v136, s[20:21]
	s_mov_b32 m0, s30
	s_nop 0
	global_load_lds_dwordx4 v140, s[20:21]
	s_waitcnt vmcnt(8)
	s_waitcnt lgkmcnt(0)
	v_mfma_f32_16x16x32_bf16 v[132:135], v[152:155], v[184:187], v[132:135]
	v_mfma_f32_16x16x32_bf16 v[132:135], v[156:159], v[188:191], v[132:135]
	s_barrier
	s_setprio 1
	v_mfma_f32_16x16x32_bf16 v[128:131], v[164:167], v[188:191], v[128:131]
	v_mfma_f32_16x16x32_bf16 v[128:131], v[160:163], v[184:187], v[128:131]
	v_mfma_f32_16x16x32_bf16 v[120:123], v[160:163], v[192:195], v[120:123]
	v_mfma_f32_16x16x32_bf16 v[120:123], v[164:167], v[196:199], v[120:123]
	v_mfma_f32_16x16x32_bf16 v[124:127], v[156:159], v[196:199], v[124:127]
	v_mfma_f32_16x16x32_bf16 v[124:127], v[152:155], v[192:195], v[124:127]
	v_mfma_f32_16x16x32_bf16 v[108:111], v[152:155], v[200:203], v[108:111]
	v_mfma_f32_16x16x32_bf16 v[108:111], v[156:159], v[204:207], v[108:111]
	v_mfma_f32_16x16x32_bf16 v[104:107], v[164:167], v[204:207], v[104:107]
	v_mfma_f32_16x16x32_bf16 v[104:107], v[160:163], v[200:203], v[104:107]
	v_mfma_f32_16x16x32_bf16 v[88:91], v[160:163], v[208:211], v[88:91]
	v_mfma_f32_16x16x32_bf16 v[88:91], v[164:167], v[212:215], v[88:91]
	v_mfma_f32_16x16x32_bf16 v[92:95], v[156:159], v[212:215], v[92:95]
	v_mfma_f32_16x16x32_bf16 v[92:95], v[152:155], v[208:211], v[92:95]
	v_mfma_f32_16x16x32_bf16 v[76:79], v[168:171], v[208:211], v[76:79]
	v_mfma_f32_16x16x32_bf16 v[76:79], v[172:175], v[212:215], v[76:79]
	v_mfma_f32_16x16x32_bf16 v[116:119], v[172:175], v[188:191], v[116:119]
	v_mfma_f32_16x16x32_bf16 v[116:119], v[168:171], v[184:187], v[116:119]
	v_mfma_f32_16x16x32_bf16 v[112:115], v[176:179], v[184:187], v[112:115]
	v_mfma_f32_16x16x32_bf16 v[112:115], v[180:183], v[188:191], v[112:115]
	v_mfma_f32_16x16x32_bf16 v[96:99], v[180:183], v[196:199], v[96:99]
	v_mfma_f32_16x16x32_bf16 v[96:99], v[176:179], v[192:195], v[96:99]
	v_mfma_f32_16x16x32_bf16 v[100:103], v[168:171], v[192:195], v[100:103]
	v_mfma_f32_16x16x32_bf16 v[100:103], v[172:175], v[196:199], v[100:103]
	v_mfma_f32_16x16x32_bf16 v[84:87], v[172:175], v[204:207], v[84:87]
	v_mfma_f32_16x16x32_bf16 v[84:87], v[168:171], v[200:203], v[84:87]
	v_mfma_f32_16x16x32_bf16 v[80:83], v[176:179], v[200:203], v[80:83]
	v_mfma_f32_16x16x32_bf16 v[80:83], v[180:183], v[204:207], v[80:83]
	v_mfma_f32_16x16x32_bf16 v[72:75], v[180:183], v[212:215], v[72:75]
	v_mfma_f32_16x16x32_bf16 v[72:75], v[176:179], v[208:211], v[72:75]
	s_setprio 0
	s_barrier
	s_add_u32 s20, s18, 0x8000
	s_addc_u32 s21, s19, 0
	s_add_i32 s68, s68, s24
	s_mov_b32 m0, s68
	ds_read_b128 v[184:187], v150 offset:49152
	ds_read_b128 v[188:191], v150 offset:50176
	ds_read_b128 v[192:195], v150 offset:51200
	ds_read_b128 v[196:199], v150 offset:52224
	ds_read_b128 v[200:203], v150 offset:53248
	ds_read_b128 v[204:207], v150 offset:54272
	ds_read_b128 v[208:211], v150 offset:55296
	ds_read_b128 v[212:215], v150 offset:56320
	global_load_lds_dwordx4 v138, s[20:21]
	s_add_i32 m0, s68, 0x2000
	s_add_u32 s18, s18, 0xc000
	s_addc_u32 s19, s19, 0
	global_load_lds_dwordx4 v142, s[20:21]
	s_add_i32 s20, s69, s24
	s_mov_b32 m0, s20
	s_nop 0
	global_load_lds_dwordx4 v138, s[18:19]
	s_add_i32 m0, s20, 0x2000
	s_nop 0
	global_load_lds_dwordx4 v142, s[18:19]
	s_mov_b32 m0, s35
	s_nop 0
	global_load_lds_dwordx4 v136, s[16:17]
	s_mov_b32 m0, s70
	s_nop 0
	global_load_lds_dwordx4 v140, s[16:17]
	s_waitcnt vmcnt(8)
	s_waitcnt lgkmcnt(0)
	v_mfma_f32_16x16x32_bf16 v[68:71], v[152:155], v[184:187], v[68:71]
	v_mfma_f32_16x16x32_bf16 v[68:71], v[156:159], v[188:191], v[68:71]
	s_barrier
	s_setprio 1
	v_mfma_f32_16x16x32_bf16 v[64:67], v[164:167], v[188:191], v[64:67]
	v_mfma_f32_16x16x32_bf16 v[64:67], v[160:163], v[184:187], v[64:67]
	v_mfma_f32_16x16x32_bf16 v[56:59], v[160:163], v[192:195], v[56:59]
	v_mfma_f32_16x16x32_bf16 v[56:59], v[164:167], v[196:199], v[56:59]
	v_mfma_f32_16x16x32_bf16 v[60:63], v[156:159], v[196:199], v[60:63]
	v_mfma_f32_16x16x32_bf16 v[60:63], v[152:155], v[192:195], v[60:63]
	v_mfma_f32_16x16x32_bf16 v[44:47], v[152:155], v[200:203], v[44:47]
	v_mfma_f32_16x16x32_bf16 v[44:47], v[156:159], v[204:207], v[44:47]
	v_mfma_f32_16x16x32_bf16 v[40:43], v[164:167], v[204:207], v[40:43]
	v_mfma_f32_16x16x32_bf16 v[40:43], v[160:163], v[200:203], v[40:43]
	v_mfma_f32_16x16x32_bf16 v[20:23], v[160:163], v[208:211], v[20:23]
	v_mfma_f32_16x16x32_bf16 v[20:23], v[164:167], v[212:215], v[20:23]
	v_mfma_f32_16x16x32_bf16 v[24:27], v[156:159], v[212:215], v[24:27]
	v_mfma_f32_16x16x32_bf16 v[24:27], v[152:155], v[208:211], v[24:27]
	v_mfma_f32_16x16x32_bf16 v[8:11], v[168:171], v[208:211], v[8:11]
	v_mfma_f32_16x16x32_bf16 v[8:11], v[172:175], v[212:215], v[8:11]
	v_mfma_f32_16x16x32_bf16 v[52:55], v[172:175], v[188:191], v[52:55]
	v_mfma_f32_16x16x32_bf16 v[52:55], v[168:171], v[184:187], v[52:55]
	v_mfma_f32_16x16x32_bf16 v[48:51], v[176:179], v[184:187], v[48:51]
	v_mfma_f32_16x16x32_bf16 v[48:51], v[180:183], v[188:191], v[48:51]
	v_mfma_f32_16x16x32_bf16 v[28:31], v[180:183], v[196:199], v[28:31]
	v_mfma_f32_16x16x32_bf16 v[28:31], v[176:179], v[192:195], v[28:31]
	v_mfma_f32_16x16x32_bf16 v[32:35], v[168:171], v[192:195], v[32:35]
	v_mfma_f32_16x16x32_bf16 v[32:35], v[172:175], v[196:199], v[32:35]
	v_mfma_f32_16x16x32_bf16 v[16:19], v[172:175], v[204:207], v[16:19]
	v_mfma_f32_16x16x32_bf16 v[16:19], v[168:171], v[200:203], v[16:19]
	v_mfma_f32_16x16x32_bf16 v[12:15], v[176:179], v[200:203], v[12:15]
	v_mfma_f32_16x16x32_bf16 v[12:15], v[180:183], v[204:207], v[12:15]
	v_mfma_f32_16x16x32_bf16 v[4:7], v[180:183], v[212:215], v[4:7]
	v_mfma_f32_16x16x32_bf16 v[4:7], v[176:179], v[208:211], v[4:7]
	s_setprio 0
	s_barrier
	s_add_i32 s13, s13, 2
	s_add_u32 s10, s10, 0x10000
	s_addc_u32 s11, s11, 0
	s_add_u32 vcc_lo, vcc_lo, 0x10000
	s_addc_u32 vcc_hi, vcc_hi, 0
	s_cmpk_gt_u32 s13, 0x55
; #define PG8_STAGE(bufoff, gbase, voff) do { _Pragma("unroll") for (int _i = 0; _i < 2; ++_i) \
;         __builtin_amdgcn_global_load_lds((const unsigned*)((const char*)(gbase) + (voff)[_i]), (PG8_LAS unsigned*)(lds + (bufoff) + ldsw + _i * 8192), 16, 0, 0); } while (0)
; #define PG8_LDA(dst, b, h) do { _Pragma("unroll") for (int m = 0; m < 4; ++m) _Pragma("unroll") for (int k = 0; k < 2; ++k) dst[m][k] = *(const PG8_LAS bf16x8*)(lds + PG8_SA(b, h) + aoff + m * 2048 + k * 1024); } while (0)
; #define PG8_LDB(dst, b, h) do { _Pragma("unroll") for (int n = 0; n < 2; ++n) _Pragma("unroll") for (int k = 0; k < 2; ++k) dst[n][k] = *(const PG8_LAS bf16x8*)(lds + PG8_SB(b, h) + boff + n * 2048 + k * 1024); } while (0)
; #define PG8_MMA(ai, bj, At, Bt) do { __builtin_amdgcn_s_setprio(1); _Pragma("unroll") for (int m = 0; m < 4; ++m) _Pragma("unroll") for (int n = 0; n < 2; ++n) _Pragma("unroll") for (int k = 0; k < 2; ++k) \
;         acc[ai][bj][m][n] = __builtin_amdgcn_mfma_f32_16x16x32_bf16(Bt[n][k], At[m][k], acc[ai][bj][m][n], 0, 0, 0); __builtin_amdgcn_s_setprio(0); } while (0)
; #define PG8_WAIT_V(n) asm volatile("s_waitcnt vmcnt(" #n ")" ::: "memory")
; template <class Epi, class Sched, bool ALIGN_EPI = false, bool SP2 = false, bool ABLK = false, bool BBLK = false>
; __device__ __forceinline__ void gemm_phase(PG8_LAS unsigned char* lds, const Gemm g, const Sched& S, const Epi& E) {
;     ...
;         for (int t = 0; t < nt; t += 2) {
;             const bool last = (t == nt - 2);
;             const char* a1 = cA + (size_t)(t + 1) * kstepA;
;             const char* a2 = last ? nA : cA + (size_t)(t + 2) * kstepA; const char* b2 = last ? nB : cB + (size_t)(t + 2) * kstepB;
;             const char* a3 = a2 + kstepA; const char* b3 = b2 + kstepB;
;             if (last && has_next) S.a_ready(nxt);
;             if constexpr (SP2) {
;             PG8_LDB(B0, 0, 0); PG8_LDB(B1, 0, 1); PG8_SCHED; PG8_LDA(At, 0, 0); PG8_STAGE(PG8_SA(1, 1), a1 + hstepA, voffA);
;             PG8_WAIT_V(8); PG8_WAIT_L(0); PG8_BAR; PG8_MMA(0, 0, At, B0); PG8_MMA(0, 1, At, B1); PG8_BAR; PG8_SCHED;
;             PG8_LDA(At, 0, 1); PG8_STAGE(PG8_SB(0, 0), b2, voffB); PG8_STAGE(PG8_SB(0, 1), b2 + hstepB, voffB); PG8_STAGE(PG8_SA(0, 0), a2, voffA);
;             PG8_WAIT_V(8); PG8_WAIT_L(0); PG8_BAR; PG8_MMA(1, 0, At, B0); PG8_MMA(1, 1, At, B1); PG8_BAR; PG8_SCHED;
.LBB0_439:
	s_add_u32 s16, s10, 0x4000
	s_addc_u32 s17, s11, 0
	s_cmpk_eq_i32 s13, 0x54
	s_cselect_b32 s20, s0, s16
	s_cselect_b32 s21, s1, s17
	s_cselect_b32 s18, s8, vcc_lo
	s_cselect_b32 s19, s9, vcc_hi
	s_add_u32 s16, s20, 0x8000
	s_addc_u32 s17, s21, 0
	s_add_i32 s68, 0, 0x10000
	v_add_u32_e32 v36, s68, v148
	s_add_i32 s88, 0, 0x14000
	ds_read_b128 v[152:155], v36
	ds_read_b128 v[156:159], v36 offset:1024
	ds_read_b128 v[160:163], v36 offset:2048
	ds_read_b128 v[164:167], v36 offset:3072
	v_add_u32_e32 v36, s88, v148
	ds_read_b128 v[168:171], v36
	ds_read_b128 v[172:175], v36 offset:1024
	ds_read_b128 v[176:179], v36 offset:2048
	ds_read_b128 v[180:183], v36 offset:3072
	s_add_i32 m0, s27, 0xc000
	ds_read_b128 v[184:187], v150
	ds_read_b128 v[188:191], v150 offset:1024
	ds_read_b128 v[192:195], v150 offset:2048
	ds_read_b128 v[196:199], v150 offset:3072
	ds_read_b128 v[200:203], v150 offset:4096
	ds_read_b128 v[204:207], v150 offset:5120
	ds_read_b128 v[208:211], v150 offset:6144
	ds_read_b128 v[212:215], v150 offset:7168
	global_load_lds_dwordx4 v144, s[10:11]
	s_add_i32 m0, s27, 0xe000
	s_nop 0
	global_load_lds_dwordx4 v146, s[10:11]
	s_waitcnt vmcnt(8)
	s_waitcnt lgkmcnt(0)
	v_mfma_f32_16x16x32_bf16 v[132:135], v[152:155], v[184:187], v[132:135]
	v_mfma_f32_16x16x32_bf16 v[132:135], v[156:159], v[188:191], v[132:135]
	s_barrier
	s_setprio 1
	v_mfma_f32_16x16x32_bf16 v[128:131], v[164:167], v[188:191], v[128:131]
	v_mfma_f32_16x16x32_bf16 v[128:131], v[160:163], v[184:187], v[128:131]
	v_mfma_f32_16x16x32_bf16 v[120:123], v[160:163], v[192:195], v[120:123]
	v_mfma_f32_16x16x32_bf16 v[120:123], v[164:167], v[196:199], v[120:123]
	v_mfma_f32_16x16x32_bf16 v[124:127], v[156:159], v[196:199], v[124:127]
	v_mfma_f32_16x16x32_bf16 v[124:127], v[152:155], v[192:195], v[124:127]
	v_mfma_f32_16x16x32_bf16 v[108:111], v[152:155], v[200:203], v[108:111]
	v_mfma_f32_16x16x32_bf16 v[108:111], v[156:159], v[204:207], v[108:111]
	v_mfma_f32_16x16x32_bf16 v[104:107], v[164:167], v[204:207], v[104:107]
	v_mfma_f32_16x16x32_bf16 v[104:107], v[160:163], v[200:203], v[104:107]
	v_mfma_f32_16x16x32_bf16 v[88:91], v[160:163], v[208:211], v[88:91]
	v_mfma_f32_16x16x32_bf16 v[88:91], v[164:167], v[212:215], v[88:91]
	v_mfma_f32_16x16x32_bf16 v[92:95], v[156:159], v[212:215], v[92:95]
	v_mfma_f32_16x16x32_bf16 v[92:95], v[152:155], v[208:211], v[92:95]
	v_mfma_f32_16x16x32_bf16 v[76:79], v[168:171], v[208:211], v[76:79]
	v_mfma_f32_16x16x32_bf16 v[76:79], v[172:175], v[212:215], v[76:79]
	v_mfma_f32_16x16x32_bf16 v[116:119], v[172:175], v[188:191], v[116:119]
	v_mfma_f32_16x16x32_bf16 v[116:119], v[168:171], v[184:187], v[116:119]
	v_mfma_f32_16x16x32_bf16 v[112:115], v[176:179], v[184:187], v[112:115]
	v_mfma_f32_16x16x32_bf16 v[112:115], v[180:183], v[188:191], v[112:115]
	v_mfma_f32_16x16x32_bf16 v[96:99], v[180:183], v[196:199], v[96:99]
	v_mfma_f32_16x16x32_bf16 v[96:99], v[176:179], v[192:195], v[96:99]
	v_mfma_f32_16x16x32_bf16 v[100:103], v[168:171], v[192:195], v[100:103]
	v_mfma_f32_16x16x32_bf16 v[100:103], v[172:175], v[196:199], v[100:103]
	v_mfma_f32_16x16x32_bf16 v[84:87], v[172:175], v[204:207], v[84:87]
	v_mfma_f32_16x16x32_bf16 v[84:87], v[168:171], v[200:203], v[84:87]
	v_mfma_f32_16x16x32_bf16 v[80:83], v[176:179], v[200:203], v[80:83]
	v_mfma_f32_16x16x32_bf16 v[80:83], v[180:183], v[204:207], v[80:83]
	v_mfma_f32_16x16x32_bf16 v[72:75], v[180:183], v[212:215], v[72:75]
	v_mfma_f32_16x16x32_bf16 v[72:75], v[176:179], v[208:211], v[72:75]
	s_setprio 0
	s_barrier
	s_add_i32 s68, s68, s24
	s_mov_b32 m0, s68
	ds_read_b128 v[184:187], v150 offset:16384
	ds_read_b128 v[188:191], v150 offset:17408
	ds_read_b128 v[192:195], v150 offset:18432
	ds_read_b128 v[196:199], v150 offset:19456
	ds_read_b128 v[200:203], v150 offset:20480
	ds_read_b128 v[204:207], v150 offset:21504
	ds_read_b128 v[208:211], v150 offset:22528
	ds_read_b128 v[212:215], v150 offset:23552
	global_load_lds_dwordx4 v138, s[18:19]
	s_add_i32 m0, s68, 0x2000
	s_add_u32 s68, s18, 0x4000
	s_addc_u32 s69, s19, 0
	s_add_i32 s88, s88, s24
	global_load_lds_dwordx4 v142, s[18:19]
	s_mov_b32 m0, s88
	s_nop 0
	global_load_lds_dwordx4 v138, s[68:69]
	s_add_i32 m0, s88, 0x2000
	s_nop 0
	global_load_lds_dwordx4 v142, s[68:69]
	s_mov_b32 m0, s27
	s_nop 0
	global_load_lds_dwordx4 v136, s[20:21]
	s_mov_b32 m0, s28
	s_nop 0
	global_load_lds_dwordx4 v140, s[20:21]
	s_waitcnt vmcnt(8)
	s_waitcnt lgkmcnt(0)
	v_mfma_f32_16x16x32_bf16 v[68:71], v[152:155], v[184:187], v[68:71]
	v_mfma_f32_16x16x32_bf16 v[68:71], v[156:159], v[188:191], v[68:71]
	s_barrier
	s_setprio 1
	v_mfma_f32_16x16x32_bf16 v[64:67], v[164:167], v[188:191], v[64:67]
	v_mfma_f32_16x16x32_bf16 v[64:67], v[160:163], v[184:187], v[64:67]
	v_mfma_f32_16x16x32_bf16 v[56:59], v[160:163], v[192:195], v[56:59]
	v_mfma_f32_16x16x32_bf16 v[56:59], v[164:167], v[196:199], v[56:59]
	v_mfma_f32_16x16x32_bf16 v[60:63], v[156:159], v[196:199], v[60:63]
	v_mfma_f32_16x16x32_bf16 v[60:63], v[152:155], v[192:195], v[60:63]
	v_mfma_f32_16x16x32_bf16 v[44:47], v[152:155], v[200:203], v[44:47]
	v_mfma_f32_16x16x32_bf16 v[44:47], v[156:159], v[204:207], v[44:47]
	v_mfma_f32_16x16x32_bf16 v[40:43], v[164:167], v[204:207], v[40:43]
	v_mfma_f32_16x16x32_bf16 v[40:43], v[160:163], v[200:203], v[40:43]
	v_mfma_f32_16x16x32_bf16 v[20:23], v[160:163], v[208:211], v[20:23]
	v_mfma_f32_16x16x32_bf16 v[20:23], v[164:167], v[212:215], v[20:23]
	v_mfma_f32_16x16x32_bf16 v[24:27], v[156:159], v[212:215], v[24:27]
	v_mfma_f32_16x16x32_bf16 v[24:27], v[152:155], v[208:211], v[24:27]
	v_mfma_f32_16x16x32_bf16 v[8:11], v[168:171], v[208:211], v[8:11]
	v_mfma_f32_16x16x32_bf16 v[8:11], v[172:175], v[212:215], v[8:11]
	v_mfma_f32_16x16x32_bf16 v[52:55], v[172:175], v[188:191], v[52:55]
	v_mfma_f32_16x16x32_bf16 v[52:55], v[168:171], v[184:187], v[52:55]
	v_mfma_f32_16x16x32_bf16 v[48:51], v[176:179], v[184:187], v[48:51]
	v_mfma_f32_16x16x32_bf16 v[48:51], v[180:183], v[188:191], v[48:51]
	v_mfma_f32_16x16x32_bf16 v[28:31], v[180:183], v[196:199], v[28:31]
	v_mfma_f32_16x16x32_bf16 v[28:31], v[176:179], v[192:195], v[28:31]
	v_mfma_f32_16x16x32_bf16 v[32:35], v[168:171], v[192:195], v[32:35]
	v_mfma_f32_16x16x32_bf16 v[32:35], v[172:175], v[196:199], v[32:35]
	v_mfma_f32_16x16x32_bf16 v[16:19], v[172:175], v[204:207], v[16:19]
	v_mfma_f32_16x16x32_bf16 v[16:19], v[168:171], v[200:203], v[16:19]
	v_mfma_f32_16x16x32_bf16 v[12:15], v[176:179], v[200:203], v[12:15]
	v_mfma_f32_16x16x32_bf16 v[12:15], v[180:183], v[204:207], v[12:15]
	v_mfma_f32_16x16x32_bf16 v[4:7], v[180:183], v[212:215], v[4:7]
	v_mfma_f32_16x16x32_bf16 v[4:7], v[176:179], v[208:211], v[4:7]
	s_setprio 0
	s_barrier
; #define PG8_STAGE(bufoff, gbase, voff) do { _Pragma("unroll") for (int _i = 0; _i < 2; ++_i) \
;         __builtin_amdgcn_global_load_lds((const unsigned*)((const char*)(gbase) + (voff)[_i]), (PG8_LAS unsigned*)(lds + (bufoff) + ldsw + _i * 8192), 16, 0, 0); } while (0)
; #define PG8_LDA(dst, b, h) do { _Pragma("unroll") for (int m = 0; m < 4; ++m) _Pragma("unroll") for (int k = 0; k < 2; ++k) dst[m][k] = *(const PG8_LAS bf16x8*)(lds + PG8_SA(b, h) + aoff + m * 2048 + k * 1024); } while (0)
; #define PG8_LDB(dst, b, h) do { _Pragma("unroll") for (int n = 0; n < 2; ++n) _Pragma("unroll") for (int k = 0; k < 2; ++k) dst[n][k] = *(const PG8_LAS bf16x8*)(lds + PG8_SB(b, h) + boff + n * 2048 + k * 1024); } while (0)
; #define PG8_MMA(ai, bj, At, Bt) do { __builtin_amdgcn_s_setprio(1); _Pragma("unroll") for (int m = 0; m < 4; ++m) _Pragma("unroll") for (int n = 0; n < 2; ++n) _Pragma("unroll") for (int k = 0; k < 2; ++k) \
;         acc[ai][bj][m][n] = __builtin_amdgcn_mfma_f32_16x16x32_bf16(Bt[n][k], At[m][k], acc[ai][bj][m][n], 0, 0, 0); __builtin_amdgcn_s_setprio(0); } while (0)
; #define PG8_WAIT_V(n) asm volatile("s_waitcnt vmcnt(" #n ")" ::: "memory")
; #define PG8_WAIT_L(n) asm volatile("s_waitcnt lgkmcnt(" #n ")" ::: "memory")
; #define PG8_BAR __builtin_amdgcn_s_barrier()
; #define PG8_SCHED __builtin_amdgcn_sched_barrier(0)
; template <class Epi, class Sched, bool ALIGN_EPI = false, bool SP2 = false, bool ABLK = false, bool BBLK = false>
; __device__ __forceinline__ void gemm_phase(PG8_LAS unsigned char* lds, const Gemm g, const Sched& S, const Epi& E) {
;     ...
;             PG8_LDB(B0, 1, 0); PG8_LDB(B1, 1, 1); PG8_SCHED; PG8_LDA(At, 1, 0); PG8_STAGE(PG8_SA(0, 1), a2 + hstepA, voffA);
;             PG8_WAIT_V(8); PG8_WAIT_L(0); PG8_BAR; PG8_MMA(0, 0, At, B0); PG8_MMA(0, 1, At, B1); PG8_BAR; PG8_SCHED;
;             PG8_LDA(At, 1, 1); PG8_STAGE(PG8_SB(1, 0), b3, voffB); PG8_STAGE(PG8_SB(1, 1), b3 + hstepB, voffB); PG8_STAGE(PG8_SA(1, 0), a3, voffA);
;             PG8_WAIT_V(8); PG8_WAIT_L(0); PG8_BAR; PG8_MMA(1, 0, At, B0); PG8_MMA(1, 1, At, B1); PG8_BAR; PG8_SCHED;
;     ...
;         if constexpr (ALIGN_EPI) { if (wr == 0) PG8_BAR; }
	s_add_i32 s68, 0, 0x18000
	v_add_u32_e32 v36, s68, v148
	s_add_i32 s69, 0, 0x1c000
	ds_read_b128 v[152:155], v36
	ds_read_b128 v[156:159], v36 offset:1024
	ds_read_b128 v[160:163], v36 offset:2048
	ds_read_b128 v[164:167], v36 offset:3072
	v_add_u32_e32 v36, s69, v148
	ds_read_b128 v[168:171], v36
	ds_read_b128 v[172:175], v36 offset:1024
	ds_read_b128 v[176:179], v36 offset:2048
	ds_read_b128 v[180:183], v36 offset:3072
	s_add_u32 s20, s20, 0x4000
	s_addc_u32 s21, s21, 0
	s_mov_b32 m0, s29
	ds_read_b128 v[184:187], v150 offset:32768
	ds_read_b128 v[188:191], v150 offset:33792
	ds_read_b128 v[192:195], v150 offset:34816
	ds_read_b128 v[196:199], v150 offset:35840
	ds_read_b128 v[200:203], v150 offset:36864
	ds_read_b128 v[204:207], v150 offset:37888
	ds_read_b128 v[208:211], v150 offset:38912
	ds_read_b128 v[212:215], v150 offset:39936
	global_load_lds_dwordx4 v136, s[20:21]
	s_mov_b32 m0, s30
	s_nop 0
	global_load_lds_dwordx4 v140, s[20:21]
	s_waitcnt vmcnt(8)
	s_waitcnt lgkmcnt(0)
	v_mfma_f32_16x16x32_bf16 v[132:135], v[152:155], v[184:187], v[132:135]
	v_mfma_f32_16x16x32_bf16 v[132:135], v[156:159], v[188:191], v[132:135]
	s_barrier
	s_setprio 1
	v_mfma_f32_16x16x32_bf16 v[128:131], v[164:167], v[188:191], v[128:131]
	v_mfma_f32_16x16x32_bf16 v[128:131], v[160:163], v[184:187], v[128:131]
	v_mfma_f32_16x16x32_bf16 v[120:123], v[160:163], v[192:195], v[120:123]
	v_mfma_f32_16x16x32_bf16 v[120:123], v[164:167], v[196:199], v[120:123]
	v_mfma_f32_16x16x32_bf16 v[124:127], v[156:159], v[196:199], v[124:127]
	v_mfma_f32_16x16x32_bf16 v[124:127], v[152:155], v[192:195], v[124:127]
	v_mfma_f32_16x16x32_bf16 v[108:111], v[152:155], v[200:203], v[108:111]
	v_mfma_f32_16x16x32_bf16 v[108:111], v[156:159], v[204:207], v[108:111]
	v_mfma_f32_16x16x32_bf16 v[104:107], v[164:167], v[204:207], v[104:107]
	v_mfma_f32_16x16x32_bf16 v[104:107], v[160:163], v[200:203], v[104:107]
	v_mfma_f32_16x16x32_bf16 v[88:91], v[160:163], v[208:211], v[88:91]
	v_mfma_f32_16x16x32_bf16 v[88:91], v[164:167], v[212:215], v[88:91]
	v_mfma_f32_16x16x32_bf16 v[92:95], v[156:159], v[212:215], v[92:95]
	v_mfma_f32_16x16x32_bf16 v[92:95], v[152:155], v[208:211], v[92:95]
	v_mfma_f32_16x16x32_bf16 v[76:79], v[168:171], v[208:211], v[76:79]
	v_mfma_f32_16x16x32_bf16 v[76:79], v[172:175], v[212:215], v[76:79]
	v_mfma_f32_16x16x32_bf16 v[116:119], v[172:175], v[188:191], v[116:119]
	v_mfma_f32_16x16x32_bf16 v[116:119], v[168:171], v[184:187], v[116:119]
	v_mfma_f32_16x16x32_bf16 v[112:115], v[176:179], v[184:187], v[112:115]
	v_mfma_f32_16x16x32_bf16 v[112:115], v[180:183], v[188:191], v[112:115]
	v_mfma_f32_16x16x32_bf16 v[96:99], v[180:183], v[196:199], v[96:99]
	v_mfma_f32_16x16x32_bf16 v[96:99], v[176:179], v[192:195], v[96:99]
	v_mfma_f32_16x16x32_bf16 v[100:103], v[168:171], v[192:195], v[100:103]
	v_mfma_f32_16x16x32_bf16 v[100:103], v[172:175], v[196:199], v[100:103]
	v_mfma_f32_16x16x32_bf16 v[84:87], v[172:175], v[204:207], v[84:87]
	v_mfma_f32_16x16x32_bf16 v[84:87], v[168:171], v[200:203], v[84:87]
	v_mfma_f32_16x16x32_bf16 v[80:83], v[176:179], v[200:203], v[80:83]
	v_mfma_f32_16x16x32_bf16 v[80:83], v[180:183], v[204:207], v[80:83]
	v_mfma_f32_16x16x32_bf16 v[72:75], v[180:183], v[212:215], v[72:75]
	v_mfma_f32_16x16x32_bf16 v[72:75], v[176:179], v[208:211], v[72:75]
	s_setprio 0
	s_barrier
	s_add_u32 s20, s18, 0x8000
	s_addc_u32 s21, s19, 0
	s_add_i32 s68, s68, s24
	s_mov_b32 m0, s68
	ds_read_b128 v[184:187], v150 offset:49152
	ds_read_b128 v[188:191], v150 offset:50176
	ds_read_b128 v[192:195], v150 offset:51200
	ds_read_b128 v[196:199], v150 offset:52224
	ds_read_b128 v[200:203], v150 offset:53248
	ds_read_b128 v[204:207], v150 offset:54272
	ds_read_b128 v[208:211], v150 offset:55296
	ds_read_b128 v[212:215], v150 offset:56320
	global_load_lds_dwordx4 v138, s[20:21]
	s_add_i32 m0, s68, 0x2000
	s_add_u32 s18, s18, 0xc000
	s_addc_u32 s19, s19, 0
	global_load_lds_dwordx4 v142, s[20:21]
	s_add_i32 s20, s69, s24
	s_mov_b32 m0, s20
	s_nop 0
	global_load_lds_dwordx4 v138, s[18:19]
	s_add_i32 m0, s20, 0x2000
	s_nop 0
	global_load_lds_dwordx4 v142, s[18:19]
	s_mov_b32 m0, s35
	s_nop 0
	global_load_lds_dwordx4 v136, s[16:17]
	s_mov_b32 m0, s70
	s_nop 0
	global_load_lds_dwordx4 v140, s[16:17]
	s_waitcnt vmcnt(8)
	s_waitcnt lgkmcnt(0)
	v_mfma_f32_16x16x32_bf16 v[68:71], v[152:155], v[184:187], v[68:71]
	v_mfma_f32_16x16x32_bf16 v[68:71], v[156:159], v[188:191], v[68:71]
	s_barrier
	s_setprio 1
	v_mfma_f32_16x16x32_bf16 v[64:67], v[164:167], v[188:191], v[64:67]
	v_mfma_f32_16x16x32_bf16 v[64:67], v[160:163], v[184:187], v[64:67]
	v_mfma_f32_16x16x32_bf16 v[56:59], v[160:163], v[192:195], v[56:59]
	v_mfma_f32_16x16x32_bf16 v[56:59], v[164:167], v[196:199], v[56:59]
	v_mfma_f32_16x16x32_bf16 v[60:63], v[156:159], v[196:199], v[60:63]
	v_mfma_f32_16x16x32_bf16 v[60:63], v[152:155], v[192:195], v[60:63]
	v_mfma_f32_16x16x32_bf16 v[44:47], v[152:155], v[200:203], v[44:47]
	v_mfma_f32_16x16x32_bf16 v[44:47], v[156:159], v[204:207], v[44:47]
	v_mfma_f32_16x16x32_bf16 v[40:43], v[164:167], v[204:207], v[40:43]
	v_mfma_f32_16x16x32_bf16 v[40:43], v[160:163], v[200:203], v[40:43]
	v_mfma_f32_16x16x32_bf16 v[20:23], v[160:163], v[208:211], v[20:23]
	v_mfma_f32_16x16x32_bf16 v[20:23], v[164:167], v[212:215], v[20:23]
	v_mfma_f32_16x16x32_bf16 v[24:27], v[156:159], v[212:215], v[24:27]
	v_mfma_f32_16x16x32_bf16 v[24:27], v[152:155], v[208:211], v[24:27]
	v_mfma_f32_16x16x32_bf16 v[8:11], v[168:171], v[208:211], v[8:11]
	v_mfma_f32_16x16x32_bf16 v[8:11], v[172:175], v[212:215], v[8:11]
	v_mfma_f32_16x16x32_bf16 v[52:55], v[172:175], v[188:191], v[52:55]
	v_mfma_f32_16x16x32_bf16 v[52:55], v[168:171], v[184:187], v[52:55]
	v_mfma_f32_16x16x32_bf16 v[48:51], v[176:179], v[184:187], v[48:51]
	v_mfma_f32_16x16x32_bf16 v[48:51], v[180:183], v[188:191], v[48:51]
	v_mfma_f32_16x16x32_bf16 v[28:31], v[180:183], v[196:199], v[28:31]
	v_mfma_f32_16x16x32_bf16 v[28:31], v[176:179], v[192:195], v[28:31]
	v_mfma_f32_16x16x32_bf16 v[32:35], v[168:171], v[192:195], v[32:35]
	v_mfma_f32_16x16x32_bf16 v[32:35], v[172:175], v[196:199], v[32:35]
	v_mfma_f32_16x16x32_bf16 v[16:19], v[172:175], v[204:207], v[16:19]
	v_mfma_f32_16x16x32_bf16 v[16:19], v[168:171], v[200:203], v[16:19]
	v_mfma_f32_16x16x32_bf16 v[12:15], v[176:179], v[200:203], v[12:15]
	v_mfma_f32_16x16x32_bf16 v[12:15], v[180:183], v[204:207], v[12:15]
	v_mfma_f32_16x16x32_bf16 v[4:7], v[180:183], v[212:215], v[4:7]
	v_mfma_f32_16x16x32_bf16 v[4:7], v[176:179], v[208:211], v[4:7]
	s_setprio 0
	s_barrier
	s_add_i32 s13, s13, 2
	s_add_u32 s10, s10, 0x10000
	s_addc_u32 s11, s11, 0
	s_add_u32 vcc_lo, vcc_lo, 0x10000
	s_addc_u32 vcc_hi, vcc_hi, 0
	s_cmpk_gt_u32 s13, 0x55
	s_cbranch_scc0 .LBB0_439
	s_and_b64 vcc, exec, s[6:7]
	s_cbranch_vccz .LBB0_442
	s_barrier

; #define PG8_LAS __attribute__((address_space(3)))
; #define PG8_STAGE(bufoff, gbase, voff) do { _Pragma("unroll") for (int _i = 0; _i < 2; ++_i) \
;         __builtin_amdgcn_global_load_lds((const unsigned*)((const char*)(gbase) + (voff)[_i]), (PG8_LAS unsigned*)(lds + (bufoff) + ldsw + _i * 8192), 16, 0, 0); } while (0)
; #define PG8_WAIT_V(n) asm volatile("s_waitcnt vmcnt(" #n ")" ::: "memory")
; #define PG8_BAR __builtin_amdgcn_s_barrier()
;     __device__ __forceinline__ void stage(const Unit& u, PG8_LAS unsigned char* area, int wr, int lane) const {
;         const float* src = rs + u.pm * BM + wr * 64 + lane;
;         __builtin_amdgcn_global_load_lds((const unsigned*)src, (PG8_LAS unsigned*)area, 4, 0, 0);
;         __builtin_amdgcn_global_load_lds((const unsigned*)(src + HALF), (PG8_LAS unsigned*)(area + 256), 4, 0, 0);
;     }
; template <class Epi, class Sched, bool ALIGN_EPI = false, bool SP2 = false, bool ABLK = false, bool BBLK = false>
; __device__ __forceinline__ void gemm_phase(PG8_LAS unsigned char* lds, const Gemm g, const Sched& S, const Epi& E) {
;     ...
;         const bool has_next = S.next(ui + 1, nxt);
;         PG8_LAS unsigned char* const rs_area = lds + STAGE_BYTES + wid * 512;
;         E.stage(cur, rs_area, wr, lane);
;         const char* nA = has_next ? (const char*)g.A + (size_t)nxt.pm * tstep : cA; const char* nB = has_next ? (const char*)g.Bt + (size_t)nxt.pn * tstep : cB;
;         for (int t = 0; t < nt; t += 2) {
;             const bool last = (t == nt - 2);
;             const char* a1 = cA + (size_t)(t + 1) * kstepA;
;             const char* a2 = last ? nA : cA + (size_t)(t + 2) * kstepA; const char* b2 = last ? nB : cB + (size_t)(t + 2) * kstepB;
;             const char* a3 = a2 + kstepA; const char* b3 = b2 + kstepB;
;             if (last && has_next) S.a_ready(nxt);
;             if constexpr (SP2) {
;             PG8_LDB(B0, 0, 0); PG8_LDB(B1, 0, 1); PG8_SCHED; PG8_LDA(At, 0, 0); PG8_STAGE(PG8_SA(1, 1), a1 + hstepA, voffA);
;             PG8_WAIT_V(8); PG8_WAIT_L(0); PG8_BAR; PG8_MMA(0, 0, At, B0); PG8_MMA(0, 1, At, B1); PG8_BAR; PG8_SCHED;
;             PG8_LDA(At, 0, 1); PG8_STAGE(PG8_SB(0, 0), b2, voffB); PG8_STAGE(PG8_SB(0, 1), b2 + hstepB, voffB); PG8_STAGE(PG8_SA(0, 0), a2, voffA);
;             PG8_WAIT_V(8); PG8_WAIT_L(0); PG8_BAR; PG8_MMA(1, 0, At, B0); PG8_MMA(1, 1, At, B1); PG8_BAR; PG8_SCHED;
.LBB0_915:
	s_lshl_b32 s18, s0, 8
	s_ashr_i32 s19, s18, 31
	s_mov_b32 m0, s63
	v_lshl_add_u64 v[4:5], s[18:19], 2, v[144:145]
	v_lshl_add_u64 v[6:7], v[4:5], 0, s[90:91]
	global_load_lds_dword v[4:5], off
	s_add_i32 m0, s63, 0x100
	s_mov_b32 s0, s1
	global_load_lds_dword v[6:7], off
	s_ashr_i32 s1, s1, 31
	s_lshl_b64 s[10:11], s[0:1], 20
	v_readlane_b32 s16, v252, 27
	v_readlane_b32 s17, v252, 28
	s_add_u32 s10, s16, s10
	s_addc_u32 s11, s17, s11
	s_and_b64 s[16:17], s[2:3], exec
	s_cselect_b32 s1, s11, s21
	s_cselect_b32 s19, s10, s20
	s_ashr_i32 s9, s8, 31
	s_lshl_b64 s[16:17], s[8:9], 20
	v_readlane_b32 s24, v254, 5
	v_readlane_b32 s25, v254, 6
	s_add_u32 s16, s24, s16
	s_addc_u32 s17, s25, s17
	s_and_b64 s[24:25], s[2:3], exec
	s_cselect_b32 s9, s17, s23
	s_cselect_b32 s65, s16, s22
	s_add_u32 s20, s20, 0xc000
	s_addc_u32 s21, s21, 0
	s_add_u32 s70, s22, 0x10000
	s_addc_u32 s71, s23, 0
	s_mov_b32 s13, -2
	s_add_u32 s22, s20, 0x4000
	s_addc_u32 s23, s21, 0
	s_cmp_eq_u32 s13, 28
	s_cselect_b32 s26, s19, s22
	s_cselect_b32 s27, s1, s23
	s_cselect_b32 s24, s65, s70
	s_cselect_b32 s25, s9, s71
	s_add_u32 s22, s26, 0x8000
	s_addc_u32 s23, s27, 0
	s_add_i32 s68, 0, 0x10000
	v_add_u32_e32 v36, s68, v155
	s_add_i32 s77, 0, 0x14000
	ds_read_b128 v[150:153], v36
	ds_read_b128 v[158:161], v36 offset:1024
	ds_read_b128 v[162:165], v36 offset:2048
	ds_read_b128 v[166:169], v36 offset:3072
	v_add_u32_e32 v36, s77, v155
	ds_read_b128 v[170:173], v36
	ds_read_b128 v[174:177], v36 offset:1024
	ds_read_b128 v[178:181], v36 offset:2048
	ds_read_b128 v[182:185], v36 offset:3072
	s_add_i32 m0, s31, 0xc000
	ds_read_b128 v[186:189], v157
	ds_read_b128 v[190:193], v157 offset:1024
	ds_read_b128 v[194:197], v157 offset:2048
	ds_read_b128 v[198:201], v157 offset:3072
	ds_read_b128 v[202:205], v157 offset:4096
	ds_read_b128 v[206:209], v157 offset:5120
	ds_read_b128 v[210:213], v157 offset:6144
	ds_read_b128 v[214:217], v157 offset:7168
	global_load_lds_dwordx4 v146, s[20:21]
	s_add_i32 m0, s31, 0xe000
	s_nop 0
	global_load_lds_dwordx4 v148, s[20:21]
	s_waitcnt vmcnt(8)
	s_waitcnt lgkmcnt(0)
	v_mfma_f32_16x16x32_bf16 v[132:135], v[150:153], v[186:189], 0
	v_mfma_f32_16x16x32_bf16 v[132:135], v[158:161], v[190:193], v[132:135]
	s_barrier
	s_setprio 1
	v_mfma_f32_16x16x32_bf16 v[128:131], v[166:169], v[190:193], 0
	v_mfma_f32_16x16x32_bf16 v[128:131], v[162:165], v[186:189], v[128:131]
	v_mfma_f32_16x16x32_bf16 v[116:119], v[162:165], v[194:197], 0
	v_mfma_f32_16x16x32_bf16 v[116:119], v[166:169], v[198:201], v[116:119]
	v_mfma_f32_16x16x32_bf16 v[124:127], v[158:161], v[198:201], 0
	v_mfma_f32_16x16x32_bf16 v[124:127], v[150:153], v[194:197], v[124:127]
	v_mfma_f32_16x16x32_bf16 v[108:111], v[150:153], v[202:205], 0
	v_mfma_f32_16x16x32_bf16 v[108:111], v[158:161], v[206:209], v[108:111]
	v_mfma_f32_16x16x32_bf16 v[100:103], v[166:169], v[206:209], 0
	v_mfma_f32_16x16x32_bf16 v[100:103], v[162:165], v[202:205], v[100:103]
	v_mfma_f32_16x16x32_bf16 v[84:87], v[162:165], v[210:213], 0
	v_mfma_f32_16x16x32_bf16 v[84:87], v[166:169], v[214:217], v[84:87]
	v_mfma_f32_16x16x32_bf16 v[92:95], v[158:161], v[214:217], 0
	v_mfma_f32_16x16x32_bf16 v[92:95], v[150:153], v[210:213], v[92:95]
	v_mfma_f32_16x16x32_bf16 v[76:79], v[170:173], v[210:213], 0
	v_mfma_f32_16x16x32_bf16 v[76:79], v[174:177], v[214:217], v[76:79]
	v_mfma_f32_16x16x32_bf16 v[120:123], v[174:177], v[190:193], 0
	v_mfma_f32_16x16x32_bf16 v[120:123], v[170:173], v[186:189], v[120:123]
	v_mfma_f32_16x16x32_bf16 v[112:115], v[178:181], v[186:189], 0
	v_mfma_f32_16x16x32_bf16 v[112:115], v[182:185], v[190:193], v[112:115]
	v_mfma_f32_16x16x32_bf16 v[96:99], v[182:185], v[198:201], 0
	v_mfma_f32_16x16x32_bf16 v[96:99], v[178:181], v[194:197], v[96:99]
	v_mfma_f32_16x16x32_bf16 v[104:107], v[170:173], v[194:197], 0
	v_mfma_f32_16x16x32_bf16 v[104:107], v[174:177], v[198:201], v[104:107]
	v_mfma_f32_16x16x32_bf16 v[88:91], v[174:177], v[206:209], 0
	v_mfma_f32_16x16x32_bf16 v[88:91], v[170:173], v[202:205], v[88:91]
	v_mfma_f32_16x16x32_bf16 v[80:83], v[178:181], v[202:205], 0
	v_mfma_f32_16x16x32_bf16 v[80:83], v[182:185], v[206:209], v[80:83]
	v_mfma_f32_16x16x32_bf16 v[72:75], v[182:185], v[214:217], 0
	v_mfma_f32_16x16x32_bf16 v[72:75], v[178:181], v[210:213], v[72:75]
	s_setprio 0
	s_barrier
	s_add_i32 s68, s68, s29
	s_mov_b32 m0, s68
	ds_read_b128 v[186:189], v157 offset:16384
	ds_read_b128 v[190:193], v157 offset:17408
	ds_read_b128 v[194:197], v157 offset:18432
	ds_read_b128 v[198:201], v157 offset:19456
	ds_read_b128 v[202:205], v157 offset:20480
	ds_read_b128 v[206:209], v157 offset:21504
	ds_read_b128 v[210:213], v157 offset:22528
	ds_read_b128 v[214:217], v157 offset:23552
	global_load_lds_dwordx4 v140, s[24:25]
	s_add_i32 m0, s68, 0x2000
	s_add_u32 s68, s24, 0x4000
	s_addc_u32 s69, s25, 0
	s_add_i32 s77, s77, s29
	global_load_lds_dwordx4 v136, s[24:25]
	s_mov_b32 m0, s77
	s_nop 0
	global_load_lds_dwordx4 v140, s[68:69]
	s_add_i32 m0, s77, 0x2000
	s_nop 0
	global_load_lds_dwordx4 v136, s[68:69]
	s_mov_b32 m0, s31
	s_nop 0
	global_load_lds_dwordx4 v142, s[26:27]
	s_mov_b32 m0, s34
	s_nop 0
	global_load_lds_dwordx4 v138, s[26:27]
	s_waitcnt vmcnt(8)
	s_waitcnt lgkmcnt(0)
	v_mfma_f32_16x16x32_bf16 v[68:71], v[150:153], v[186:189], 0
	v_mfma_f32_16x16x32_bf16 v[68:71], v[158:161], v[190:193], v[68:71]
	s_barrier
; #define PG8_STAGE(bufoff, gbase, voff) do { _Pragma("unroll") for (int _i = 0; _i < 2; ++_i) \
;         __builtin_amdgcn_global_load_lds((const unsigned*)((const char*)(gbase) + (voff)[_i]), (PG8_LAS unsigned*)(lds + (bufoff) + ldsw + _i * 8192), 16, 0, 0); } while (0)
; #define PG8_LDA(dst, b, h) do { _Pragma("unroll") for (int m = 0; m < 4; ++m) _Pragma("unroll") for (int k = 0; k < 2; ++k) dst[m][k] = *(const PG8_LAS bf16x8*)(lds + PG8_SA(b, h) + aoff + m * 2048 + k * 1024); } while (0)
; #define PG8_LDB(dst, b, h) do { _Pragma("unroll") for (int n = 0; n < 2; ++n) _Pragma("unroll") for (int k = 0; k < 2; ++k) dst[n][k] = *(const PG8_LAS bf16x8*)(lds + PG8_SB(b, h) + boff + n * 2048 + k * 1024); } while (0)
; #define PG8_MMA(ai, bj, At, Bt) do { __builtin_amdgcn_s_setprio(1); _Pragma("unroll") for (int m = 0; m < 4; ++m) _Pragma("unroll") for (int n = 0; n < 2; ++n) _Pragma("unroll") for (int k = 0; k < 2; ++k) \
;         acc[ai][bj][m][n] = __builtin_amdgcn_mfma_f32_16x16x32_bf16(Bt[n][k], At[m][k], acc[ai][bj][m][n], 0, 0, 0); __builtin_amdgcn_s_setprio(0); } while (0)
; #define PG8_WAIT_V(n) asm volatile("s_waitcnt vmcnt(" #n ")" ::: "memory")
; #define PG8_WAIT_L(n) asm volatile("s_waitcnt lgkmcnt(" #n ")" ::: "memory")
; #define PG8_BAR __builtin_amdgcn_s_barrier()
; #define PG8_SCHED __builtin_amdgcn_sched_barrier(0)
; template <class Epi, class Sched, bool ALIGN_EPI = false, bool SP2 = false, bool ABLK = false, bool BBLK = false>
; __device__ __forceinline__ void gemm_phase(PG8_LAS unsigned char* lds, const Gemm g, const Sched& S, const Epi& E) {
;     ...
;             PG8_WAIT_V(8); PG8_WAIT_L(0); PG8_BAR; PG8_MMA(1, 0, At, B0); PG8_MMA(1, 1, At, B1); PG8_BAR; PG8_SCHED;
;             PG8_LDB(B0, 1, 0); PG8_LDB(B1, 1, 1); PG8_SCHED; PG8_LDA(At, 1, 0); PG8_STAGE(PG8_SA(0, 1), a2 + hstepA, voffA);
;             PG8_WAIT_V(8); PG8_WAIT_L(0); PG8_BAR; PG8_MMA(0, 0, At, B0); PG8_MMA(0, 1, At, B1); PG8_BAR; PG8_SCHED;
	s_setprio 1
	v_mfma_f32_16x16x32_bf16 v[64:67], v[166:169], v[190:193], 0
	v_mfma_f32_16x16x32_bf16 v[64:67], v[162:165], v[186:189], v[64:67]
	v_mfma_f32_16x16x32_bf16 v[52:55], v[162:165], v[194:197], 0
	v_mfma_f32_16x16x32_bf16 v[52:55], v[166:169], v[198:201], v[52:55]
	v_mfma_f32_16x16x32_bf16 v[60:63], v[158:161], v[198:201], 0
	v_mfma_f32_16x16x32_bf16 v[60:63], v[150:153], v[194:197], v[60:63]
	v_mfma_f32_16x16x32_bf16 v[44:47], v[150:153], v[202:205], 0
	v_mfma_f32_16x16x32_bf16 v[44:47], v[158:161], v[206:209], v[44:47]
	v_mfma_f32_16x16x32_bf16 v[32:35], v[166:169], v[206:209], 0
	v_mfma_f32_16x16x32_bf16 v[32:35], v[162:165], v[202:205], v[32:35]
	v_mfma_f32_16x16x32_bf16 v[16:19], v[162:165], v[210:213], 0
	v_mfma_f32_16x16x32_bf16 v[16:19], v[166:169], v[214:217], v[16:19]
	v_mfma_f32_16x16x32_bf16 v[24:27], v[158:161], v[214:217], 0
	v_mfma_f32_16x16x32_bf16 v[24:27], v[150:153], v[210:213], v[24:27]
	v_mfma_f32_16x16x32_bf16 v[8:11], v[170:173], v[210:213], 0
	v_mfma_f32_16x16x32_bf16 v[8:11], v[174:177], v[214:217], v[8:11]
	v_mfma_f32_16x16x32_bf16 v[56:59], v[174:177], v[190:193], 0
	v_mfma_f32_16x16x32_bf16 v[56:59], v[170:173], v[186:189], v[56:59]
	v_mfma_f32_16x16x32_bf16 v[48:51], v[178:181], v[186:189], 0
	v_mfma_f32_16x16x32_bf16 v[48:51], v[182:185], v[190:193], v[48:51]
	v_mfma_f32_16x16x32_bf16 v[28:31], v[182:185], v[198:201], 0
	v_mfma_f32_16x16x32_bf16 v[28:31], v[178:181], v[194:197], v[28:31]
	v_mfma_f32_16x16x32_bf16 v[40:43], v[170:173], v[194:197], 0
	v_mfma_f32_16x16x32_bf16 v[40:43], v[174:177], v[198:201], v[40:43]
	v_mfma_f32_16x16x32_bf16 v[20:23], v[174:177], v[206:209], 0
	v_mfma_f32_16x16x32_bf16 v[20:23], v[170:173], v[202:205], v[20:23]
	v_mfma_f32_16x16x32_bf16 v[12:15], v[178:181], v[202:205], 0
	v_mfma_f32_16x16x32_bf16 v[12:15], v[182:185], v[206:209], v[12:15]
	v_mfma_f32_16x16x32_bf16 v[4:7], v[182:185], v[214:217], 0
	v_mfma_f32_16x16x32_bf16 v[4:7], v[178:181], v[210:213], v[4:7]
	s_setprio 0
	s_barrier
	s_add_i32 s68, 0, 0x18000
	v_add_u32_e32 v36, s68, v155
	s_add_i32 s69, 0, 0x1c000
	ds_read_b128 v[150:153], v36
	ds_read_b128 v[158:161], v36 offset:1024
	ds_read_b128 v[162:165], v36 offset:2048
	ds_read_b128 v[166:169], v36 offset:3072
	v_add_u32_e32 v36, s69, v155
	ds_read_b128 v[170:173], v36
	ds_read_b128 v[174:177], v36 offset:1024
	ds_read_b128 v[178:181], v36 offset:2048
	ds_read_b128 v[182:185], v36 offset:3072
	s_add_u32 s26, s26, 0x4000
	s_addc_u32 s27, s27, 0
	s_mov_b32 m0, s35
	ds_read_b128 v[186:189], v157 offset:32768
	ds_read_b128 v[190:193], v157 offset:33792
	ds_read_b128 v[194:197], v157 offset:34816
	ds_read_b128 v[198:201], v157 offset:35840
	ds_read_b128 v[202:205], v157 offset:36864
	ds_read_b128 v[206:209], v157 offset:37888
	ds_read_b128 v[210:213], v157 offset:38912
	ds_read_b128 v[214:217], v157 offset:39936
	global_load_lds_dwordx4 v142, s[26:27]
	s_mov_b32 m0, s36
	s_nop 0
	global_load_lds_dwordx4 v138, s[26:27]
	s_waitcnt vmcnt(8)
	s_waitcnt lgkmcnt(0)
	v_mfma_f32_16x16x32_bf16 v[132:135], v[150:153], v[186:189], v[132:135]
	v_mfma_f32_16x16x32_bf16 v[132:135], v[158:161], v[190:193], v[132:135]
	s_barrier
	s_setprio 1
	v_mfma_f32_16x16x32_bf16 v[128:131], v[166:169], v[190:193], v[128:131]
	v_mfma_f32_16x16x32_bf16 v[128:131], v[162:165], v[186:189], v[128:131]
	v_mfma_f32_16x16x32_bf16 v[116:119], v[162:165], v[194:197], v[116:119]
	v_mfma_f32_16x16x32_bf16 v[116:119], v[166:169], v[198:201], v[116:119]
	v_mfma_f32_16x16x32_bf16 v[124:127], v[158:161], v[198:201], v[124:127]
	v_mfma_f32_16x16x32_bf16 v[124:127], v[150:153], v[194:197], v[124:127]
	v_mfma_f32_16x16x32_bf16 v[108:111], v[150:153], v[202:205], v[108:111]
	v_mfma_f32_16x16x32_bf16 v[108:111], v[158:161], v[206:209], v[108:111]
	v_mfma_f32_16x16x32_bf16 v[100:103], v[166:169], v[206:209], v[100:103]
	v_mfma_f32_16x16x32_bf16 v[100:103], v[162:165], v[202:205], v[100:103]
	v_mfma_f32_16x16x32_bf16 v[84:87], v[162:165], v[210:213], v[84:87]
	v_mfma_f32_16x16x32_bf16 v[84:87], v[166:169], v[214:217], v[84:87]
	v_mfma_f32_16x16x32_bf16 v[92:95], v[158:161], v[214:217], v[92:95]
	v_mfma_f32_16x16x32_bf16 v[92:95], v[150:153], v[210:213], v[92:95]
	v_mfma_f32_16x16x32_bf16 v[76:79], v[170:173], v[210:213], v[76:79]
	v_mfma_f32_16x16x32_bf16 v[76:79], v[174:177], v[214:217], v[76:79]
	v_mfma_f32_16x16x32_bf16 v[120:123], v[174:177], v[190:193], v[120:123]
	v_mfma_f32_16x16x32_bf16 v[120:123], v[170:173], v[186:189], v[120:123]
	v_mfma_f32_16x16x32_bf16 v[112:115], v[178:181], v[186:189], v[112:115]
	v_mfma_f32_16x16x32_bf16 v[112:115], v[182:185], v[190:193], v[112:115]
	v_mfma_f32_16x16x32_bf16 v[96:99], v[182:185], v[198:201], v[96:99]
	v_mfma_f32_16x16x32_bf16 v[96:99], v[178:181], v[194:197], v[96:99]
	v_mfma_f32_16x16x32_bf16 v[104:107], v[170:173], v[194:197], v[104:107]
	v_mfma_f32_16x16x32_bf16 v[104:107], v[174:177], v[198:201], v[104:107]
	v_mfma_f32_16x16x32_bf16 v[88:91], v[174:177], v[206:209], v[88:91]
	v_mfma_f32_16x16x32_bf16 v[88:91], v[170:173], v[202:205], v[88:91]
	v_mfma_f32_16x16x32_bf16 v[80:83], v[178:181], v[202:205], v[80:83]
	v_mfma_f32_16x16x32_bf16 v[80:83], v[182:185], v[206:209], v[80:83]
	v_mfma_f32_16x16x32_bf16 v[72:75], v[182:185], v[214:217], v[72:75]
	v_mfma_f32_16x16x32_bf16 v[72:75], v[178:181], v[210:213], v[72:75]
	s_setprio 0
	s_barrier
; #define PG8_STAGE(bufoff, gbase, voff) do { _Pragma("unroll") for (int _i = 0; _i < 2; ++_i) \
;         __builtin_amdgcn_global_load_lds((const unsigned*)((const char*)(gbase) + (voff)[_i]), (PG8_LAS unsigned*)(lds + (bufoff) + ldsw + _i * 8192), 16, 0, 0); } while (0)
; #define PG8_LDA(dst, b, h) do { _Pragma("unroll") for (int m = 0; m < 4; ++m) _Pragma("unroll") for (int k = 0; k < 2; ++k) dst[m][k] = *(const PG8_LAS bf16x8*)(lds + PG8_SA(b, h) + aoff + m * 2048 + k * 1024); } while (0)
; #define PG8_WAIT_V(n) asm volatile("s_waitcnt vmcnt(" #n ")" ::: "memory")
; #define PG8_WAIT_L(n) asm volatile("s_waitcnt lgkmcnt(" #n ")" ::: "memory")
; template <class Epi, class Sched, bool ALIGN_EPI = false, bool SP2 = false, bool ABLK = false, bool BBLK = false>
; __device__ __forceinline__ void gemm_phase(PG8_LAS unsigned char* lds, const Gemm g, const Sched& S, const Epi& E) {
;     ...
;         for (int t = 0; t < nt; t += 2) {
;             const bool last = (t == nt - 2);
;             const char* a1 = cA + (size_t)(t + 1) * kstepA;
;             const char* a2 = last ? nA : cA + (size_t)(t + 2) * kstepA; const char* b2 = last ? nB : cB + (size_t)(t + 2) * kstepB;
;             const char* a3 = a2 + kstepA; const char* b3 = b2 + kstepB;
;             if (last && has_next) S.a_ready(nxt);
;             if constexpr (SP2) {
;             PG8_LDB(B0, 0, 0); PG8_LDB(B1, 0, 1); PG8_SCHED; PG8_LDA(At, 0, 0); PG8_STAGE(PG8_SA(1, 1), a1 + hstepA, voffA);
;             PG8_WAIT_V(8); PG8_WAIT_L(0); PG8_BAR; PG8_MMA(0, 0, At, B0); PG8_MMA(0, 1, At, B1); PG8_BAR; PG8_SCHED;
;             PG8_LDA(At, 0, 1); PG8_STAGE(PG8_SB(0, 0), b2, voffB); PG8_STAGE(PG8_SB(0, 1), b2 + hstepB, voffB); PG8_STAGE(PG8_SA(0, 0), a2, voffA);
;             PG8_WAIT_V(8); PG8_WAIT_L(0); PG8_BAR; PG8_MMA(1, 0, At, B0); PG8_MMA(1, 1, At, B1); PG8_BAR; PG8_SCHED;
;             PG8_LDB(B0, 1, 0); PG8_LDB(B1, 1, 1); PG8_SCHED; PG8_LDA(At, 1, 0); PG8_STAGE(PG8_SA(0, 1), a2 + hstepA, voffA);
;             PG8_WAIT_V(8); PG8_WAIT_L(0); PG8_BAR; PG8_MMA(0, 0, At, B0); PG8_MMA(0, 1, At, B1); PG8_BAR; PG8_SCHED;
;             PG8_LDA(At, 1, 1); PG8_STAGE(PG8_SB(1, 0), b3, voffB); PG8_STAGE(PG8_SB(1, 1), b3 + hstepB, voffB); PG8_STAGE(PG8_SA(1, 0), a3, voffA);
;             PG8_WAIT_V(8); PG8_WAIT_L(0); PG8_BAR; PG8_MMA(1, 0, At, B0); PG8_MMA(1, 1, At, B1); PG8_BAR; PG8_SCHED;
	s_add_u32 s26, s24, 0x8000
	s_addc_u32 s27, s25, 0
	s_add_i32 s68, s68, s29
	s_mov_b32 m0, s68
	ds_read_b128 v[186:189], v157 offset:49152
	ds_read_b128 v[190:193], v157 offset:50176
	ds_read_b128 v[194:197], v157 offset:51200
	ds_read_b128 v[198:201], v157 offset:52224
	ds_read_b128 v[202:205], v157 offset:53248
	ds_read_b128 v[206:209], v157 offset:54272
	ds_read_b128 v[210:213], v157 offset:55296
	ds_read_b128 v[214:217], v157 offset:56320
	global_load_lds_dwordx4 v140, s[26:27]
	s_add_i32 m0, s68, 0x2000
	s_add_u32 s24, s24, 0xc000
	s_addc_u32 s25, s25, 0
	global_load_lds_dwordx4 v136, s[26:27]
	s_add_i32 s26, s69, s29
	s_mov_b32 m0, s26
	s_nop 0
	global_load_lds_dwordx4 v140, s[24:25]
	s_add_i32 m0, s26, 0x2000
	s_nop 0
	global_load_lds_dwordx4 v136, s[24:25]
	s_mov_b32 m0, s37
	s_nop 0
	global_load_lds_dwordx4 v142, s[22:23]
	s_mov_b32 m0, s62
	s_nop 0
	global_load_lds_dwordx4 v138, s[22:23]
	s_waitcnt vmcnt(8)
	s_waitcnt lgkmcnt(0)
	v_mfma_f32_16x16x32_bf16 v[68:71], v[150:153], v[186:189], v[68:71]
	v_mfma_f32_16x16x32_bf16 v[68:71], v[158:161], v[190:193], v[68:71]
	s_barrier
	s_setprio 1
	v_mfma_f32_16x16x32_bf16 v[64:67], v[166:169], v[190:193], v[64:67]
	v_mfma_f32_16x16x32_bf16 v[64:67], v[162:165], v[186:189], v[64:67]
	v_mfma_f32_16x16x32_bf16 v[52:55], v[162:165], v[194:197], v[52:55]
	v_mfma_f32_16x16x32_bf16 v[52:55], v[166:169], v[198:201], v[52:55]
	v_mfma_f32_16x16x32_bf16 v[60:63], v[158:161], v[198:201], v[60:63]
	v_mfma_f32_16x16x32_bf16 v[60:63], v[150:153], v[194:197], v[60:63]
	v_mfma_f32_16x16x32_bf16 v[44:47], v[150:153], v[202:205], v[44:47]
	v_mfma_f32_16x16x32_bf16 v[44:47], v[158:161], v[206:209], v[44:47]
	v_mfma_f32_16x16x32_bf16 v[32:35], v[166:169], v[206:209], v[32:35]
	v_mfma_f32_16x16x32_bf16 v[32:35], v[162:165], v[202:205], v[32:35]
	v_mfma_f32_16x16x32_bf16 v[16:19], v[162:165], v[210:213], v[16:19]
	v_mfma_f32_16x16x32_bf16 v[16:19], v[166:169], v[214:217], v[16:19]
	v_mfma_f32_16x16x32_bf16 v[24:27], v[158:161], v[214:217], v[24:27]
	v_mfma_f32_16x16x32_bf16 v[24:27], v[150:153], v[210:213], v[24:27]
	v_mfma_f32_16x16x32_bf16 v[8:11], v[170:173], v[210:213], v[8:11]
	v_mfma_f32_16x16x32_bf16 v[8:11], v[174:177], v[214:217], v[8:11]
	v_mfma_f32_16x16x32_bf16 v[56:59], v[174:177], v[190:193], v[56:59]
	v_mfma_f32_16x16x32_bf16 v[56:59], v[170:173], v[186:189], v[56:59]
	v_mfma_f32_16x16x32_bf16 v[48:51], v[178:181], v[186:189], v[48:51]
	v_mfma_f32_16x16x32_bf16 v[48:51], v[182:185], v[190:193], v[48:51]
	v_mfma_f32_16x16x32_bf16 v[28:31], v[182:185], v[198:201], v[28:31]
	v_mfma_f32_16x16x32_bf16 v[28:31], v[178:181], v[194:197], v[28:31]
	v_mfma_f32_16x16x32_bf16 v[40:43], v[170:173], v[194:197], v[40:43]
	v_mfma_f32_16x16x32_bf16 v[40:43], v[174:177], v[198:201], v[40:43]
	v_mfma_f32_16x16x32_bf16 v[20:23], v[174:177], v[206:209], v[20:23]
	v_mfma_f32_16x16x32_bf16 v[20:23], v[170:173], v[202:205], v[20:23]
	v_mfma_f32_16x16x32_bf16 v[12:15], v[178:181], v[202:205], v[12:15]
	v_mfma_f32_16x16x32_bf16 v[12:15], v[182:185], v[206:209], v[12:15]
	v_mfma_f32_16x16x32_bf16 v[4:7], v[182:185], v[214:217], v[4:7]
	v_mfma_f32_16x16x32_bf16 v[4:7], v[178:181], v[210:213], v[4:7]
	s_setprio 0
	s_barrier
	s_add_i32 s13, s13, 2
	s_add_u32 s20, s20, 0x10000
	s_addc_u32 s21, s21, 0
	s_add_u32 s70, s70, 0x10000
	s_addc_u32 s71, s71, 0
	s_cmp_gt_u32 s13, 29
.LBB0_916:
	s_add_u32 s22, s20, 0x4000
	s_addc_u32 s23, s21, 0
	s_cmp_eq_u32 s13, 28
	s_cselect_b32 s26, s19, s22
	s_cselect_b32 s27, s1, s23
	s_cselect_b32 s24, s65, s70
	s_cselect_b32 s25, s9, s71
	s_add_u32 s22, s26, 0x8000
	s_addc_u32 s23, s27, 0
	s_add_i32 s68, 0, 0x10000
	v_add_u32_e32 v36, s68, v155
	s_add_i32 s77, 0, 0x14000
	ds_read_b128 v[150:153], v36
	ds_read_b128 v[158:161], v36 offset:1024
	ds_read_b128 v[162:165], v36 offset:2048
	ds_read_b128 v[166:169], v36 offset:3072
	v_add_u32_e32 v36, s77, v155
	ds_read_b128 v[170:173], v36
	ds_read_b128 v[174:177], v36 offset:1024
	ds_read_b128 v[178:181], v36 offset:2048
	ds_read_b128 v[182:185], v36 offset:3072
	s_add_i32 m0, s31, 0xc000
	ds_read_b128 v[186:189], v157
	ds_read_b128 v[190:193], v157 offset:1024
	ds_read_b128 v[194:197], v157 offset:2048
	ds_read_b128 v[198:201], v157 offset:3072
	ds_read_b128 v[202:205], v157 offset:4096
	ds_read_b128 v[206:209], v157 offset:5120
	ds_read_b128 v[210:213], v157 offset:6144
	ds_read_b128 v[214:217], v157 offset:7168
	global_load_lds_dwordx4 v146, s[20:21]
	s_add_i32 m0, s31, 0xe000
	s_nop 0
	global_load_lds_dwordx4 v148, s[20:21]
	s_waitcnt vmcnt(8)
	s_waitcnt lgkmcnt(0)
	v_mfma_f32_16x16x32_bf16 v[132:135], v[150:153], v[186:189], v[132:135]
	v_mfma_f32_16x16x32_bf16 v[132:135], v[158:161], v[190:193], v[132:135]
	s_barrier
; #define PG8_STAGE(bufoff, gbase, voff) do { _Pragma("unroll") for (int _i = 0; _i < 2; ++_i) \
;         __builtin_amdgcn_global_load_lds((const unsigned*)((const char*)(gbase) + (voff)[_i]), (PG8_LAS unsigned*)(lds + (bufoff) + ldsw + _i * 8192), 16, 0, 0); } while (0)
; #define PG8_LDA(dst, b, h) do { _Pragma("unroll") for (int m = 0; m < 4; ++m) _Pragma("unroll") for (int k = 0; k < 2; ++k) dst[m][k] = *(const PG8_LAS bf16x8*)(lds + PG8_SA(b, h) + aoff + m * 2048 + k * 1024); } while (0)
; #define PG8_LDB(dst, b, h) do { _Pragma("unroll") for (int n = 0; n < 2; ++n) _Pragma("unroll") for (int k = 0; k < 2; ++k) dst[n][k] = *(const PG8_LAS bf16x8*)(lds + PG8_SB(b, h) + boff + n * 2048 + k * 1024); } while (0)
; #define PG8_MMA(ai, bj, At, Bt) do { __builtin_amdgcn_s_setprio(1); _Pragma("unroll") for (int m = 0; m < 4; ++m) _Pragma("unroll") for (int n = 0; n < 2; ++n) _Pragma("unroll") for (int k = 0; k < 2; ++k) \
;         acc[ai][bj][m][n] = __builtin_amdgcn_mfma_f32_16x16x32_bf16(Bt[n][k], At[m][k], acc[ai][bj][m][n], 0, 0, 0); __builtin_amdgcn_s_setprio(0); } while (0)
; #define PG8_WAIT_V(n) asm volatile("s_waitcnt vmcnt(" #n ")" ::: "memory")
; #define PG8_WAIT_L(n) asm volatile("s_waitcnt lgkmcnt(" #n ")" ::: "memory")
; #define PG8_BAR __builtin_amdgcn_s_barrier()
; #define PG8_SCHED __builtin_amdgcn_sched_barrier(0)
; template <class Epi, class Sched, bool ALIGN_EPI = false, bool SP2 = false, bool ABLK = false, bool BBLK = false>
; __device__ __forceinline__ void gemm_phase(PG8_LAS unsigned char* lds, const Gemm g, const Sched& S, const Epi& E) {
;     ...
;             PG8_LDB(B0, 0, 0); PG8_LDB(B1, 0, 1); PG8_SCHED; PG8_LDA(At, 0, 0); PG8_STAGE(PG8_SA(1, 1), a1 + hstepA, voffA);
;             PG8_WAIT_V(8); PG8_WAIT_L(0); PG8_BAR; PG8_MMA(0, 0, At, B0); PG8_MMA(0, 1, At, B1); PG8_BAR; PG8_SCHED;
;             PG8_LDA(At, 0, 1); PG8_STAGE(PG8_SB(0, 0), b2, voffB); PG8_STAGE(PG8_SB(0, 1), b2 + hstepB, voffB); PG8_STAGE(PG8_SA(0, 0), a2, voffA);
;             PG8_WAIT_V(8); PG8_WAIT_L(0); PG8_BAR; PG8_MMA(1, 0, At, B0); PG8_MMA(1, 1, At, B1); PG8_BAR; PG8_SCHED;
	s_setprio 1
	v_mfma_f32_16x16x32_bf16 v[128:131], v[166:169], v[190:193], v[128:131]
	v_mfma_f32_16x16x32_bf16 v[128:131], v[162:165], v[186:189], v[128:131]
	v_mfma_f32_16x16x32_bf16 v[116:119], v[162:165], v[194:197], v[116:119]
	v_mfma_f32_16x16x32_bf16 v[116:119], v[166:169], v[198:201], v[116:119]
	v_mfma_f32_16x16x32_bf16 v[124:127], v[158:161], v[198:201], v[124:127]
	v_mfma_f32_16x16x32_bf16 v[124:127], v[150:153], v[194:197], v[124:127]
	v_mfma_f32_16x16x32_bf16 v[108:111], v[150:153], v[202:205], v[108:111]
	v_mfma_f32_16x16x32_bf16 v[108:111], v[158:161], v[206:209], v[108:111]
	v_mfma_f32_16x16x32_bf16 v[100:103], v[166:169], v[206:209], v[100:103]
	v_mfma_f32_16x16x32_bf16 v[100:103], v[162:165], v[202:205], v[100:103]
	v_mfma_f32_16x16x32_bf16 v[84:87], v[162:165], v[210:213], v[84:87]
	v_mfma_f32_16x16x32_bf16 v[84:87], v[166:169], v[214:217], v[84:87]
	v_mfma_f32_16x16x32_bf16 v[92:95], v[158:161], v[214:217], v[92:95]
	v_mfma_f32_16x16x32_bf16 v[92:95], v[150:153], v[210:213], v[92:95]
	v_mfma_f32_16x16x32_bf16 v[76:79], v[170:173], v[210:213], v[76:79]
	v_mfma_f32_16x16x32_bf16 v[76:79], v[174:177], v[214:217], v[76:79]
	v_mfma_f32_16x16x32_bf16 v[120:123], v[174:177], v[190:193], v[120:123]
	v_mfma_f32_16x16x32_bf16 v[120:123], v[170:173], v[186:189], v[120:123]
	v_mfma_f32_16x16x32_bf16 v[112:115], v[178:181], v[186:189], v[112:115]
	v_mfma_f32_16x16x32_bf16 v[112:115], v[182:185], v[190:193], v[112:115]
	v_mfma_f32_16x16x32_bf16 v[96:99], v[182:185], v[198:201], v[96:99]
	v_mfma_f32_16x16x32_bf16 v[96:99], v[178:181], v[194:197], v[96:99]
	v_mfma_f32_16x16x32_bf16 v[104:107], v[170:173], v[194:197], v[104:107]
	v_mfma_f32_16x16x32_bf16 v[104:107], v[174:177], v[198:201], v[104:107]
	v_mfma_f32_16x16x32_bf16 v[88:91], v[174:177], v[206:209], v[88:91]
	v_mfma_f32_16x16x32_bf16 v[88:91], v[170:173], v[202:205], v[88:91]
	v_mfma_f32_16x16x32_bf16 v[80:83], v[178:181], v[202:205], v[80:83]
	v_mfma_f32_16x16x32_bf16 v[80:83], v[182:185], v[206:209], v[80:83]
	v_mfma_f32_16x16x32_bf16 v[72:75], v[182:185], v[214:217], v[72:75]
	v_mfma_f32_16x16x32_bf16 v[72:75], v[178:181], v[210:213], v[72:75]
	s_setprio 0
	s_barrier
	s_add_i32 s68, s68, s29
	s_mov_b32 m0, s68
	ds_read_b128 v[186:189], v157 offset:16384
	ds_read_b128 v[190:193], v157 offset:17408
	ds_read_b128 v[194:197], v157 offset:18432
	ds_read_b128 v[198:201], v157 offset:19456
	ds_read_b128 v[202:205], v157 offset:20480
	ds_read_b128 v[206:209], v157 offset:21504
	ds_read_b128 v[210:213], v157 offset:22528
	ds_read_b128 v[214:217], v157 offset:23552
	global_load_lds_dwordx4 v140, s[24:25]
	s_add_i32 m0, s68, 0x2000
	s_add_u32 s68, s24, 0x4000
	s_addc_u32 s69, s25, 0
	s_add_i32 s77, s77, s29
	global_load_lds_dwordx4 v136, s[24:25]
	s_mov_b32 m0, s77
	s_nop 0
	global_load_lds_dwordx4 v140, s[68:69]
	s_add_i32 m0, s77, 0x2000
	s_nop 0
	global_load_lds_dwordx4 v136, s[68:69]
	s_mov_b32 m0, s31
	s_nop 0
	global_load_lds_dwordx4 v142, s[26:27]
	s_mov_b32 m0, s34
	s_nop 0
	global_load_lds_dwordx4 v138, s[26:27]
	s_waitcnt vmcnt(8)
	s_waitcnt lgkmcnt(0)
	v_mfma_f32_16x16x32_bf16 v[68:71], v[150:153], v[186:189], v[68:71]
	v_mfma_f32_16x16x32_bf16 v[68:71], v[158:161], v[190:193], v[68:71]
	s_barrier
	s_setprio 1
	v_mfma_f32_16x16x32_bf16 v[64:67], v[166:169], v[190:193], v[64:67]
	v_mfma_f32_16x16x32_bf16 v[64:67], v[162:165], v[186:189], v[64:67]
	v_mfma_f32_16x16x32_bf16 v[52:55], v[162:165], v[194:197], v[52:55]
	v_mfma_f32_16x16x32_bf16 v[52:55], v[166:169], v[198:201], v[52:55]
	v_mfma_f32_16x16x32_bf16 v[60:63], v[158:161], v[198:201], v[60:63]
	v_mfma_f32_16x16x32_bf16 v[60:63], v[150:153], v[194:197], v[60:63]
	v_mfma_f32_16x16x32_bf16 v[44:47], v[150:153], v[202:205], v[44:47]
	v_mfma_f32_16x16x32_bf16 v[44:47], v[158:161], v[206:209], v[44:47]
	v_mfma_f32_16x16x32_bf16 v[32:35], v[166:169], v[206:209], v[32:35]
	v_mfma_f32_16x16x32_bf16 v[32:35], v[162:165], v[202:205], v[32:35]
	v_mfma_f32_16x16x32_bf16 v[16:19], v[162:165], v[210:213], v[16:19]
	v_mfma_f32_16x16x32_bf16 v[16:19], v[166:169], v[214:217], v[16:19]
	v_mfma_f32_16x16x32_bf16 v[24:27], v[158:161], v[214:217], v[24:27]
	v_mfma_f32_16x16x32_bf16 v[24:27], v[150:153], v[210:213], v[24:27]
	v_mfma_f32_16x16x32_bf16 v[8:11], v[170:173], v[210:213], v[8:11]
	v_mfma_f32_16x16x32_bf16 v[8:11], v[174:177], v[214:217], v[8:11]
	v_mfma_f32_16x16x32_bf16 v[56:59], v[174:177], v[190:193], v[56:59]
	v_mfma_f32_16x16x32_bf16 v[56:59], v[170:173], v[186:189], v[56:59]
	v_mfma_f32_16x16x32_bf16 v[48:51], v[178:181], v[186:189], v[48:51]
	v_mfma_f32_16x16x32_bf16 v[48:51], v[182:185], v[190:193], v[48:51]
	v_mfma_f32_16x16x32_bf16 v[28:31], v[182:185], v[198:201], v[28:31]
	v_mfma_f32_16x16x32_bf16 v[28:31], v[178:181], v[194:197], v[28:31]
	v_mfma_f32_16x16x32_bf16 v[40:43], v[170:173], v[194:197], v[40:43]
	v_mfma_f32_16x16x32_bf16 v[40:43], v[174:177], v[198:201], v[40:43]
	v_mfma_f32_16x16x32_bf16 v[20:23], v[174:177], v[206:209], v[20:23]
	v_mfma_f32_16x16x32_bf16 v[20:23], v[170:173], v[202:205], v[20:23]
	v_mfma_f32_16x16x32_bf16 v[12:15], v[178:181], v[202:205], v[12:15]
	v_mfma_f32_16x16x32_bf16 v[12:15], v[182:185], v[206:209], v[12:15]
	v_mfma_f32_16x16x32_bf16 v[4:7], v[182:185], v[214:217], v[4:7]
	v_mfma_f32_16x16x32_bf16 v[4:7], v[178:181], v[210:213], v[4:7]
	s_setprio 0
	s_barrier
; #define PG8_STAGE(bufoff, gbase, voff) do { _Pragma("unroll") for (int _i = 0; _i < 2; ++_i) \
;         __builtin_amdgcn_global_load_lds((const unsigned*)((const char*)(gbase) + (voff)[_i]), (PG8_LAS unsigned*)(lds + (bufoff) + ldsw + _i * 8192), 16, 0, 0); } while (0)
; #define PG8_LDA(dst, b, h) do { _Pragma("unroll") for (int m = 0; m < 4; ++m) _Pragma("unroll") for (int k = 0; k < 2; ++k) dst[m][k] = *(const PG8_LAS bf16x8*)(lds + PG8_SA(b, h) + aoff + m * 2048 + k * 1024); } while (0)
; #define PG8_LDB(dst, b, h) do { _Pragma("unroll") for (int n = 0; n < 2; ++n) _Pragma("unroll") for (int k = 0; k < 2; ++k) dst[n][k] = *(const PG8_LAS bf16x8*)(lds + PG8_SB(b, h) + boff + n * 2048 + k * 1024); } while (0)
; #define PG8_MMA(ai, bj, At, Bt) do { __builtin_amdgcn_s_setprio(1); _Pragma("unroll") for (int m = 0; m < 4; ++m) _Pragma("unroll") for (int n = 0; n < 2; ++n) _Pragma("unroll") for (int k = 0; k < 2; ++k) \
;         acc[ai][bj][m][n] = __builtin_amdgcn_mfma_f32_16x16x32_bf16(Bt[n][k], At[m][k], acc[ai][bj][m][n], 0, 0, 0); __builtin_amdgcn_s_setprio(0); } while (0)
; #define PG8_WAIT_V(n) asm volatile("s_waitcnt vmcnt(" #n ")" ::: "memory")
; #define PG8_WAIT_L(n) asm volatile("s_waitcnt lgkmcnt(" #n ")" ::: "memory")
; #define PG8_BAR __builtin_amdgcn_s_barrier()
; #define PG8_SCHED __builtin_amdgcn_sched_barrier(0)
; template <class Epi, class Sched, bool ALIGN_EPI = false, bool SP2 = false, bool ABLK = false, bool BBLK = false>
; __device__ __forceinline__ void gemm_phase(PG8_LAS unsigned char* lds, const Gemm g, const Sched& S, const Epi& E) {
;     ...
;             PG8_LDB(B0, 1, 0); PG8_LDB(B1, 1, 1); PG8_SCHED; PG8_LDA(At, 1, 0); PG8_STAGE(PG8_SA(0, 1), a2 + hstepA, voffA);
;             PG8_WAIT_V(8); PG8_WAIT_L(0); PG8_BAR; PG8_MMA(0, 0, At, B0); PG8_MMA(0, 1, At, B1); PG8_BAR; PG8_SCHED;
;             PG8_LDA(At, 1, 1); PG8_STAGE(PG8_SB(1, 0), b3, voffB); PG8_STAGE(PG8_SB(1, 1), b3 + hstepB, voffB); PG8_STAGE(PG8_SA(1, 0), a3, voffA);
;             PG8_WAIT_V(8); PG8_WAIT_L(0); PG8_BAR; PG8_MMA(1, 0, At, B0); PG8_MMA(1, 1, At, B1); PG8_BAR; PG8_SCHED;
;     ...
;         if constexpr (ALIGN_EPI) { if (wr == 0) PG8_BAR; }
	s_add_i32 s68, 0, 0x18000
	v_add_u32_e32 v36, s68, v155
	s_add_i32 s69, 0, 0x1c000
	ds_read_b128 v[150:153], v36
	ds_read_b128 v[158:161], v36 offset:1024
	ds_read_b128 v[162:165], v36 offset:2048
	ds_read_b128 v[166:169], v36 offset:3072
	v_add_u32_e32 v36, s69, v155
	ds_read_b128 v[170:173], v36
	ds_read_b128 v[174:177], v36 offset:1024
	ds_read_b128 v[178:181], v36 offset:2048
	ds_read_b128 v[182:185], v36 offset:3072
	s_add_u32 s26, s26, 0x4000
	s_addc_u32 s27, s27, 0
	s_mov_b32 m0, s35
	ds_read_b128 v[186:189], v157 offset:32768
	ds_read_b128 v[190:193], v157 offset:33792
	ds_read_b128 v[194:197], v157 offset:34816
	ds_read_b128 v[198:201], v157 offset:35840
	ds_read_b128 v[202:205], v157 offset:36864
	ds_read_b128 v[206:209], v157 offset:37888
	ds_read_b128 v[210:213], v157 offset:38912
	ds_read_b128 v[214:217], v157 offset:39936
	global_load_lds_dwordx4 v142, s[26:27]
	s_mov_b32 m0, s36
	s_nop 0
	global_load_lds_dwordx4 v138, s[26:27]
	s_waitcnt vmcnt(8)
	s_waitcnt lgkmcnt(0)
	v_mfma_f32_16x16x32_bf16 v[132:135], v[150:153], v[186:189], v[132:135]
	v_mfma_f32_16x16x32_bf16 v[132:135], v[158:161], v[190:193], v[132:135]
	s_barrier
	s_setprio 1
	v_mfma_f32_16x16x32_bf16 v[128:131], v[166:169], v[190:193], v[128:131]
	v_mfma_f32_16x16x32_bf16 v[128:131], v[162:165], v[186:189], v[128:131]
	v_mfma_f32_16x16x32_bf16 v[116:119], v[162:165], v[194:197], v[116:119]
	v_mfma_f32_16x16x32_bf16 v[116:119], v[166:169], v[198:201], v[116:119]
	v_mfma_f32_16x16x32_bf16 v[124:127], v[158:161], v[198:201], v[124:127]
	v_mfma_f32_16x16x32_bf16 v[124:127], v[150:153], v[194:197], v[124:127]
	v_mfma_f32_16x16x32_bf16 v[108:111], v[150:153], v[202:205], v[108:111]
	v_mfma_f32_16x16x32_bf16 v[108:111], v[158:161], v[206:209], v[108:111]
	v_mfma_f32_16x16x32_bf16 v[100:103], v[166:169], v[206:209], v[100:103]
	v_mfma_f32_16x16x32_bf16 v[100:103], v[162:165], v[202:205], v[100:103]
	v_mfma_f32_16x16x32_bf16 v[84:87], v[162:165], v[210:213], v[84:87]
	v_mfma_f32_16x16x32_bf16 v[84:87], v[166:169], v[214:217], v[84:87]
	v_mfma_f32_16x16x32_bf16 v[92:95], v[158:161], v[214:217], v[92:95]
	v_mfma_f32_16x16x32_bf16 v[92:95], v[150:153], v[210:213], v[92:95]
	v_mfma_f32_16x16x32_bf16 v[76:79], v[170:173], v[210:213], v[76:79]
	v_mfma_f32_16x16x32_bf16 v[76:79], v[174:177], v[214:217], v[76:79]
	v_mfma_f32_16x16x32_bf16 v[120:123], v[174:177], v[190:193], v[120:123]
	v_mfma_f32_16x16x32_bf16 v[120:123], v[170:173], v[186:189], v[120:123]
	v_mfma_f32_16x16x32_bf16 v[112:115], v[178:181], v[186:189], v[112:115]
	v_mfma_f32_16x16x32_bf16 v[112:115], v[182:185], v[190:193], v[112:115]
	v_mfma_f32_16x16x32_bf16 v[96:99], v[182:185], v[198:201], v[96:99]
	v_mfma_f32_16x16x32_bf16 v[96:99], v[178:181], v[194:197], v[96:99]
	v_mfma_f32_16x16x32_bf16 v[104:107], v[170:173], v[194:197], v[104:107]
	v_mfma_f32_16x16x32_bf16 v[104:107], v[174:177], v[198:201], v[104:107]
	v_mfma_f32_16x16x32_bf16 v[88:91], v[174:177], v[206:209], v[88:91]
	v_mfma_f32_16x16x32_bf16 v[88:91], v[170:173], v[202:205], v[88:91]
	v_mfma_f32_16x16x32_bf16 v[80:83], v[178:181], v[202:205], v[80:83]
	v_mfma_f32_16x16x32_bf16 v[80:83], v[182:185], v[206:209], v[80:83]
	v_mfma_f32_16x16x32_bf16 v[72:75], v[182:185], v[214:217], v[72:75]
	v_mfma_f32_16x16x32_bf16 v[72:75], v[178:181], v[210:213], v[72:75]
	s_setprio 0
	s_barrier
	s_add_u32 s26, s24, 0x8000
	s_addc_u32 s27, s25, 0
	s_add_i32 s68, s68, s29
	s_mov_b32 m0, s68
	ds_read_b128 v[186:189], v157 offset:49152
	ds_read_b128 v[190:193], v157 offset:50176
	ds_read_b128 v[194:197], v157 offset:51200
	ds_read_b128 v[198:201], v157 offset:52224
	ds_read_b128 v[202:205], v157 offset:53248
	ds_read_b128 v[206:209], v157 offset:54272
	ds_read_b128 v[210:213], v157 offset:55296
	ds_read_b128 v[214:217], v157 offset:56320
	global_load_lds_dwordx4 v140, s[26:27]
	s_add_i32 m0, s68, 0x2000
	s_add_u32 s24, s24, 0xc000
	s_addc_u32 s25, s25, 0
	global_load_lds_dwordx4 v136, s[26:27]
	s_add_i32 s26, s69, s29
	s_mov_b32 m0, s26
	s_nop 0
	global_load_lds_dwordx4 v140, s[24:25]
	s_add_i32 m0, s26, 0x2000
	s_nop 0
	global_load_lds_dwordx4 v136, s[24:25]
	s_mov_b32 m0, s37
	s_nop 0
	global_load_lds_dwordx4 v142, s[22:23]
	s_mov_b32 m0, s62
	s_nop 0
	global_load_lds_dwordx4 v138, s[22:23]
	s_waitcnt vmcnt(8)
	s_waitcnt lgkmcnt(0)
	v_mfma_f32_16x16x32_bf16 v[68:71], v[150:153], v[186:189], v[68:71]
	v_mfma_f32_16x16x32_bf16 v[68:71], v[158:161], v[190:193], v[68:71]
	s_barrier
	s_setprio 1
	v_mfma_f32_16x16x32_bf16 v[64:67], v[166:169], v[190:193], v[64:67]
	v_mfma_f32_16x16x32_bf16 v[64:67], v[162:165], v[186:189], v[64:67]
	v_mfma_f32_16x16x32_bf16 v[52:55], v[162:165], v[194:197], v[52:55]
	v_mfma_f32_16x16x32_bf16 v[52:55], v[166:169], v[198:201], v[52:55]
	v_mfma_f32_16x16x32_bf16 v[60:63], v[158:161], v[198:201], v[60:63]
	v_mfma_f32_16x16x32_bf16 v[60:63], v[150:153], v[194:197], v[60:63]
	v_mfma_f32_16x16x32_bf16 v[44:47], v[150:153], v[202:205], v[44:47]
	v_mfma_f32_16x16x32_bf16 v[44:47], v[158:161], v[206:209], v[44:47]
	v_mfma_f32_16x16x32_bf16 v[32:35], v[166:169], v[206:209], v[32:35]
	v_mfma_f32_16x16x32_bf16 v[32:35], v[162:165], v[202:205], v[32:35]
	v_mfma_f32_16x16x32_bf16 v[16:19], v[162:165], v[210:213], v[16:19]
	v_mfma_f32_16x16x32_bf16 v[16:19], v[166:169], v[214:217], v[16:19]
	v_mfma_f32_16x16x32_bf16 v[24:27], v[158:161], v[214:217], v[24:27]
	v_mfma_f32_16x16x32_bf16 v[24:27], v[150:153], v[210:213], v[24:27]
	v_mfma_f32_16x16x32_bf16 v[8:11], v[170:173], v[210:213], v[8:11]
	v_mfma_f32_16x16x32_bf16 v[8:11], v[174:177], v[214:217], v[8:11]
	v_mfma_f32_16x16x32_bf16 v[56:59], v[174:177], v[190:193], v[56:59]
	v_mfma_f32_16x16x32_bf16 v[56:59], v[170:173], v[186:189], v[56:59]
	v_mfma_f32_16x16x32_bf16 v[48:51], v[178:181], v[186:189], v[48:51]
	v_mfma_f32_16x16x32_bf16 v[48:51], v[182:185], v[190:193], v[48:51]
	v_mfma_f32_16x16x32_bf16 v[28:31], v[182:185], v[198:201], v[28:31]
	v_mfma_f32_16x16x32_bf16 v[28:31], v[178:181], v[194:197], v[28:31]
	v_mfma_f32_16x16x32_bf16 v[40:43], v[170:173], v[194:197], v[40:43]
	v_mfma_f32_16x16x32_bf16 v[40:43], v[174:177], v[198:201], v[40:43]
	v_mfma_f32_16x16x32_bf16 v[20:23], v[174:177], v[206:209], v[20:23]
	v_mfma_f32_16x16x32_bf16 v[20:23], v[170:173], v[202:205], v[20:23]
	v_mfma_f32_16x16x32_bf16 v[12:15], v[178:181], v[202:205], v[12:15]
	v_mfma_f32_16x16x32_bf16 v[12:15], v[182:185], v[206:209], v[12:15]
	v_mfma_f32_16x16x32_bf16 v[4:7], v[182:185], v[214:217], v[4:7]
	v_mfma_f32_16x16x32_bf16 v[4:7], v[178:181], v[210:213], v[4:7]
	s_setprio 0
	s_barrier
	s_add_i32 s13, s13, 2
	s_add_u32 s20, s20, 0x10000
	s_addc_u32 s21, s21, 0
	s_add_u32 s70, s70, 0x10000
	s_addc_u32 s71, s71, 0
	s_cmp_gt_u32 s13, 29
	s_cbranch_scc0 .LBB0_916
	s_and_b64 vcc, exec, s[6:7]
	s_cbranch_vccz .LBB0_919
	s_barrier

; #define PG8_STAGE(bufoff, gbase, voff) do { _Pragma("unroll") for (int _i = 0; _i < 2; ++_i) \
;         __builtin_amdgcn_global_load_lds((const unsigned*)((const char*)(gbase) + (voff)[_i]), (PG8_LAS unsigned*)(lds + (bufoff) + ldsw + _i * 8192), 16, 0, 0); } while (0)
; #define PG8_LDA(dst, b, h) do { _Pragma("unroll") for (int m = 0; m < 4; ++m) _Pragma("unroll") for (int k = 0; k < 2; ++k) dst[m][k] = *(const PG8_LAS bf16x8*)(lds + PG8_SA(b, h) + aoff + m * 2048 + k * 1024); } while (0)
; #define PG8_LDB(dst, b, h) do { _Pragma("unroll") for (int n = 0; n < 2; ++n) _Pragma("unroll") for (int k = 0; k < 2; ++k) dst[n][k] = *(const PG8_LAS bf16x8*)(lds + PG8_SB(b, h) + boff + n * 2048 + k * 1024); } while (0)
; #define PG8_WAIT_V(n) asm volatile("s_waitcnt vmcnt(" #n ")" ::: "memory")
; #define PG8_WAIT_L(n) asm volatile("s_waitcnt lgkmcnt(" #n ")" ::: "memory")
; #define PG8_BAR __builtin_amdgcn_s_barrier()
; #define PG8_SCHED __builtin_amdgcn_sched_barrier(0)
; template <class Epi, class Sched, bool ALIGN_EPI = false, bool SP2 = false, bool ABLK = false, bool BBLK = false>
; __device__ __forceinline__ void gemm_phase(PG8_LAS unsigned char* lds, const Gemm g, const Sched& S, const Epi& E) {
;     ...
;         const char* nA = has_next ? (const char*)g.A + (size_t)nxt.pm * tstep : cA; const char* nB = has_next ? (const char*)g.Bt + (size_t)nxt.pn * tstep : cB;
;         for (int t = 0; t < nt; t += 2) {
;             const bool last = (t == nt - 2);
;             const char* a1 = cA + (size_t)(t + 1) * kstepA;
;             const char* a2 = last ? nA : cA + (size_t)(t + 2) * kstepA; const char* b2 = last ? nB : cB + (size_t)(t + 2) * kstepB;
;             const char* a3 = a2 + kstepA; const char* b3 = b2 + kstepB;
;             if (last && has_next) S.a_ready(nxt);
;             if constexpr (SP2) {
;             PG8_LDB(B0, 0, 0); PG8_LDB(B1, 0, 1); PG8_SCHED; PG8_LDA(At, 0, 0); PG8_STAGE(PG8_SA(1, 1), a1 + hstepA, voffA);
;             PG8_WAIT_V(8); PG8_WAIT_L(0); PG8_BAR; PG8_MMA(0, 0, At, B0); PG8_MMA(0, 1, At, B1); PG8_BAR; PG8_SCHED;
;             PG8_LDA(At, 0, 1); PG8_STAGE(PG8_SB(0, 0), b2, voffB); PG8_STAGE(PG8_SB(0, 1), b2 + hstepB, voffB); PG8_STAGE(PG8_SA(0, 0), a2, voffA);
;             PG8_WAIT_V(8); PG8_WAIT_L(0); PG8_BAR; PG8_MMA(1, 0, At, B0); PG8_MMA(1, 1, At, B1); PG8_BAR; PG8_SCHED;
.LBB0_2110:
	s_ashr_i32 s17, s16, 31
	s_lshl_b64 s[12:13], s[16:17], 20
	s_add_u32 s18, s72, s12
	s_addc_u32 s19, s73, s13
	s_and_b64 s[12:13], s[4:5], exec
	s_cselect_b32 s12, s19, s23
	s_cselect_b32 s17, s18, s22
	s_ashr_i32 s11, s10, 31
	s_lshl_b64 s[20:21], s[10:11], 20
	v_readlane_b32 s26, v254, 3
	v_readlane_b32 s27, v254, 4
	s_add_u32 s20, s26, s20
	s_addc_u32 s21, s27, s21
	s_and_b64 s[26:27], s[4:5], exec
	s_cselect_b32 s11, s21, s25
	s_cselect_b32 s77, s20, s24
	s_add_u32 s22, s22, 0xc000
	s_addc_u32 s23, s23, 0
	s_add_u32 s82, s24, 0x10000
	s_addc_u32 vcc_lo, s25, 0
	s_mov_b32 s13, -2
	s_add_u32 s24, s22, 0x4000
	s_addc_u32 s25, s23, 0
	s_cmp_eq_u32 s13, 28
	s_cselect_b32 s28, s17, s24
	s_cselect_b32 s29, s12, s25
	s_cselect_b32 s26, s77, s82
	s_cselect_b32 s27, s11, vcc_lo
	s_add_u32 s24, s28, 0x8000
	s_addc_u32 s25, s29, 0
	s_add_i32 s68, 0, 0x10000
	v_add_u32_e32 v151, s68, v148
	s_add_i32 s88, 0, 0x14000
	ds_read_b128 v[36:39], v151
	ds_read_b128 v[152:155], v151 offset:1024
	ds_read_b128 v[156:159], v151 offset:2048
	ds_read_b128 v[160:163], v151 offset:3072
	v_add_u32_e32 v151, s88, v148
	ds_read_b128 v[164:167], v151
	ds_read_b128 v[168:171], v151 offset:1024
	ds_read_b128 v[172:175], v151 offset:2048
	ds_read_b128 v[176:179], v151 offset:3072
	s_add_i32 m0, s9, 0xc000
	ds_read_b128 v[180:183], v150
	ds_read_b128 v[184:187], v150 offset:1024
	ds_read_b128 v[188:191], v150 offset:2048
	ds_read_b128 v[192:195], v150 offset:3072
	ds_read_b128 v[196:199], v150 offset:4096
	ds_read_b128 v[200:203], v150 offset:5120
	ds_read_b128 v[204:207], v150 offset:6144
	ds_read_b128 v[208:211], v150 offset:7168
	global_load_lds_dwordx4 v144, s[22:23]
	s_add_i32 m0, s9, 0xe000
	s_nop 0
	global_load_lds_dwordx4 v146, s[22:23]
	s_waitcnt vmcnt(8)
	s_waitcnt lgkmcnt(0)
	v_mfma_f32_16x16x32_bf16 v[132:135], v[36:39], v[180:183], 0
	v_mfma_f32_16x16x32_bf16 v[132:135], v[152:155], v[184:187], v[132:135]
	s_barrier
	s_setprio 1
	v_mfma_f32_16x16x32_bf16 v[128:131], v[160:163], v[184:187], 0
	v_mfma_f32_16x16x32_bf16 v[128:131], v[156:159], v[180:183], v[128:131]
	v_mfma_f32_16x16x32_bf16 v[120:123], v[156:159], v[188:191], 0
	v_mfma_f32_16x16x32_bf16 v[120:123], v[160:163], v[192:195], v[120:123]
	v_mfma_f32_16x16x32_bf16 v[124:127], v[152:155], v[192:195], 0
	v_mfma_f32_16x16x32_bf16 v[124:127], v[36:39], v[188:191], v[124:127]
	v_mfma_f32_16x16x32_bf16 v[108:111], v[36:39], v[196:199], 0
	v_mfma_f32_16x16x32_bf16 v[108:111], v[152:155], v[200:203], v[108:111]
	v_mfma_f32_16x16x32_bf16 v[104:107], v[160:163], v[200:203], 0
	v_mfma_f32_16x16x32_bf16 v[104:107], v[156:159], v[196:199], v[104:107]
	v_mfma_f32_16x16x32_bf16 v[88:91], v[156:159], v[204:207], 0
	v_mfma_f32_16x16x32_bf16 v[88:91], v[160:163], v[208:211], v[88:91]
	v_mfma_f32_16x16x32_bf16 v[92:95], v[152:155], v[208:211], 0
	v_mfma_f32_16x16x32_bf16 v[92:95], v[36:39], v[204:207], v[92:95]
	v_mfma_f32_16x16x32_bf16 v[76:79], v[164:167], v[204:207], 0
	v_mfma_f32_16x16x32_bf16 v[76:79], v[168:171], v[208:211], v[76:79]
	v_mfma_f32_16x16x32_bf16 v[116:119], v[168:171], v[184:187], 0
	v_mfma_f32_16x16x32_bf16 v[116:119], v[164:167], v[180:183], v[116:119]
	v_mfma_f32_16x16x32_bf16 v[112:115], v[172:175], v[180:183], 0
	v_mfma_f32_16x16x32_bf16 v[112:115], v[176:179], v[184:187], v[112:115]
	v_mfma_f32_16x16x32_bf16 v[96:99], v[176:179], v[192:195], 0
	v_mfma_f32_16x16x32_bf16 v[96:99], v[172:175], v[188:191], v[96:99]
	v_mfma_f32_16x16x32_bf16 v[100:103], v[164:167], v[188:191], 0
	v_mfma_f32_16x16x32_bf16 v[100:103], v[168:171], v[192:195], v[100:103]
	v_mfma_f32_16x16x32_bf16 v[84:87], v[168:171], v[200:203], 0
	v_mfma_f32_16x16x32_bf16 v[84:87], v[164:167], v[196:199], v[84:87]
	v_mfma_f32_16x16x32_bf16 v[80:83], v[172:175], v[196:199], 0
	v_mfma_f32_16x16x32_bf16 v[80:83], v[176:179], v[200:203], v[80:83]
	v_mfma_f32_16x16x32_bf16 v[72:75], v[176:179], v[208:211], 0
	v_mfma_f32_16x16x32_bf16 v[72:75], v[172:175], v[204:207], v[72:75]
	s_setprio 0
	s_barrier
	s_add_i32 s68, s68, s34
	s_mov_b32 m0, s68
	ds_read_b128 v[180:183], v150 offset:16384
	ds_read_b128 v[184:187], v150 offset:17408
	ds_read_b128 v[188:191], v150 offset:18432
	ds_read_b128 v[192:195], v150 offset:19456
	ds_read_b128 v[196:199], v150 offset:20480
	ds_read_b128 v[200:203], v150 offset:21504
	ds_read_b128 v[204:207], v150 offset:22528
	ds_read_b128 v[208:211], v150 offset:23552
	global_load_lds_dwordx4 v138, s[26:27]
	s_add_i32 m0, s68, 0x2000
	s_add_u32 s68, s26, 0x4000
	s_addc_u32 s69, s27, 0
	s_add_i32 s88, s88, s34
	global_load_lds_dwordx4 v142, s[26:27]
	s_mov_b32 m0, s88
	s_nop 0
	global_load_lds_dwordx4 v138, s[68:69]
	s_add_i32 m0, s88, 0x2000
	s_nop 0
	global_load_lds_dwordx4 v142, s[68:69]
	s_mov_b32 m0, s9
	s_nop 0
	global_load_lds_dwordx4 v136, s[28:29]
	s_mov_b32 m0, s35
	s_nop 0
	global_load_lds_dwordx4 v140, s[28:29]
	s_waitcnt vmcnt(8)
	s_waitcnt lgkmcnt(0)
	v_mfma_f32_16x16x32_bf16 v[68:71], v[36:39], v[180:183], 0
	v_mfma_f32_16x16x32_bf16 v[68:71], v[152:155], v[184:187], v[68:71]
	s_barrier
; #define PG8_STAGE(bufoff, gbase, voff) do { _Pragma("unroll") for (int _i = 0; _i < 2; ++_i) \
;         __builtin_amdgcn_global_load_lds((const unsigned*)((const char*)(gbase) + (voff)[_i]), (PG8_LAS unsigned*)(lds + (bufoff) + ldsw + _i * 8192), 16, 0, 0); } while (0)
; #define PG8_LDA(dst, b, h) do { _Pragma("unroll") for (int m = 0; m < 4; ++m) _Pragma("unroll") for (int k = 0; k < 2; ++k) dst[m][k] = *(const PG8_LAS bf16x8*)(lds + PG8_SA(b, h) + aoff + m * 2048 + k * 1024); } while (0)
; #define PG8_LDB(dst, b, h) do { _Pragma("unroll") for (int n = 0; n < 2; ++n) _Pragma("unroll") for (int k = 0; k < 2; ++k) dst[n][k] = *(const PG8_LAS bf16x8*)(lds + PG8_SB(b, h) + boff + n * 2048 + k * 1024); } while (0)
; #define PG8_MMA(ai, bj, At, Bt) do { __builtin_amdgcn_s_setprio(1); _Pragma("unroll") for (int m = 0; m < 4; ++m) _Pragma("unroll") for (int n = 0; n < 2; ++n) _Pragma("unroll") for (int k = 0; k < 2; ++k) \
;         acc[ai][bj][m][n] = __builtin_amdgcn_mfma_f32_16x16x32_bf16(Bt[n][k], At[m][k], acc[ai][bj][m][n], 0, 0, 0); __builtin_amdgcn_s_setprio(0); } while (0)
; #define PG8_WAIT_V(n) asm volatile("s_waitcnt vmcnt(" #n ")" ::: "memory")
; #define PG8_WAIT_L(n) asm volatile("s_waitcnt lgkmcnt(" #n ")" ::: "memory")
; #define PG8_BAR __builtin_amdgcn_s_barrier()
; #define PG8_SCHED __builtin_amdgcn_sched_barrier(0)
; template <class Epi, class Sched, bool ALIGN_EPI = false, bool SP2 = false, bool ABLK = false, bool BBLK = false>
; __device__ __forceinline__ void gemm_phase(PG8_LAS unsigned char* lds, const Gemm g, const Sched& S, const Epi& E) {
;     ...
;             PG8_WAIT_V(8); PG8_WAIT_L(0); PG8_BAR; PG8_MMA(1, 0, At, B0); PG8_MMA(1, 1, At, B1); PG8_BAR; PG8_SCHED;
;             PG8_LDB(B0, 1, 0); PG8_LDB(B1, 1, 1); PG8_SCHED; PG8_LDA(At, 1, 0); PG8_STAGE(PG8_SA(0, 1), a2 + hstepA, voffA);
;             PG8_WAIT_V(8); PG8_WAIT_L(0); PG8_BAR; PG8_MMA(0, 0, At, B0); PG8_MMA(0, 1, At, B1); PG8_BAR; PG8_SCHED;
	s_setprio 1
	v_mfma_f32_16x16x32_bf16 v[64:67], v[160:163], v[184:187], 0
	v_mfma_f32_16x16x32_bf16 v[64:67], v[156:159], v[180:183], v[64:67]
	v_mfma_f32_16x16x32_bf16 v[56:59], v[156:159], v[188:191], 0
	v_mfma_f32_16x16x32_bf16 v[56:59], v[160:163], v[192:195], v[56:59]
	v_mfma_f32_16x16x32_bf16 v[60:63], v[152:155], v[192:195], 0
	v_mfma_f32_16x16x32_bf16 v[60:63], v[36:39], v[188:191], v[60:63]
	v_mfma_f32_16x16x32_bf16 v[44:47], v[36:39], v[196:199], 0
	v_mfma_f32_16x16x32_bf16 v[44:47], v[152:155], v[200:203], v[44:47]
	v_mfma_f32_16x16x32_bf16 v[40:43], v[160:163], v[200:203], 0
	v_mfma_f32_16x16x32_bf16 v[40:43], v[156:159], v[196:199], v[40:43]
	v_mfma_f32_16x16x32_bf16 v[20:23], v[156:159], v[204:207], 0
	v_mfma_f32_16x16x32_bf16 v[20:23], v[160:163], v[208:211], v[20:23]
	v_mfma_f32_16x16x32_bf16 v[24:27], v[152:155], v[208:211], 0
	v_mfma_f32_16x16x32_bf16 v[24:27], v[36:39], v[204:207], v[24:27]
	v_mfma_f32_16x16x32_bf16 v[48:51], v[172:175], v[180:183], 0
	v_mfma_f32_16x16x32_bf16 v[32:35], v[164:167], v[188:191], 0
	v_mfma_f32_16x16x32_bf16 v[28:31], v[172:175], v[188:191], 0
	v_mfma_f32_16x16x32_bf16 v[16:19], v[164:167], v[196:199], 0
	v_mfma_f32_16x16x32_bf16 v[12:15], v[172:175], v[196:199], 0
	v_mfma_f32_16x16x32_bf16 v[8:11], v[164:167], v[204:207], 0
	v_mfma_f32_16x16x32_bf16 v[4:7], v[172:175], v[204:207], 0
	v_mfma_f32_16x16x32_bf16 v[36:39], v[164:167], v[180:183], 0
	v_mfma_f32_16x16x32_bf16 v[48:51], v[176:179], v[184:187], v[48:51]
	v_mfma_f32_16x16x32_bf16 v[32:35], v[168:171], v[192:195], v[32:35]
	v_mfma_f32_16x16x32_bf16 v[28:31], v[176:179], v[192:195], v[28:31]
	v_mfma_f32_16x16x32_bf16 v[16:19], v[168:171], v[200:203], v[16:19]
	v_mfma_f32_16x16x32_bf16 v[12:15], v[176:179], v[200:203], v[12:15]
	v_mfma_f32_16x16x32_bf16 v[8:11], v[168:171], v[208:211], v[8:11]
	v_mfma_f32_16x16x32_bf16 v[4:7], v[176:179], v[208:211], v[4:7]
	v_mfma_f32_16x16x32_bf16 v[36:39], v[168:171], v[184:187], v[36:39]
	s_setprio 0
	s_barrier
	s_add_i32 s68, 0, 0x18000
	v_add_u32_e32 v151, s68, v148
	s_add_i32 s69, 0, 0x1c000
	ds_read_b128 v[52:55], v151
	ds_read_b128 v[152:155], v151 offset:1024
	ds_read_b128 v[156:159], v151 offset:2048
	ds_read_b128 v[160:163], v151 offset:3072
	v_add_u32_e32 v151, s69, v148
	ds_read_b128 v[164:167], v151
	ds_read_b128 v[168:171], v151 offset:1024
	ds_read_b128 v[172:175], v151 offset:2048
	ds_read_b128 v[176:179], v151 offset:3072
	s_add_u32 s28, s28, 0x4000
	s_addc_u32 s29, s29, 0
	s_mov_b32 m0, s36
	ds_read_b128 v[180:183], v150 offset:32768
	ds_read_b128 v[184:187], v150 offset:33792
	ds_read_b128 v[188:191], v150 offset:34816
	ds_read_b128 v[192:195], v150 offset:35840
	ds_read_b128 v[196:199], v150 offset:36864
	ds_read_b128 v[200:203], v150 offset:37888
	ds_read_b128 v[204:207], v150 offset:38912
	ds_read_b128 v[208:211], v150 offset:39936
	global_load_lds_dwordx4 v136, s[28:29]
	s_mov_b32 m0, s37
	s_nop 0
	global_load_lds_dwordx4 v140, s[28:29]
	s_waitcnt vmcnt(8)
	s_waitcnt lgkmcnt(0)
	v_mfma_f32_16x16x32_bf16 v[132:135], v[52:55], v[180:183], v[132:135]
	v_mfma_f32_16x16x32_bf16 v[132:135], v[152:155], v[184:187], v[132:135]
	s_barrier
	s_setprio 1
	v_mfma_f32_16x16x32_bf16 v[128:131], v[160:163], v[184:187], v[128:131]
	v_mfma_f32_16x16x32_bf16 v[128:131], v[156:159], v[180:183], v[128:131]
	v_mfma_f32_16x16x32_bf16 v[120:123], v[156:159], v[188:191], v[120:123]
	v_mfma_f32_16x16x32_bf16 v[120:123], v[160:163], v[192:195], v[120:123]
	v_mfma_f32_16x16x32_bf16 v[124:127], v[152:155], v[192:195], v[124:127]
	v_mfma_f32_16x16x32_bf16 v[124:127], v[52:55], v[188:191], v[124:127]
	v_mfma_f32_16x16x32_bf16 v[108:111], v[52:55], v[196:199], v[108:111]
	v_mfma_f32_16x16x32_bf16 v[108:111], v[152:155], v[200:203], v[108:111]
	v_mfma_f32_16x16x32_bf16 v[104:107], v[160:163], v[200:203], v[104:107]
	v_mfma_f32_16x16x32_bf16 v[104:107], v[156:159], v[196:199], v[104:107]
	v_mfma_f32_16x16x32_bf16 v[88:91], v[156:159], v[204:207], v[88:91]
	v_mfma_f32_16x16x32_bf16 v[88:91], v[160:163], v[208:211], v[88:91]
	v_mfma_f32_16x16x32_bf16 v[92:95], v[152:155], v[208:211], v[92:95]
	v_mfma_f32_16x16x32_bf16 v[92:95], v[52:55], v[204:207], v[92:95]
	v_mfma_f32_16x16x32_bf16 v[76:79], v[164:167], v[204:207], v[76:79]
	v_mfma_f32_16x16x32_bf16 v[76:79], v[168:171], v[208:211], v[76:79]
	v_mfma_f32_16x16x32_bf16 v[116:119], v[168:171], v[184:187], v[116:119]
	v_mfma_f32_16x16x32_bf16 v[116:119], v[164:167], v[180:183], v[116:119]
	v_mfma_f32_16x16x32_bf16 v[112:115], v[172:175], v[180:183], v[112:115]
	v_mfma_f32_16x16x32_bf16 v[112:115], v[176:179], v[184:187], v[112:115]
	v_mfma_f32_16x16x32_bf16 v[96:99], v[176:179], v[192:195], v[96:99]
	v_mfma_f32_16x16x32_bf16 v[96:99], v[172:175], v[188:191], v[96:99]
	v_mfma_f32_16x16x32_bf16 v[100:103], v[164:167], v[188:191], v[100:103]
	v_mfma_f32_16x16x32_bf16 v[100:103], v[168:171], v[192:195], v[100:103]
	v_mfma_f32_16x16x32_bf16 v[84:87], v[168:171], v[200:203], v[84:87]
	v_mfma_f32_16x16x32_bf16 v[84:87], v[164:167], v[196:199], v[84:87]
	v_mfma_f32_16x16x32_bf16 v[80:83], v[172:175], v[196:199], v[80:83]
	v_mfma_f32_16x16x32_bf16 v[80:83], v[176:179], v[200:203], v[80:83]
	v_mfma_f32_16x16x32_bf16 v[72:75], v[176:179], v[208:211], v[72:75]
	v_mfma_f32_16x16x32_bf16 v[72:75], v[172:175], v[204:207], v[72:75]
	s_setprio 0
	s_barrier
; #define PG8_STAGE(bufoff, gbase, voff) do { _Pragma("unroll") for (int _i = 0; _i < 2; ++_i) \
;         __builtin_amdgcn_global_load_lds((const unsigned*)((const char*)(gbase) + (voff)[_i]), (PG8_LAS unsigned*)(lds + (bufoff) + ldsw + _i * 8192), 16, 0, 0); } while (0)
; #define PG8_LDA(dst, b, h) do { _Pragma("unroll") for (int m = 0; m < 4; ++m) _Pragma("unroll") for (int k = 0; k < 2; ++k) dst[m][k] = *(const PG8_LAS bf16x8*)(lds + PG8_SA(b, h) + aoff + m * 2048 + k * 1024); } while (0)
; #define PG8_WAIT_V(n) asm volatile("s_waitcnt vmcnt(" #n ")" ::: "memory")
; #define PG8_WAIT_L(n) asm volatile("s_waitcnt lgkmcnt(" #n ")" ::: "memory")
; template <class Epi, class Sched, bool ALIGN_EPI = false, bool SP2 = false, bool ABLK = false, bool BBLK = false>
; __device__ __forceinline__ void gemm_phase(PG8_LAS unsigned char* lds, const Gemm g, const Sched& S, const Epi& E) {
;     ...
;         for (int t = 0; t < nt; t += 2) {
;             const bool last = (t == nt - 2);
;             const char* a1 = cA + (size_t)(t + 1) * kstepA;
;             const char* a2 = last ? nA : cA + (size_t)(t + 2) * kstepA; const char* b2 = last ? nB : cB + (size_t)(t + 2) * kstepB;
;             const char* a3 = a2 + kstepA; const char* b3 = b2 + kstepB;
;             if (last && has_next) S.a_ready(nxt);
;             if constexpr (SP2) {
;             PG8_LDB(B0, 0, 0); PG8_LDB(B1, 0, 1); PG8_SCHED; PG8_LDA(At, 0, 0); PG8_STAGE(PG8_SA(1, 1), a1 + hstepA, voffA);
;             PG8_WAIT_V(8); PG8_WAIT_L(0); PG8_BAR; PG8_MMA(0, 0, At, B0); PG8_MMA(0, 1, At, B1); PG8_BAR; PG8_SCHED;
;             PG8_LDA(At, 0, 1); PG8_STAGE(PG8_SB(0, 0), b2, voffB); PG8_STAGE(PG8_SB(0, 1), b2 + hstepB, voffB); PG8_STAGE(PG8_SA(0, 0), a2, voffA);
;             PG8_WAIT_V(8); PG8_WAIT_L(0); PG8_BAR; PG8_MMA(1, 0, At, B0); PG8_MMA(1, 1, At, B1); PG8_BAR; PG8_SCHED;
;             PG8_LDB(B0, 1, 0); PG8_LDB(B1, 1, 1); PG8_SCHED; PG8_LDA(At, 1, 0); PG8_STAGE(PG8_SA(0, 1), a2 + hstepA, voffA);
;             PG8_WAIT_V(8); PG8_WAIT_L(0); PG8_BAR; PG8_MMA(0, 0, At, B0); PG8_MMA(0, 1, At, B1); PG8_BAR; PG8_SCHED;
;             PG8_LDA(At, 1, 1); PG8_STAGE(PG8_SB(1, 0), b3, voffB); PG8_STAGE(PG8_SB(1, 1), b3 + hstepB, voffB); PG8_STAGE(PG8_SA(1, 0), a3, voffA);
;             PG8_WAIT_V(8); PG8_WAIT_L(0); PG8_BAR; PG8_MMA(1, 0, At, B0); PG8_MMA(1, 1, At, B1); PG8_BAR; PG8_SCHED;
	s_add_u32 s28, s26, 0x8000
	s_addc_u32 s29, s27, 0
	s_add_i32 s68, s68, s34
	s_mov_b32 m0, s68
	ds_read_b128 v[180:183], v150 offset:49152
	ds_read_b128 v[184:187], v150 offset:50176
	ds_read_b128 v[188:191], v150 offset:51200
	ds_read_b128 v[192:195], v150 offset:52224
	ds_read_b128 v[196:199], v150 offset:53248
	ds_read_b128 v[200:203], v150 offset:54272
	ds_read_b128 v[204:207], v150 offset:55296
	ds_read_b128 v[208:211], v150 offset:56320
	global_load_lds_dwordx4 v138, s[28:29]
	s_add_i32 m0, s68, 0x2000
	s_add_u32 s26, s26, 0xc000
	s_addc_u32 s27, s27, 0
	global_load_lds_dwordx4 v142, s[28:29]
	s_add_i32 s28, s69, s34
	s_mov_b32 m0, s28
	s_nop 0
	global_load_lds_dwordx4 v138, s[26:27]
	s_add_i32 m0, s28, 0x2000
	s_nop 0
	global_load_lds_dwordx4 v142, s[26:27]
	s_mov_b32 m0, s64
	s_nop 0
	global_load_lds_dwordx4 v136, s[24:25]
	s_mov_b32 m0, s65
	s_nop 0
	global_load_lds_dwordx4 v140, s[24:25]
	s_waitcnt vmcnt(8)
	s_waitcnt lgkmcnt(0)
	v_mfma_f32_16x16x32_bf16 v[68:71], v[52:55], v[180:183], v[68:71]
	v_mfma_f32_16x16x32_bf16 v[68:71], v[152:155], v[184:187], v[68:71]
	s_barrier
	s_setprio 1
	v_mfma_f32_16x16x32_bf16 v[64:67], v[160:163], v[184:187], v[64:67]
	v_mfma_f32_16x16x32_bf16 v[64:67], v[156:159], v[180:183], v[64:67]
	v_mfma_f32_16x16x32_bf16 v[56:59], v[156:159], v[188:191], v[56:59]
	v_mfma_f32_16x16x32_bf16 v[56:59], v[160:163], v[192:195], v[56:59]
	v_mfma_f32_16x16x32_bf16 v[60:63], v[152:155], v[192:195], v[60:63]
	v_mfma_f32_16x16x32_bf16 v[60:63], v[52:55], v[188:191], v[60:63]
	v_mfma_f32_16x16x32_bf16 v[44:47], v[52:55], v[196:199], v[44:47]
	v_mfma_f32_16x16x32_bf16 v[44:47], v[152:155], v[200:203], v[44:47]
	v_mfma_f32_16x16x32_bf16 v[40:43], v[160:163], v[200:203], v[40:43]
	v_mfma_f32_16x16x32_bf16 v[40:43], v[156:159], v[196:199], v[40:43]
	v_mfma_f32_16x16x32_bf16 v[20:23], v[156:159], v[204:207], v[20:23]
	v_mfma_f32_16x16x32_bf16 v[20:23], v[160:163], v[208:211], v[20:23]
	v_mfma_f32_16x16x32_bf16 v[24:27], v[152:155], v[208:211], v[24:27]
	v_mfma_f32_16x16x32_bf16 v[24:27], v[52:55], v[204:207], v[24:27]
	v_mfma_f32_16x16x32_bf16 v[36:39], v[164:167], v[180:183], v[36:39]
	v_mfma_f32_16x16x32_bf16 v[52:55], v[168:171], v[184:187], v[36:39]
	v_mfma_f32_16x16x32_bf16 v[36:39], v[172:175], v[180:183], v[48:51]
	v_mfma_f32_16x16x32_bf16 v[32:35], v[164:167], v[188:191], v[32:35]
	v_mfma_f32_16x16x32_bf16 v[28:31], v[172:175], v[188:191], v[28:31]
	v_mfma_f32_16x16x32_bf16 v[16:19], v[164:167], v[196:199], v[16:19]
	v_mfma_f32_16x16x32_bf16 v[12:15], v[172:175], v[196:199], v[12:15]
	v_mfma_f32_16x16x32_bf16 v[8:11], v[164:167], v[204:207], v[8:11]
	v_mfma_f32_16x16x32_bf16 v[4:7], v[172:175], v[204:207], v[4:7]
	v_mfma_f32_16x16x32_bf16 v[48:51], v[176:179], v[184:187], v[36:39]
	v_mfma_f32_16x16x32_bf16 v[32:35], v[168:171], v[192:195], v[32:35]
	v_mfma_f32_16x16x32_bf16 v[28:31], v[176:179], v[192:195], v[28:31]
	v_mfma_f32_16x16x32_bf16 v[16:19], v[168:171], v[200:203], v[16:19]
	v_mfma_f32_16x16x32_bf16 v[12:15], v[176:179], v[200:203], v[12:15]
	v_mfma_f32_16x16x32_bf16 v[8:11], v[168:171], v[208:211], v[8:11]
	v_mfma_f32_16x16x32_bf16 v[4:7], v[176:179], v[208:211], v[4:7]
	s_setprio 0
	s_barrier
	s_add_i32 s13, s13, 2
	s_add_u32 s22, s22, 0x10000
	s_addc_u32 s23, s23, 0
	s_add_u32 s82, s82, 0x10000
	s_addc_u32 vcc_lo, vcc_lo, 0
	s_cmp_gt_u32 s13, 29
.LBB0_2111:
	s_add_u32 s24, s22, 0x4000
	s_addc_u32 s25, s23, 0
	s_cmp_eq_u32 s13, 28
	s_cselect_b32 s28, s17, s24
	s_cselect_b32 s29, s12, s25
	s_cselect_b32 s26, s77, s82
	s_cselect_b32 s27, s11, vcc_lo
	s_add_u32 s24, s28, 0x8000
	s_addc_u32 s25, s29, 0
	s_add_i32 s68, 0, 0x10000
	v_add_u32_e32 v151, s68, v148
	s_add_i32 s88, 0, 0x14000
	ds_read_b128 v[36:39], v151
	ds_read_b128 v[152:155], v151 offset:1024
	ds_read_b128 v[156:159], v151 offset:2048
	ds_read_b128 v[160:163], v151 offset:3072
	v_add_u32_e32 v151, s88, v148
	ds_read_b128 v[164:167], v151
	ds_read_b128 v[168:171], v151 offset:1024
	ds_read_b128 v[172:175], v151 offset:2048
	ds_read_b128 v[176:179], v151 offset:3072
	s_add_i32 m0, s9, 0xc000
	ds_read_b128 v[180:183], v150
	ds_read_b128 v[184:187], v150 offset:1024
	ds_read_b128 v[188:191], v150 offset:2048
	ds_read_b128 v[192:195], v150 offset:3072
	ds_read_b128 v[196:199], v150 offset:4096
	ds_read_b128 v[200:203], v150 offset:5120
	ds_read_b128 v[204:207], v150 offset:6144
	ds_read_b128 v[208:211], v150 offset:7168
	global_load_lds_dwordx4 v144, s[22:23]
	s_add_i32 m0, s9, 0xe000
	s_nop 0
	global_load_lds_dwordx4 v146, s[22:23]
	s_waitcnt vmcnt(8)
	s_waitcnt lgkmcnt(0)
	v_mfma_f32_16x16x32_bf16 v[132:135], v[36:39], v[180:183], v[132:135]
	v_mfma_f32_16x16x32_bf16 v[132:135], v[152:155], v[184:187], v[132:135]
	s_barrier
; #define PG8_STAGE(bufoff, gbase, voff) do { _Pragma("unroll") for (int _i = 0; _i < 2; ++_i) \
;         __builtin_amdgcn_global_load_lds((const unsigned*)((const char*)(gbase) + (voff)[_i]), (PG8_LAS unsigned*)(lds + (bufoff) + ldsw + _i * 8192), 16, 0, 0); } while (0)
; #define PG8_LDA(dst, b, h) do { _Pragma("unroll") for (int m = 0; m < 4; ++m) _Pragma("unroll") for (int k = 0; k < 2; ++k) dst[m][k] = *(const PG8_LAS bf16x8*)(lds + PG8_SA(b, h) + aoff + m * 2048 + k * 1024); } while (0)
; #define PG8_LDB(dst, b, h) do { _Pragma("unroll") for (int n = 0; n < 2; ++n) _Pragma("unroll") for (int k = 0; k < 2; ++k) dst[n][k] = *(const PG8_LAS bf16x8*)(lds + PG8_SB(b, h) + boff + n * 2048 + k * 1024); } while (0)
; #define PG8_MMA(ai, bj, At, Bt) do { __builtin_amdgcn_s_setprio(1); _Pragma("unroll") for (int m = 0; m < 4; ++m) _Pragma("unroll") for (int n = 0; n < 2; ++n) _Pragma("unroll") for (int k = 0; k < 2; ++k) \
;         acc[ai][bj][m][n] = __builtin_amdgcn_mfma_f32_16x16x32_bf16(Bt[n][k], At[m][k], acc[ai][bj][m][n], 0, 0, 0); __builtin_amdgcn_s_setprio(0); } while (0)
; #define PG8_WAIT_V(n) asm volatile("s_waitcnt vmcnt(" #n ")" ::: "memory")
; #define PG8_WAIT_L(n) asm volatile("s_waitcnt lgkmcnt(" #n ")" ::: "memory")
; #define PG8_BAR __builtin_amdgcn_s_barrier()
; #define PG8_SCHED __builtin_amdgcn_sched_barrier(0)
; template <class Epi, class Sched, bool ALIGN_EPI = false, bool SP2 = false, bool ABLK = false, bool BBLK = false>
; __device__ __forceinline__ void gemm_phase(PG8_LAS unsigned char* lds, const Gemm g, const Sched& S, const Epi& E) {
;     ...
;             PG8_LDB(B0, 0, 0); PG8_LDB(B1, 0, 1); PG8_SCHED; PG8_LDA(At, 0, 0); PG8_STAGE(PG8_SA(1, 1), a1 + hstepA, voffA);
;             PG8_WAIT_V(8); PG8_WAIT_L(0); PG8_BAR; PG8_MMA(0, 0, At, B0); PG8_MMA(0, 1, At, B1); PG8_BAR; PG8_SCHED;
;             PG8_LDA(At, 0, 1); PG8_STAGE(PG8_SB(0, 0), b2, voffB); PG8_STAGE(PG8_SB(0, 1), b2 + hstepB, voffB); PG8_STAGE(PG8_SA(0, 0), a2, voffA);
;             PG8_WAIT_V(8); PG8_WAIT_L(0); PG8_BAR; PG8_MMA(1, 0, At, B0); PG8_MMA(1, 1, At, B1); PG8_BAR; PG8_SCHED;
	s_setprio 1
	v_mfma_f32_16x16x32_bf16 v[128:131], v[160:163], v[184:187], v[128:131]
	v_mfma_f32_16x16x32_bf16 v[128:131], v[156:159], v[180:183], v[128:131]
	v_mfma_f32_16x16x32_bf16 v[120:123], v[156:159], v[188:191], v[120:123]
	v_mfma_f32_16x16x32_bf16 v[120:123], v[160:163], v[192:195], v[120:123]
	v_mfma_f32_16x16x32_bf16 v[124:127], v[152:155], v[192:195], v[124:127]
	v_mfma_f32_16x16x32_bf16 v[124:127], v[36:39], v[188:191], v[124:127]
	v_mfma_f32_16x16x32_bf16 v[108:111], v[36:39], v[196:199], v[108:111]
	v_mfma_f32_16x16x32_bf16 v[108:111], v[152:155], v[200:203], v[108:111]
	v_mfma_f32_16x16x32_bf16 v[104:107], v[160:163], v[200:203], v[104:107]
	v_mfma_f32_16x16x32_bf16 v[104:107], v[156:159], v[196:199], v[104:107]
	v_mfma_f32_16x16x32_bf16 v[88:91], v[156:159], v[204:207], v[88:91]
	v_mfma_f32_16x16x32_bf16 v[88:91], v[160:163], v[208:211], v[88:91]
	v_mfma_f32_16x16x32_bf16 v[92:95], v[152:155], v[208:211], v[92:95]
	v_mfma_f32_16x16x32_bf16 v[92:95], v[36:39], v[204:207], v[92:95]
	v_mfma_f32_16x16x32_bf16 v[76:79], v[164:167], v[204:207], v[76:79]
	v_mfma_f32_16x16x32_bf16 v[76:79], v[168:171], v[208:211], v[76:79]
	v_mfma_f32_16x16x32_bf16 v[116:119], v[168:171], v[184:187], v[116:119]
	v_mfma_f32_16x16x32_bf16 v[116:119], v[164:167], v[180:183], v[116:119]
	v_mfma_f32_16x16x32_bf16 v[112:115], v[172:175], v[180:183], v[112:115]
	v_mfma_f32_16x16x32_bf16 v[112:115], v[176:179], v[184:187], v[112:115]
	v_mfma_f32_16x16x32_bf16 v[96:99], v[176:179], v[192:195], v[96:99]
	v_mfma_f32_16x16x32_bf16 v[96:99], v[172:175], v[188:191], v[96:99]
	v_mfma_f32_16x16x32_bf16 v[100:103], v[164:167], v[188:191], v[100:103]
	v_mfma_f32_16x16x32_bf16 v[100:103], v[168:171], v[192:195], v[100:103]
	v_mfma_f32_16x16x32_bf16 v[84:87], v[168:171], v[200:203], v[84:87]
	v_mfma_f32_16x16x32_bf16 v[84:87], v[164:167], v[196:199], v[84:87]
	v_mfma_f32_16x16x32_bf16 v[80:83], v[172:175], v[196:199], v[80:83]
	v_mfma_f32_16x16x32_bf16 v[80:83], v[176:179], v[200:203], v[80:83]
	v_mfma_f32_16x16x32_bf16 v[72:75], v[176:179], v[208:211], v[72:75]
	v_mfma_f32_16x16x32_bf16 v[72:75], v[172:175], v[204:207], v[72:75]
	s_setprio 0
	s_barrier
	s_add_i32 s68, s68, s34
	s_mov_b32 m0, s68
	ds_read_b128 v[180:183], v150 offset:16384
	ds_read_b128 v[184:187], v150 offset:17408
	ds_read_b128 v[188:191], v150 offset:18432
	ds_read_b128 v[192:195], v150 offset:19456
	ds_read_b128 v[196:199], v150 offset:20480
	ds_read_b128 v[200:203], v150 offset:21504
	ds_read_b128 v[204:207], v150 offset:22528
	ds_read_b128 v[208:211], v150 offset:23552
	global_load_lds_dwordx4 v138, s[26:27]
	s_add_i32 m0, s68, 0x2000
	s_add_u32 s68, s26, 0x4000
	s_addc_u32 s69, s27, 0
	s_add_i32 s88, s88, s34
	global_load_lds_dwordx4 v142, s[26:27]
	s_mov_b32 m0, s88
	s_nop 0
	global_load_lds_dwordx4 v138, s[68:69]
	s_add_i32 m0, s88, 0x2000
	s_nop 0
	global_load_lds_dwordx4 v142, s[68:69]
	s_mov_b32 m0, s9
	s_nop 0
	global_load_lds_dwordx4 v136, s[28:29]
	s_mov_b32 m0, s35
	s_nop 0
	global_load_lds_dwordx4 v140, s[28:29]
	s_waitcnt vmcnt(8)
	s_waitcnt lgkmcnt(0)
	v_mfma_f32_16x16x32_bf16 v[68:71], v[36:39], v[180:183], v[68:71]
	v_mfma_f32_16x16x32_bf16 v[68:71], v[152:155], v[184:187], v[68:71]
	s_barrier
	s_setprio 1
	v_mfma_f32_16x16x32_bf16 v[64:67], v[160:163], v[184:187], v[64:67]
	v_mfma_f32_16x16x32_bf16 v[64:67], v[156:159], v[180:183], v[64:67]
	v_mfma_f32_16x16x32_bf16 v[56:59], v[156:159], v[188:191], v[56:59]
	v_mfma_f32_16x16x32_bf16 v[56:59], v[160:163], v[192:195], v[56:59]
	v_mfma_f32_16x16x32_bf16 v[60:63], v[152:155], v[192:195], v[60:63]
	v_mfma_f32_16x16x32_bf16 v[60:63], v[36:39], v[188:191], v[60:63]
	v_mfma_f32_16x16x32_bf16 v[44:47], v[36:39], v[196:199], v[44:47]
	v_mfma_f32_16x16x32_bf16 v[44:47], v[152:155], v[200:203], v[44:47]
	v_mfma_f32_16x16x32_bf16 v[40:43], v[160:163], v[200:203], v[40:43]
	v_mfma_f32_16x16x32_bf16 v[40:43], v[156:159], v[196:199], v[40:43]
	v_mfma_f32_16x16x32_bf16 v[20:23], v[156:159], v[204:207], v[20:23]
	v_mfma_f32_16x16x32_bf16 v[20:23], v[160:163], v[208:211], v[20:23]
	v_mfma_f32_16x16x32_bf16 v[24:27], v[152:155], v[208:211], v[24:27]
	v_mfma_f32_16x16x32_bf16 v[24:27], v[36:39], v[204:207], v[24:27]
	v_mfma_f32_16x16x32_bf16 v[48:51], v[172:175], v[180:183], v[48:51]
	v_mfma_f32_16x16x32_bf16 v[32:35], v[164:167], v[188:191], v[32:35]
	v_mfma_f32_16x16x32_bf16 v[28:31], v[172:175], v[188:191], v[28:31]
	v_mfma_f32_16x16x32_bf16 v[16:19], v[164:167], v[196:199], v[16:19]
	v_mfma_f32_16x16x32_bf16 v[12:15], v[172:175], v[196:199], v[12:15]
	v_mfma_f32_16x16x32_bf16 v[8:11], v[164:167], v[204:207], v[8:11]
	v_mfma_f32_16x16x32_bf16 v[4:7], v[172:175], v[204:207], v[4:7]
	v_mfma_f32_16x16x32_bf16 v[36:39], v[164:167], v[180:183], v[52:55]
	v_mfma_f32_16x16x32_bf16 v[48:51], v[176:179], v[184:187], v[48:51]
	v_mfma_f32_16x16x32_bf16 v[32:35], v[168:171], v[192:195], v[32:35]
	v_mfma_f32_16x16x32_bf16 v[28:31], v[176:179], v[192:195], v[28:31]
	v_mfma_f32_16x16x32_bf16 v[16:19], v[168:171], v[200:203], v[16:19]
	v_mfma_f32_16x16x32_bf16 v[12:15], v[176:179], v[200:203], v[12:15]
	v_mfma_f32_16x16x32_bf16 v[8:11], v[168:171], v[208:211], v[8:11]
	v_mfma_f32_16x16x32_bf16 v[4:7], v[176:179], v[208:211], v[4:7]
	v_mfma_f32_16x16x32_bf16 v[36:39], v[168:171], v[184:187], v[36:39]
	s_setprio 0
	s_barrier
; #define PG8_STAGE(bufoff, gbase, voff) do { _Pragma("unroll") for (int _i = 0; _i < 2; ++_i) \
;         __builtin_amdgcn_global_load_lds((const unsigned*)((const char*)(gbase) + (voff)[_i]), (PG8_LAS unsigned*)(lds + (bufoff) + ldsw + _i * 8192), 16, 0, 0); } while (0)
; #define PG8_LDA(dst, b, h) do { _Pragma("unroll") for (int m = 0; m < 4; ++m) _Pragma("unroll") for (int k = 0; k < 2; ++k) dst[m][k] = *(const PG8_LAS bf16x8*)(lds + PG8_SA(b, h) + aoff + m * 2048 + k * 1024); } while (0)
; #define PG8_LDB(dst, b, h) do { _Pragma("unroll") for (int n = 0; n < 2; ++n) _Pragma("unroll") for (int k = 0; k < 2; ++k) dst[n][k] = *(const PG8_LAS bf16x8*)(lds + PG8_SB(b, h) + boff + n * 2048 + k * 1024); } while (0)
; #define PG8_MMA(ai, bj, At, Bt) do { __builtin_amdgcn_s_setprio(1); _Pragma("unroll") for (int m = 0; m < 4; ++m) _Pragma("unroll") for (int n = 0; n < 2; ++n) _Pragma("unroll") for (int k = 0; k < 2; ++k) \
;         acc[ai][bj][m][n] = __builtin_amdgcn_mfma_f32_16x16x32_bf16(Bt[n][k], At[m][k], acc[ai][bj][m][n], 0, 0, 0); __builtin_amdgcn_s_setprio(0); } while (0)
; #define PG8_WAIT_V(n) asm volatile("s_waitcnt vmcnt(" #n ")" ::: "memory")
; #define PG8_WAIT_L(n) asm volatile("s_waitcnt lgkmcnt(" #n ")" ::: "memory")
; #define PG8_BAR __builtin_amdgcn_s_barrier()
; #define PG8_SCHED __builtin_amdgcn_sched_barrier(0)
; template <class Epi, class Sched, bool ALIGN_EPI = false, bool SP2 = false, bool ABLK = false, bool BBLK = false>
; __device__ __forceinline__ void gemm_phase(PG8_LAS unsigned char* lds, const Gemm g, const Sched& S, const Epi& E) {
;     ...
;             PG8_LDB(B0, 1, 0); PG8_LDB(B1, 1, 1); PG8_SCHED; PG8_LDA(At, 1, 0); PG8_STAGE(PG8_SA(0, 1), a2 + hstepA, voffA);
;             PG8_WAIT_V(8); PG8_WAIT_L(0); PG8_BAR; PG8_MMA(0, 0, At, B0); PG8_MMA(0, 1, At, B1); PG8_BAR; PG8_SCHED;
;             PG8_LDA(At, 1, 1); PG8_STAGE(PG8_SB(1, 0), b3, voffB); PG8_STAGE(PG8_SB(1, 1), b3 + hstepB, voffB); PG8_STAGE(PG8_SA(1, 0), a3, voffA);
;             PG8_WAIT_V(8); PG8_WAIT_L(0); PG8_BAR; PG8_MMA(1, 0, At, B0); PG8_MMA(1, 1, At, B1); PG8_BAR; PG8_SCHED;
;     ...
;         if constexpr (ALIGN_EPI) { if (wr == 0) PG8_BAR; }
	s_add_i32 s68, 0, 0x18000
	v_add_u32_e32 v151, s68, v148
	s_add_i32 s69, 0, 0x1c000
	ds_read_b128 v[52:55], v151
	ds_read_b128 v[152:155], v151 offset:1024
	ds_read_b128 v[156:159], v151 offset:2048
	ds_read_b128 v[160:163], v151 offset:3072
	v_add_u32_e32 v151, s69, v148
	ds_read_b128 v[164:167], v151
	ds_read_b128 v[168:171], v151 offset:1024
	ds_read_b128 v[172:175], v151 offset:2048
	ds_read_b128 v[176:179], v151 offset:3072
	s_add_u32 s28, s28, 0x4000
	s_addc_u32 s29, s29, 0
	s_mov_b32 m0, s36
	ds_read_b128 v[180:183], v150 offset:32768
	ds_read_b128 v[184:187], v150 offset:33792
	ds_read_b128 v[188:191], v150 offset:34816
	ds_read_b128 v[192:195], v150 offset:35840
	ds_read_b128 v[196:199], v150 offset:36864
	ds_read_b128 v[200:203], v150 offset:37888
	ds_read_b128 v[204:207], v150 offset:38912
	ds_read_b128 v[208:211], v150 offset:39936
	global_load_lds_dwordx4 v136, s[28:29]
	s_mov_b32 m0, s37
	s_nop 0
	global_load_lds_dwordx4 v140, s[28:29]
	s_waitcnt vmcnt(8)
	s_waitcnt lgkmcnt(0)
	v_mfma_f32_16x16x32_bf16 v[132:135], v[52:55], v[180:183], v[132:135]
	v_mfma_f32_16x16x32_bf16 v[132:135], v[152:155], v[184:187], v[132:135]
	s_barrier
	s_setprio 1
	v_mfma_f32_16x16x32_bf16 v[128:131], v[160:163], v[184:187], v[128:131]
	v_mfma_f32_16x16x32_bf16 v[128:131], v[156:159], v[180:183], v[128:131]
	v_mfma_f32_16x16x32_bf16 v[120:123], v[156:159], v[188:191], v[120:123]
	v_mfma_f32_16x16x32_bf16 v[120:123], v[160:163], v[192:195], v[120:123]
	v_mfma_f32_16x16x32_bf16 v[124:127], v[152:155], v[192:195], v[124:127]
	v_mfma_f32_16x16x32_bf16 v[124:127], v[52:55], v[188:191], v[124:127]
	v_mfma_f32_16x16x32_bf16 v[108:111], v[52:55], v[196:199], v[108:111]
	v_mfma_f32_16x16x32_bf16 v[108:111], v[152:155], v[200:203], v[108:111]
	v_mfma_f32_16x16x32_bf16 v[104:107], v[160:163], v[200:203], v[104:107]
	v_mfma_f32_16x16x32_bf16 v[104:107], v[156:159], v[196:199], v[104:107]
	v_mfma_f32_16x16x32_bf16 v[88:91], v[156:159], v[204:207], v[88:91]
	v_mfma_f32_16x16x32_bf16 v[88:91], v[160:163], v[208:211], v[88:91]
	v_mfma_f32_16x16x32_bf16 v[92:95], v[152:155], v[208:211], v[92:95]
	v_mfma_f32_16x16x32_bf16 v[92:95], v[52:55], v[204:207], v[92:95]
	v_mfma_f32_16x16x32_bf16 v[76:79], v[164:167], v[204:207], v[76:79]
	v_mfma_f32_16x16x32_bf16 v[76:79], v[168:171], v[208:211], v[76:79]
	v_mfma_f32_16x16x32_bf16 v[116:119], v[168:171], v[184:187], v[116:119]
	v_mfma_f32_16x16x32_bf16 v[116:119], v[164:167], v[180:183], v[116:119]
	v_mfma_f32_16x16x32_bf16 v[112:115], v[172:175], v[180:183], v[112:115]
	v_mfma_f32_16x16x32_bf16 v[112:115], v[176:179], v[184:187], v[112:115]
	v_mfma_f32_16x16x32_bf16 v[96:99], v[176:179], v[192:195], v[96:99]
	v_mfma_f32_16x16x32_bf16 v[96:99], v[172:175], v[188:191], v[96:99]
	v_mfma_f32_16x16x32_bf16 v[100:103], v[164:167], v[188:191], v[100:103]
	v_mfma_f32_16x16x32_bf16 v[100:103], v[168:171], v[192:195], v[100:103]
	v_mfma_f32_16x16x32_bf16 v[84:87], v[168:171], v[200:203], v[84:87]
	v_mfma_f32_16x16x32_bf16 v[84:87], v[164:167], v[196:199], v[84:87]
	v_mfma_f32_16x16x32_bf16 v[80:83], v[172:175], v[196:199], v[80:83]
	v_mfma_f32_16x16x32_bf16 v[80:83], v[176:179], v[200:203], v[80:83]
	v_mfma_f32_16x16x32_bf16 v[72:75], v[176:179], v[208:211], v[72:75]
	v_mfma_f32_16x16x32_bf16 v[72:75], v[172:175], v[204:207], v[72:75]
	s_setprio 0
	s_barrier
	s_add_u32 s28, s26, 0x8000
	s_addc_u32 s29, s27, 0
	s_add_i32 s68, s68, s34
	s_mov_b32 m0, s68
	ds_read_b128 v[180:183], v150 offset:49152
	ds_read_b128 v[184:187], v150 offset:50176
	ds_read_b128 v[188:191], v150 offset:51200
	ds_read_b128 v[192:195], v150 offset:52224
	ds_read_b128 v[196:199], v150 offset:53248
	ds_read_b128 v[200:203], v150 offset:54272
	ds_read_b128 v[204:207], v150 offset:55296
	ds_read_b128 v[208:211], v150 offset:56320
	global_load_lds_dwordx4 v138, s[28:29]
	s_add_i32 m0, s68, 0x2000
	s_add_u32 s26, s26, 0xc000
	s_addc_u32 s27, s27, 0
	global_load_lds_dwordx4 v142, s[28:29]
	s_add_i32 s28, s69, s34
	s_mov_b32 m0, s28
	s_nop 0
	global_load_lds_dwordx4 v138, s[26:27]
	s_add_i32 m0, s28, 0x2000
	s_nop 0
	global_load_lds_dwordx4 v142, s[26:27]
	s_mov_b32 m0, s64
	s_nop 0
	global_load_lds_dwordx4 v136, s[24:25]
	s_mov_b32 m0, s65
	s_nop 0
	global_load_lds_dwordx4 v140, s[24:25]
	s_waitcnt vmcnt(8)
	s_waitcnt lgkmcnt(0)
	v_mfma_f32_16x16x32_bf16 v[68:71], v[52:55], v[180:183], v[68:71]
	v_mfma_f32_16x16x32_bf16 v[68:71], v[152:155], v[184:187], v[68:71]
	s_barrier
	s_setprio 1
	v_mfma_f32_16x16x32_bf16 v[64:67], v[160:163], v[184:187], v[64:67]
	v_mfma_f32_16x16x32_bf16 v[64:67], v[156:159], v[180:183], v[64:67]
	v_mfma_f32_16x16x32_bf16 v[56:59], v[156:159], v[188:191], v[56:59]
	v_mfma_f32_16x16x32_bf16 v[56:59], v[160:163], v[192:195], v[56:59]
	v_mfma_f32_16x16x32_bf16 v[60:63], v[152:155], v[192:195], v[60:63]
	v_mfma_f32_16x16x32_bf16 v[60:63], v[52:55], v[188:191], v[60:63]
	v_mfma_f32_16x16x32_bf16 v[44:47], v[52:55], v[196:199], v[44:47]
	v_mfma_f32_16x16x32_bf16 v[44:47], v[152:155], v[200:203], v[44:47]
	v_mfma_f32_16x16x32_bf16 v[40:43], v[160:163], v[200:203], v[40:43]
	v_mfma_f32_16x16x32_bf16 v[40:43], v[156:159], v[196:199], v[40:43]
	v_mfma_f32_16x16x32_bf16 v[20:23], v[156:159], v[204:207], v[20:23]
	v_mfma_f32_16x16x32_bf16 v[20:23], v[160:163], v[208:211], v[20:23]
	v_mfma_f32_16x16x32_bf16 v[24:27], v[152:155], v[208:211], v[24:27]
	v_mfma_f32_16x16x32_bf16 v[24:27], v[52:55], v[204:207], v[24:27]
	v_mfma_f32_16x16x32_bf16 v[36:39], v[164:167], v[180:183], v[36:39]
	v_mfma_f32_16x16x32_bf16 v[52:55], v[168:171], v[184:187], v[36:39]
	v_mfma_f32_16x16x32_bf16 v[36:39], v[172:175], v[180:183], v[48:51]
	v_mfma_f32_16x16x32_bf16 v[32:35], v[164:167], v[188:191], v[32:35]
	v_mfma_f32_16x16x32_bf16 v[28:31], v[172:175], v[188:191], v[28:31]
	v_mfma_f32_16x16x32_bf16 v[16:19], v[164:167], v[196:199], v[16:19]
	v_mfma_f32_16x16x32_bf16 v[12:15], v[172:175], v[196:199], v[12:15]
	v_mfma_f32_16x16x32_bf16 v[8:11], v[164:167], v[204:207], v[8:11]
	v_mfma_f32_16x16x32_bf16 v[4:7], v[172:175], v[204:207], v[4:7]
	v_mfma_f32_16x16x32_bf16 v[48:51], v[176:179], v[184:187], v[36:39]
	v_mfma_f32_16x16x32_bf16 v[32:35], v[168:171], v[192:195], v[32:35]
	v_mfma_f32_16x16x32_bf16 v[28:31], v[176:179], v[192:195], v[28:31]
	v_mfma_f32_16x16x32_bf16 v[16:19], v[168:171], v[200:203], v[16:19]
	v_mfma_f32_16x16x32_bf16 v[12:15], v[176:179], v[200:203], v[12:15]
	v_mfma_f32_16x16x32_bf16 v[8:11], v[168:171], v[208:211], v[8:11]
	v_mfma_f32_16x16x32_bf16 v[4:7], v[176:179], v[208:211], v[4:7]
	s_setprio 0
	s_barrier
	s_add_i32 s13, s13, 2
	s_add_u32 s22, s22, 0x10000
	s_addc_u32 s23, s23, 0
	s_add_u32 s82, s82, 0x10000
	s_addc_u32 vcc_lo, vcc_lo, 0
	s_cmp_gt_u32 s13, 29
	s_cbranch_scc0 .LBB0_2111
	s_and_b64 vcc, exec, s[6:7]
	s_movk_i32 s77, 0x1000
	s_cbranch_vccz .LBB0_2114
	s_barrier
